# all six GEMM streams producer/consumer (incl. split-K), hand-written merge phase as one LDS-DMA stream with fused gating, role assignment with SIMD-distinctness fallback
# speedup vs baseline: 1.0498x; 1.0041x over previous
.Lab_skip:
	s_or_b64 exec, exec, s[2:3]
	s_waitcnt lgkmcnt(0)
	s_barrier
	v_mov_b32_e32 v1, 0x10018
	ds_read_b32 v1, v1
	v_lshrrev_b32_e32 v2, 6, v194
	s_waitcnt lgkmcnt(0)
	s_nop 0
	v_readfirstlane_b32 s101, v1
	v_readfirstlane_b32 s100, v2
	s_getreg_b32 s98, hwreg(HW_REG_HW_ID, 4, 2)
	v_mov_b32_e32 v1, s98
	v_lshlrev_b32_e32 v2, 2, v2
	v_add_u32_e32 v2, 0x10000, v2
	ds_write_b32 v2, v1
	s_waitcnt lgkmcnt(0)
	s_barrier
	v_mov_b32_e32 v2, 0x10000
	ds_read_b32 v1, v2
	ds_read_b32 v3, v2 offset:4
	ds_read_b32 v4, v2 offset:8
	ds_read_b32 v5, v2 offset:12
	s_waitcnt lgkmcnt(0)
	v_lshlrev_b32_e64 v1, v1, 1
	v_lshlrev_b32_e64 v3, v3, 1
	v_lshlrev_b32_e64 v4, v4, 1
	v_lshlrev_b32_e64 v5, v5, 1
	v_or3_b32 v1, v1, v3, v4
	v_or_b32_e32 v1, v1, v5
	s_nop 0
	v_readfirstlane_b32 s99, v1
	s_cmp_eq_u32 s99, 15
	s_cbranch_scc1 .Lrole_simd
	s_cmp_lt_u32 s100, 2
	s_cselect_b32 s99, 1, 0
	s_and_b32 s98, s100, 1
	s_branch .Lrole_done
.Lrole_simd:
	s_lshr_b32 s99, s98, 1
	s_cmp_eq_u32 s99, s101
	s_cselect_b32 s99, 1, 0
	s_and_b32 s98, s98, 1
.Lrole_done:
	s_lshl_b32 s98, s98, 1
	s_or_b32 s99, s99, s98
	s_lshl_b32 s100, s100, 2
	s_or_b32 s101, s99, s100
	v_readlane_b32 s98, v252, 0
	s_lshr_b32 s98, s98, 3
	s_and_b32 s98, s98, 0xff
	s_lshl_b32 s98, s98, 8
	s_or_b32 s101, s101, s98
	s_load_dwordx2 s[52:53], s[0:1], 0x210
	s_waitcnt lgkmcnt(0)
	s_cmp_ge_i32 s52, s53
	s_cbranch_scc1 .Lend_near
	s_load_dwordx2 s[22:23], s[0:1], 0x1a8
	s_load_dwordx16 s[56:71], s[0:1], 0x0
	s_load_dwordx16 s[36:51], s[0:1], 0x40
	s_load_dwordx16 s[4:19], s[0:1], 0x80
	v_lshrrev_b32_e32 v1, 20, v0
	v_lshrrev_b32_e32 v0, 10, v0
	v_or_b32_e32 v0, v0, v1
	s_mov_b32 s97, 0
	s_waitcnt lgkmcnt(0)
	v_writelane_b32 v252, s4, 5
	s_movk_i32 s55, 0x4000
	v_mov_b32_e32 v2, 0
	v_writelane_b32 v252, s5, 6
	v_writelane_b32 v252, s6, 7
	v_writelane_b32 v252, s7, 8
	v_writelane_b32 v252, s8, 9
	v_writelane_b32 v252, s9, 10
	v_writelane_b32 v252, s10, 11
	v_writelane_b32 v252, s11, 12
	v_writelane_b32 v252, s12, 13
	v_writelane_b32 v252, s13, 14
	v_writelane_b32 v252, s14, 15
	v_writelane_b32 v252, s15, 16
	v_writelane_b32 v252, s16, 17
	v_writelane_b32 v252, s17, 18
	v_writelane_b32 v252, s18, 19
	v_writelane_b32 v252, s19, 20
	s_load_dwordx16 s[4:19], s[0:1], 0xc0
	s_mov_b32 s28, 0x10000
	v_mov_b32_e32 v198, 0x358637bd
	s_movk_i32 s96, 0x43ff
	s_mov_b32 s29, 0x20000
	s_waitcnt lgkmcnt(0)
	v_writelane_b32 v252, s4, 21
	v_mov_b32_e32 v199, 0x10000
	s_movk_i32 s33, 0x110
	v_writelane_b32 v252, s5, 22
	v_writelane_b32 v252, s6, 23
	v_writelane_b32 v252, s7, 24
	v_writelane_b32 v252, s8, 25
	v_writelane_b32 v252, s9, 26
	v_writelane_b32 v252, s10, 27
	v_writelane_b32 v252, s11, 28
	v_writelane_b32 v252, s12, 29
	v_writelane_b32 v252, s13, 30
	v_writelane_b32 v252, s14, 31
	v_writelane_b32 v252, s15, 32
	v_writelane_b32 v252, s16, 33
	v_writelane_b32 v252, s17, 34
	v_writelane_b32 v252, s18, 35
	v_writelane_b32 v252, s19, 36
	s_load_dwordx16 s[4:19], s[0:1], 0x100
	v_mov_b32_e32 v201, 0x3ecc95a3
	v_mov_b64_e32 v[212:213], 0xe00
	v_mov_b64_e32 v[196:197], 0x3600
	v_mov_b32_e32 v204, 0x7f800000
	s_waitcnt lgkmcnt(0)
	v_writelane_b32 v252, s4, 37
	v_mov_b32_e32 v206, 0x41b17218
	v_mov_b32_e32 v136, 0x3f317218
	v_writelane_b32 v252, s5, 38
	v_writelane_b32 v252, s6, 39
	v_writelane_b32 v252, s7, 40
	v_writelane_b32 v252, s8, 41
	v_writelane_b32 v252, s9, 42
	v_writelane_b32 v252, s10, 43
	v_writelane_b32 v252, s11, 44
	v_writelane_b32 v252, s12, 45
	v_writelane_b32 v252, s13, 46
	v_writelane_b32 v252, s14, 47
	v_writelane_b32 v252, s15, 48
	v_writelane_b32 v252, s16, 49
	v_writelane_b32 v252, s17, 50
	v_writelane_b32 v252, s18, 51
	v_writelane_b32 v252, s19, 52
	s_load_dwordx16 s[72:87], s[0:1], 0x140
	s_load_dwordx16 s[4:19], s[0:1], 0x1b0
	v_mov_b32_e32 v203, 0x7fc00000
	v_mov_b32_e32 v195, 0xff800000
	v_mov_b32_e32 v205, 0xe400
	v_mov_b32_e32 v200, 0x9f00
	s_waitcnt lgkmcnt(0)
	v_writelane_b32 v252, s4, 53
	v_mov_b32_e32 v207, 0x42800000
	s_nop 0
	v_writelane_b32 v252, s5, 54
	v_writelane_b32 v252, s6, 55
	v_writelane_b32 v252, s7, 56
	v_writelane_b32 v253, s15, 0
	v_writelane_b32 v252, s8, 57
	v_writelane_b32 v253, s16, 1
	v_writelane_b32 v252, s9, 58
	v_writelane_b32 v253, s17, 2
	v_writelane_b32 v252, s10, 59
	v_writelane_b32 v253, s18, 3
	v_writelane_b32 v252, s11, 60
	v_writelane_b32 v253, s19, 4
	s_load_dwordx8 s[4:11], s[0:1], 0x1f0
	s_add_u32 s0, s0, 0x218
	s_addc_u32 s1, s1, 0
	v_writelane_b32 v252, s12, 61
	v_writelane_b32 v252, s13, 62
	s_waitcnt lgkmcnt(0)
	v_writelane_b32 v253, s4, 5
	v_writelane_b32 v252, s14, 63
	s_nop 0
	v_writelane_b32 v253, s5, 6
	v_writelane_b32 v253, s6, 7
	v_writelane_b32 v253, s7, 8
	v_writelane_b32 v253, s8, 9
	v_writelane_b32 v253, s9, 10
	v_writelane_b32 v253, s10, 11
	v_writelane_b32 v253, s11, 12
	v_writelane_b32 v253, s0, 13
	s_nop 1
	v_writelane_b32 v253, s1, 14
	s_add_u32 s0, s88, 0x200
	s_addc_u32 s1, s89, 0
	v_writelane_b32 v253, s0, 15
	s_nop 1
	v_writelane_b32 v253, s1, 16
	s_add_u32 s0, s88, 0x1000
	s_addc_u32 s1, s89, 0
	v_writelane_b32 v253, s0, 17
	s_nop 1
	v_writelane_b32 v253, s1, 18
	s_add_u32 s0, s88, 0x1100
	s_addc_u32 s1, s89, 0
	v_writelane_b32 v253, s0, 19
	s_nop 1
	v_writelane_b32 v253, s1, 20
	s_add_u32 s0, s88, 0x1200
	s_addc_u32 s1, s89, 0
	v_writelane_b32 v253, s0, 21
	s_nop 1
	v_writelane_b32 v253, s1, 22
	s_add_u32 s0, s88, 0x1300
	s_addc_u32 s1, s89, 0
	v_writelane_b32 v253, s0, 23
	s_cmp_eq_u32 s20, 15
	s_nop 0
	v_writelane_b32 v253, s1, 24
	s_cselect_b64 s[0:1], -1, 0
	v_writelane_b32 v253, s0, 25
	s_cmp_eq_u32 s20, 14
	s_nop 0
	v_writelane_b32 v253, s1, 26
	s_cselect_b64 s[0:1], -1, 0
	v_writelane_b32 v253, s0, 27
	s_cmp_eq_u32 s20, 13
	s_nop 0
	v_writelane_b32 v253, s1, 28
	s_cselect_b64 s[0:1], -1, 0
	v_writelane_b32 v253, s0, 29
	s_cmp_eq_u32 s20, 12
	s_nop 0
	v_writelane_b32 v253, s1, 30
	s_cselect_b64 s[0:1], -1, 0
	v_writelane_b32 v253, s0, 31
	s_cmp_eq_u32 s20, 11
	s_nop 0
	v_writelane_b32 v253, s1, 32
	s_cselect_b64 s[0:1], -1, 0
	v_writelane_b32 v253, s0, 33
	s_cmp_eq_u32 s20, 10
	s_nop 0
	v_writelane_b32 v253, s1, 34
	s_cselect_b64 s[0:1], -1, 0
	v_writelane_b32 v253, s0, 35
	s_cmp_eq_u32 s20, 9
	s_nop 0
	v_writelane_b32 v253, s1, 36
	s_cselect_b64 s[0:1], -1, 0
	v_writelane_b32 v253, s0, 37
	s_cmp_eq_u32 s20, 8
	s_nop 0
	v_writelane_b32 v253, s1, 38
	s_cselect_b64 s[0:1], -1, 0
	v_writelane_b32 v253, s0, 39
	s_cmp_eq_u32 s20, 7
	s_nop 0
	v_writelane_b32 v253, s1, 40
	s_cselect_b64 s[0:1], -1, 0
	v_writelane_b32 v253, s0, 41
	s_cmp_eq_u32 s20, 6
	s_nop 0
	v_writelane_b32 v253, s1, 42
	s_cselect_b64 s[0:1], -1, 0
	v_writelane_b32 v253, s0, 43
	s_cmp_eq_u32 s20, 5
	s_nop 0
	v_writelane_b32 v253, s1, 44
	s_cselect_b64 s[0:1], -1, 0
	v_writelane_b32 v253, s0, 45
	s_cmp_eq_u32 s20, 4
	s_nop 0
	v_writelane_b32 v253, s1, 46
	s_cselect_b64 s[0:1], -1, 0
	v_writelane_b32 v253, s0, 47
	s_cmp_eq_u32 s20, 3
	s_nop 0
	v_writelane_b32 v253, s1, 48
	s_cselect_b64 s[0:1], -1, 0
	v_writelane_b32 v253, s0, 49
	s_cmp_eq_u32 s20, 2
	s_nop 0
	v_writelane_b32 v253, s1, 50
	s_cselect_b64 s[0:1], -1, 0
	v_writelane_b32 v253, s0, 51
	s_cmp_eq_u32 s20, 1
	s_nop 0
	v_writelane_b32 v253, s1, 52
	s_cselect_b64 s[0:1], -1, 0
	v_writelane_b32 v253, s0, 53
	s_cmp_eq_u32 s20, 0
	s_nop 0
	v_writelane_b32 v253, s1, 54
	s_cselect_b64 s[0:1], -1, 0
	v_writelane_b32 v253, s0, 55
	s_nop 1
	v_writelane_b32 v253, s1, 56
	s_lshl_b32 s0, s20, 8
	s_add_u32 s0, s88, s0
	s_addc_u32 s1, s89, 0
	s_add_u32 s2, s0, 0x1400
	s_addc_u32 s3, s1, 0
	v_writelane_b32 v253, s2, 57
	s_add_u32 s0, s0, 0x2400
	s_addc_u32 s1, s1, 0
	v_writelane_b32 v253, s3, 58
	v_writelane_b32 v253, s0, 59
	v_readlane_b32 s3, v252, 0
	s_nop 0
	v_writelane_b32 v253, s1, 60
	s_add_u32 s0, s88, 0x3400
	s_addc_u32 s1, s89, 0
	v_writelane_b32 v253, s0, 61
	s_nop 1
	v_writelane_b32 v253, s1, 62
	s_add_u32 s0, s88, 0x3500
	s_addc_u32 s1, s89, 0
	v_writelane_b32 v253, s0, 63
	s_cmp_lt_i32 s53, 0
	s_nop 0
	v_writelane_b32 v254, s1, 0
	s_cselect_b64 s[0:1], -1, 0
	v_writelane_b32 v254, s0, 1
	s_nop 1
	v_writelane_b32 v254, s1, 2
	s_movk_i32 s0, 0x3ff
	v_and_or_b32 v0, v0, s0, v194
	v_cmp_eq_u32_e64 s[0:1], 0, v0
	s_nop 1
	v_writelane_b32 v254, s0, 3
	s_nop 1
	v_writelane_b32 v254, s1, 4
	s_lshl_b32 s0, s3, 2
	v_writelane_b32 v254, s0, 5
	s_add_u32 s0, s42, 0x1000
	v_writelane_b32 v254, s36, 6
	s_addc_u32 s1, s43, 0
	s_cmp_lg_u64 s[84:85], 0
	v_writelane_b32 v254, s37, 7
	v_writelane_b32 v254, s38, 8
	v_writelane_b32 v254, s39, 9
	v_writelane_b32 v254, s40, 10
	v_writelane_b32 v254, s41, 11
	v_writelane_b32 v254, s42, 12
	v_writelane_b32 v254, s43, 13
	v_writelane_b32 v254, s44, 14
	v_writelane_b32 v254, s45, 15
	v_writelane_b32 v254, s46, 16
	v_writelane_b32 v254, s47, 17
	v_writelane_b32 v254, s48, 18
	v_writelane_b32 v254, s49, 19
	v_writelane_b32 v254, s50, 20
	v_writelane_b32 v254, s51, 21
	v_writelane_b32 v254, s0, 22
	s_mov_b64 s[36:37], 0x800
	s_nop 0
	v_writelane_b32 v254, s1, 23
	s_cselect_b64 s[0:1], -1, 0
	v_writelane_b32 v254, s0, 24
	s_cmpk_lt_i32 s3, 0x1560
	s_nop 0
	v_writelane_b32 v254, s1, 25
	s_cselect_b64 s[0:1], -1, 0
	v_writelane_b32 v254, s0, 26
	s_cmp_lg_u64 s[76:77], 0
	s_nop 0
	v_writelane_b32 v254, s1, 27
	s_cselect_b64 s[0:1], -1, 0
	v_writelane_b32 v254, s0, 28
	s_and_b32 s4, s3, 7
	s_lshl_b32 s2, s3, 4
	v_writelane_b32 v254, s1, 29
	s_lshr_b32 s0, s3, 3
	s_lshl_b32 s1, s4, 6
	v_writelane_b32 v254, s0, 30
	s_add_i32 s0, s1, s0
	v_writelane_b32 v254, s1, 31
	s_lshl_b32 s0, s0, 4
	s_and_b32 s2, s2, 0x380
	s_and_b32 s1, s0, 0xfffffc00
	v_writelane_b32 v254, s2, 32
	s_and_b32 s0, s0, 0x380
	v_writelane_b32 v254, s0, 33
	s_lshl_b32 s0, s3, 1
	s_and_b32 s0, s0, 0x7fffff80
	s_or_b32 s1, s1, s2
	s_addk_i32 s0, 0x4000
	v_writelane_b32 v254, s0, 34
	s_add_i32 s54, s1, 0x2000
	s_lshl_b32 s0, s4, 22
	v_writelane_b32 v254, s1, 35
	s_add_u32 s0, s80, s0
	v_writelane_b32 v254, s4, 36
	s_addc_u32 s1, s81, 0
	v_writelane_b32 v254, s0, 37
	s_nop 1
	v_writelane_b32 v254, s1, 38
	s_add_i32 s1, s22, -1
	s_mul_i32 s0, s1, 0x60
	v_writelane_b32 v254, s0, 39
	s_mul_i32 s0, s1, 0xa0
	v_writelane_b32 v254, s0, 40
	s_ashr_i32 s0, s1, 31
	v_writelane_b32 v254, s0, 41
	v_writelane_b32 v254, s22, 42
	s_sub_i32 s0, 1, s22
	s_max_i32 s0, s1, s0
	v_cvt_f32_u32_e32 v0, s0
	v_writelane_b32 v254, s23, 43
	v_writelane_b32 v254, s1, 44
	v_writelane_b32 v254, s0, 45
	v_rcp_iflag_f32_e32 v0, v0
	s_sub_i32 s0, 0, s0
	v_mul_f32_e32 v0, 0x4f7ffffe, v0
	v_cvt_u32_f32_e32 v0, v0
	s_nop 0
	v_readfirstlane_b32 s1, v0
	s_mul_i32 s0, s0, s1
	s_mul_hi_u32 s0, s1, s0
	s_add_i32 s0, s1, s0
	v_writelane_b32 v254, s0, 46
	s_add_u32 s0, s78, 64
	s_addc_u32 s1, s79, 0
	v_writelane_b32 v254, s0, 47
	v_mbcnt_lo_u32_b32 v0, -1, 0
	s_nop 0
	v_writelane_b32 v254, s1, 48
	v_readlane_b32 s0, v252, 1
	v_readlane_b32 s1, v252, 2
	s_add_u32 s2, s0, 0x100
	s_addc_u32 s3, s1, 0
	v_writelane_b32 v254, s2, 49
	v_mbcnt_hi_u32_b32 v202, -1, v0
	s_nop 0
	v_writelane_b32 v254, s3, 50
	s_add_u32 s2, s0, 0x140
	s_addc_u32 s3, s1, 0
	v_writelane_b32 v254, s2, 51
	s_nop 1
	v_writelane_b32 v254, s3, 52
	s_add_u32 s2, s0, 0x180
	s_addc_u32 s3, s1, 0
	v_writelane_b32 v254, s2, 53
	s_add_u32 s0, s0, 0x1c0
	s_addc_u32 s1, s1, 0
	v_writelane_b32 v254, s3, 54
	v_writelane_b32 v254, s0, 55
	s_mov_b32 s2, s52
	s_nop 0
	v_writelane_b32 v254, s1, 56
	s_add_u32 s0, s78, 0x2c00
	s_addc_u32 s1, s79, 0
	v_writelane_b32 v254, s0, 57
	s_nop 1
	v_writelane_b32 v254, s1, 58
	v_writelane_b32 v254, s54, 59
	v_writelane_b32 v254, s52, 60
	s_nop 1
	v_writelane_b32 v254, s53, 61
	s_branch .LBB0_9

.LBB0_134:
	s_andn2_b64 vcc, exec, s[2:3]
	s_movk_i32 s55, 0x4000
	v_readlane_b32 s54, v254, 59
	s_cbranch_vccnz .LBB0_165
	s_waitcnt vmcnt(0)
	v_mov_b32_e32 v74, v194
	s_movk_i32 s22, 0x1000
	s_movk_i32 s24, 0x1000
	s_movk_i32 s2, 0x1000
	v_lshlrev_b32_e32 v0, 3, v74
	v_ashrrev_i32_e32 v3, 3, v74
	v_and_b32_e32 v0, 56, v0
	v_lshrrev_b32_e32 v132, 4, v74
	v_xor_b32_e32 v132, v132, v74
	v_and_b32_e32 v132, 7, v132
	v_lshlrev_b32_e32 v0, 3, v132
	v_mov_b32_e32 v1, v2
	s_ashr_i32 s40, s2, 6
	s_ashr_i32 s41, s2, 9
	v_mad_i64_i32 v[4:5], s[2:3], s22, v3, v[0:1]
	v_mad_i64_i32 v[6:7], s[2:3], s24, v3, v[0:1]
	v_readlane_b32 s47, v254, 35
	s_mul_hi_i32 s3, s22, s47
	s_mul_i32 s2, s22, s47
	s_ashr_i32 s23, s22, 31
	s_ashr_i32 s25, s24, 31
	s_lshl_b64 s[2:3], s[2:3], 1
	s_add_u32 s2, s78, s2
	s_addc_u32 s3, s79, s3
	v_lshlrev_b64 v[68:69], 1, v[4:5]
	v_readlane_b32 s46, v254, 33
	v_lshl_add_u64 v[0:1], s[2:3], 0, v[68:69]
	s_mul_hi_i32 s3, s24, s46
	s_mul_i32 s2, s24, s46
	s_lshl_b64 s[26:27], s[2:3], 1
	s_add_u32 s2, s0, s26
	s_addc_u32 s3, s1, s27
	v_lshlrev_b64 v[70:71], 1, v[6:7]
	v_lshl_add_u64 v[138:139], s[2:3], 0, v[70:71]
	s_lshl_b64 s[2:3], s[22:23], 6
	s_waitcnt vmcnt(0)
	v_lshl_add_u64 v[28:29], v[0:1], 0, s[2:3]
	s_lshl_b64 s[20:21], s[24:25], 6
	s_waitcnt vmcnt(0)
	v_lshl_add_u64 v[36:37], v[28:29], 0, s[2:3]
	s_waitcnt vmcnt(0)
	v_lshl_add_u64 v[56:57], v[138:139], 0, s[20:21]
	v_lshl_add_u64 v[40:41], v[36:37], 0, s[2:3]
	s_waitcnt vmcnt(0)
	v_lshl_add_u64 v[60:61], v[56:57], 0, s[20:21]
	s_waitcnt vmcnt(0)
	v_lshl_add_u64 v[64:65], v[60:61], 0, s[20:21]
	s_bfe_u32 s100, s101, 0x20002
	s_lshl_b32 s100, s100, 10
	s_add_u32 m0, s100, 0x0
	s_nop 0
	global_load_lds_dwordx4 v[0:1], off
	s_add_u32 m0, s100, 0x1000
	s_nop 0
	global_load_lds_dwordx4 v[28:29], off
	s_add_u32 m0, s100, 0x2000
	s_nop 0
	global_load_lds_dwordx4 v[36:37], off
	s_add_u32 m0, s100, 0x3000
	s_nop 0
	global_load_lds_dwordx4 v[40:41], off
	s_add_u32 m0, s100, 0x4000
	s_nop 0
	global_load_lds_dwordx4 v[138:139], off
	s_add_u32 m0, s100, 0x5000
	s_nop 0
	global_load_lds_dwordx4 v[56:57], off
	s_add_u32 m0, s100, 0x6000
	s_nop 0
	global_load_lds_dwordx4 v[60:61], off
	s_add_u32 m0, s100, 0x7000
	s_nop 0
	global_load_lds_dwordx4 v[64:65], off
	s_add_u32 m0, s100, 0x7f80
	s_nop 0
	global_load_lds_dwordx4 v[0:1], off offset:128
	s_add_u32 m0, s100, 0x8f80
	s_nop 0
	global_load_lds_dwordx4 v[28:29], off offset:128
	s_add_u32 m0, s100, 0x9f80
	s_nop 0
	global_load_lds_dwordx4 v[36:37], off offset:128
	s_add_u32 m0, s100, 0xaf80
	s_nop 0
	global_load_lds_dwordx4 v[40:41], off offset:128
	s_add_u32 m0, s100, 0xbf80
	s_nop 0
	global_load_lds_dwordx4 v[138:139], off offset:128
	s_add_u32 m0, s100, 0xcf80
	s_nop 0
	global_load_lds_dwordx4 v[56:57], off offset:128
	s_add_u32 m0, s100, 0xdf80
	s_nop 0
	global_load_lds_dwordx4 v[60:61], off offset:128
	s_add_u32 m0, s100, 0xef80
	s_nop 0
	global_load_lds_dwordx4 v[64:65], off offset:128
	v_lshlrev_b32_e32 v72, 7, v3
	v_lshrrev_b32_e32 v3, 1, v3
	v_xor_b32_e32 v3, v3, v74
	v_lshl_add_u64 v[70:71], s[0:1], 0, v[70:71]
	v_readlane_b32 s0, v254, 34
	v_lshlrev_b32_e32 v3, 4, v3
	s_movk_i32 s6, 0x70
	v_lshl_add_u64 v[68:69], s[78:79], 0, v[68:69]
	s_mul_hi_i32 s1, s22, s0
	s_mul_i32 s0, s22, s0
	v_and_or_b32 v3, v3, s6, v72
	v_lshl_add_u64 v[72:73], s[0:1], 1, v[68:69]
	v_readlane_b32 s0, v254, 31
	s_mul_hi_i32 s1, s41, s0
	s_mul_i32 s0, s41, s0
	v_readlane_b32 s6, v254, 32
	s_lshl_b64 s[0:1], s[0:1], 1
	s_mul_hi_i32 s25, s24, s6
	s_mul_i32 s24, s24, s6
	v_lshl_add_u64 v[140:141], v[72:73], 0, s[0:1]
	v_lshl_add_u64 v[72:73], s[24:25], 1, v[70:71]
	v_lshl_add_u64 v[142:143], v[72:73], 0, s[0:1]
	s_mul_hi_i32 s1, s22, s54
	s_mul_i32 s0, s22, s54
	v_lshrrev_b32_e32 v75, 4, v74
	v_bfe_u32 v76, v74, 4, 2
	v_lshl_add_u64 v[144:145], s[0:1], 1, v[68:69]
	v_bfe_u32 v68, v74, 1, 3
	v_lshl_add_u64 v[146:147], v[70:71], 0, s[26:27]
	v_bitop3_b32 v69, v75, v68, 3 bitop3:0x6c
	v_lshlrev_b32_e32 v70, 6, v74
	v_lshlrev_b32_e32 v71, 7, v74
	v_bitop3_b32 v68, v76, v68, 4 bitop3:0x36
	v_lshlrev_b32_e32 v69, 4, v69
	v_and_b32_e32 v70, 0xffffe000, v70
	v_and_b32_e32 v72, 0x780, v71
	v_and_b32_e32 v71, 0x2000, v71
	v_lshlrev_b32_e32 v68, 4, v68
	v_or_b32_e32 v73, v69, v70
	v_or_b32_e32 v69, v69, v71
	v_or_b32_e32 v70, v68, v70
	v_or_b32_e32 v68, v68, v71
	s_mov_b32 s42, 0
	v_add_u32_e32 v137, v73, v72
	v_add_u32_e32 v192, v69, v72
	v_add_u32_e32 v193, v70, v72
	v_add_u32_e32 v214, v68, v72
	s_mov_b32 s43, s40
	s_mov_b32 s44, 0
	s_mov_b32 s45, 0
	s_bfe_u32 vcc_lo, s101, 0x10001
	v_and_b32_e32 v20, 15, v194
	v_lshrrev_b32_e32 v21, 1, v20
	v_bfe_u32 v22, v194, 4, 2
	v_xor_b32_e32 v21, v21, v22
	v_lshlrev_b32_e32 v21, 4, v21
	v_lshl_or_b32 v250, v20, 7, v21
	v_mov_b32_e32 v22, vcc_lo
	v_lshl_or_b32 v22, v22, 13, v250
	v_or_b32_e32 v251, 0x4000, v22
	v_and_b32_e32 v20, 63, v194
	v_mov_b32_e32 v21, vcc_lo
	v_lshlrev_b32_e32 v21, 4, v21
	v_lshrrev_b32_e32 v22, 3, v20
	v_add_u32_e32 v21, v21, v22
	v_lshrrev_b32_e32 v22, 4, v20
	v_and_b32_e32 v23, 7, v20
	v_xor_b32_e32 v24, v23, v22
	v_lshlrev_b32_e32 v24, 4, v24
	v_or_b32_e32 v22, 4, v22
	v_xor_b32_e32 v25, v23, v22
	v_lshlrev_b32_e32 v25, 4, v25
	s_movk_i32 s98, 0x2000
	s_movk_i32 s99, 0x2000
	v_add_u32_e32 v26, 0, v21
	v_mad_u32_u24 v4, v26, s98, v24
	v_add_u32_e32 v26, 8, v21
	v_mad_u32_u24 v5, v26, s98, v25
	v_add_u32_e32 v26, 32, v21
	v_mad_u32_u24 v6, v26, s98, v24
	v_add_u32_e32 v26, 40, v21
	v_mad_u32_u24 v7, v26, s98, v25
	v_add_u32_e32 v26, 64, v21
	v_mad_u32_u24 v8, v26, s98, v24
	v_add_u32_e32 v26, 72, v21
	v_mad_u32_u24 v9, v26, s98, v25
	v_add_u32_e32 v26, 96, v21
	v_mad_u32_u24 v10, v26, s98, v24
	v_add_u32_e32 v26, 104, v21
	v_mad_u32_u24 v11, v26, s98, v25
	v_add_u32_e32 v26, 0, v21
	v_mad_u32_u24 v12, v26, s99, v24
	v_add_u32_e32 v26, 8, v21
	v_mad_u32_u24 v13, v26, s99, v25
	v_add_u32_e32 v26, 32, v21
	v_mad_u32_u24 v14, v26, s99, v24
	v_add_u32_e32 v26, 40, v21
	v_mad_u32_u24 v15, v26, s99, v25
	v_add_u32_e32 v26, 64, v21
	v_mad_u32_u24 v16, v26, s99, v24
	v_add_u32_e32 v26, 72, v21
	v_mad_u32_u24 v17, v26, s99, v25
	v_add_u32_e32 v26, 96, v21
	v_mad_u32_u24 v18, v26, s99, v24
	v_add_u32_e32 v26, 104, v21
	v_mad_u32_u24 v19, v26, s99, v25
	s_bfe_u32 vcc_hi, s101, 0x20002
	s_lshl_b32 vcc_hi, vcc_hi, 3
	s_mul_i32 s98, s98, vcc_hi
	s_mul_i32 s99, s99, vcc_hi
	s_lshl_b32 vcc_hi, vcc_hi, 3
	s_and_b32 vcc_hi, vcc_hi, 0x70
	s_add_u32 s98, s98, vcc_hi
	s_add_u32 s99, s99, vcc_hi
	s_lshl_b32 s100, vcc_lo, 11
	s_bitcmp1_b32 s101, 0
	s_cselect_b32 s100, -1, s100
	s_waitcnt vmcnt(0) lgkmcnt(0)
	s_barrier
	s_branch .LBB0_138

.LBB0_137:
	v_lshrrev_b32_e32 v133, 2, v149
	v_and_b32_e32 v132, 64, v150
	v_and_b32_e32 v133, 12, v133
	v_ashrrev_i32_e32 v149, 31, v148
	v_add3_u32 v132, v132, s46, v133
	v_lshlrev_b64 v[134:135], 12, v[148:149]
	v_mov_b32_e32 v133, v2
	v_lshl_add_u64 v[134:135], s[0:1], 0, v[134:135]
	v_lshlrev_b64 v[132:133], 2, v[132:133]
	v_lshl_add_u64 v[134:135], v[134:135], 0, v[132:133]
	global_store_dwordx4 v[134:135], v[128:131], off
	global_store_dwordx4 v[134:135], v[124:127], off offset:64
	global_store_dwordx4 v[134:135], v[120:123], off offset:128
	global_store_dwordx4 v[134:135], v[112:115], off offset:192
	s_add_i32 s42, s42, 1
	s_cmp_eq_u32 s42, 3
	v_add_u32_e32 v112, 16, v148
	v_ashrrev_i32_e32 v113, 31, v112
	v_lshlrev_b64 v[112:113], 12, v[112:113]
	v_lshl_add_u64 v[112:113], s[0:1], 0, v[112:113]
	v_lshl_add_u64 v[112:113], v[112:113], 0, v[132:133]
	global_store_dwordx4 v[112:113], v[116:119], off
	global_store_dwordx4 v[112:113], v[108:111], off offset:64
	global_store_dwordx4 v[112:113], v[104:107], off offset:128
	global_store_dwordx4 v[112:113], v[100:103], off offset:192
	s_mov_b32 s46, s44
	s_mov_b32 s47, s45
	v_add_u32_e32 v100, 32, v148
	v_ashrrev_i32_e32 v101, 31, v100
	v_lshlrev_b64 v[100:101], 12, v[100:101]
	v_lshl_add_u64 v[100:101], s[0:1], 0, v[100:101]
	v_lshl_add_u64 v[100:101], v[100:101], 0, v[132:133]
	global_store_dwordx4 v[100:101], v[96:99], off
	global_store_dwordx4 v[100:101], v[92:95], off offset:64
	global_store_dwordx4 v[100:101], v[88:91], off offset:128
	global_store_dwordx4 v[100:101], v[84:87], off offset:192
	s_nop 1
	v_add_u32_e32 v84, 48, v148
	v_ashrrev_i32_e32 v85, 31, v84
	v_lshlrev_b64 v[84:85], 12, v[84:85]
	v_lshl_add_u64 v[84:85], s[0:1], 0, v[84:85]
	v_lshl_add_u64 v[84:85], v[84:85], 0, v[132:133]
	global_store_dwordx4 v[84:85], v[80:83], off
	global_store_dwordx4 v[84:85], v[76:79], off offset:64
	global_store_dwordx4 v[84:85], v[72:75], off offset:128
	global_store_dwordx4 v[84:85], v[68:71], off offset:192
	s_branch .Lpc_edone_5

.LBB0_144:
	s_cmp_lg_u32 s42, 2
	s_cselect_b64 s[22:23], -1, 0
	s_cmp_eq_u32 s42, 2
	s_cselect_b64 s[0:1], -1, 0
	s_cmp_lt_i32 s52, 1
	s_cbranch_scc1 .LBB0_161
	v_lshl_add_u64 v[152:153], v[0:1], 0, s[2:3]
	v_lshl_add_u64 v[158:159], v[138:139], 0, s[20:21]
	v_lshl_add_u64 v[164:165], v[150:151], 0, s[2:3]
	v_lshl_add_u64 v[170:171], v[148:149], 0, s[20:21]
	v_lshl_add_u64 v[154:155], v[152:153], 0, s[2:3]
	v_lshl_add_u64 v[160:161], v[158:159], 0, s[20:21]
	v_lshl_add_u64 v[166:167], v[164:165], 0, s[2:3]
	v_lshl_add_u64 v[172:173], v[170:171], 0, s[20:21]
	v_mov_b32_e32 v68, 0
	v_lshl_add_u64 v[156:157], v[154:155], 0, s[2:3]
	v_lshl_add_u64 v[162:163], v[160:161], 0, s[20:21]
	v_lshl_add_u64 v[168:169], v[166:167], 0, s[2:3]
	v_lshl_add_u64 v[174:175], v[172:173], 0, s[20:21]
	s_mov_b64 s[24:25], 0x100
	s_mov_b32 s53, 2
	v_mov_b32_e32 v69, v68
	v_mov_b32_e32 v70, v68
	v_mov_b32_e32 v71, v68
	v_mov_b32_e32 v72, v68
	v_mov_b32_e32 v73, v68
	v_mov_b32_e32 v74, v68
	v_mov_b32_e32 v75, v68
	v_mov_b32_e32 v76, v68
	v_mov_b32_e32 v77, v68
	v_mov_b32_e32 v78, v68
	v_mov_b32_e32 v79, v68
	v_mov_b32_e32 v80, v68
	v_mov_b32_e32 v81, v68
	v_mov_b32_e32 v82, v68
	v_mov_b32_e32 v83, v68
	v_mov_b32_e32 v84, v68
	v_mov_b32_e32 v85, v68
	v_mov_b32_e32 v86, v68
	v_mov_b32_e32 v87, v68
	v_mov_b32_e32 v88, v68
	v_mov_b32_e32 v89, v68
	v_mov_b32_e32 v90, v68
	v_mov_b32_e32 v91, v68
	v_mov_b32_e32 v92, v68
	v_mov_b32_e32 v93, v68
	v_mov_b32_e32 v94, v68
	v_mov_b32_e32 v95, v68
	v_mov_b32_e32 v96, v68
	v_mov_b32_e32 v97, v68
	v_mov_b32_e32 v98, v68
	v_mov_b32_e32 v99, v68
	v_mov_b32_e32 v100, v68
	v_mov_b32_e32 v101, v68
	v_mov_b32_e32 v102, v68
	v_mov_b32_e32 v103, v68
	v_mov_b32_e32 v104, v68
	v_mov_b32_e32 v105, v68
	v_mov_b32_e32 v106, v68
	v_mov_b32_e32 v107, v68
	v_mov_b32_e32 v108, v68
	v_mov_b32_e32 v109, v68
	v_mov_b32_e32 v110, v68
	v_mov_b32_e32 v111, v68
	v_mov_b32_e32 v116, v68
	v_mov_b32_e32 v117, v68
	v_mov_b32_e32 v118, v68
	v_mov_b32_e32 v119, v68
	v_mov_b32_e32 v112, v68
	v_mov_b32_e32 v113, v68
	v_mov_b32_e32 v114, v68
	v_mov_b32_e32 v115, v68
	v_mov_b32_e32 v120, v68
	v_mov_b32_e32 v121, v68
	v_mov_b32_e32 v122, v68
	v_mov_b32_e32 v123, v68
	v_mov_b32_e32 v124, v68
	v_mov_b32_e32 v125, v68
	v_mov_b32_e32 v126, v68
	v_mov_b32_e32 v127, v68
	v_mov_b32_e32 v128, v68
	v_mov_b32_e32 v129, v68
	v_mov_b32_e32 v130, v68
	v_mov_b32_e32 v131, v68
	s_branch .LBB0_147
.LBB0_147:
	s_cmp_ge_i32 s100, 0
	s_cbranch_scc1 .Lpc_prod_5
	v_mov_b64_e32 v[4:5], 0
	v_mov_b64_e32 v[6:7], 0
	v_mov_b64_e32 v[8:9], 0
	v_mov_b64_e32 v[10:11], 0
	v_mov_b64_e32 v[12:13], 0
	v_mov_b64_e32 v[14:15], 0
	v_mov_b64_e32 v[16:17], 0
	v_mov_b64_e32 v[18:19], 0
	v_mov_b64_e32 v[20:21], 0
	v_mov_b64_e32 v[22:23], 0
	v_mov_b64_e32 v[24:25], 0
	v_mov_b64_e32 v[26:27], 0
	v_mov_b64_e32 v[28:29], 0
	v_mov_b64_e32 v[30:31], 0
	v_mov_b64_e32 v[32:33], 0
	v_mov_b64_e32 v[34:35], 0
	v_mov_b64_e32 v[36:37], 0
	v_mov_b64_e32 v[38:39], 0
	v_mov_b64_e32 v[40:41], 0
	v_mov_b64_e32 v[42:43], 0
	v_mov_b64_e32 v[44:45], 0
	v_mov_b64_e32 v[46:47], 0
	v_mov_b64_e32 v[48:49], 0
	v_mov_b64_e32 v[50:51], 0
	v_mov_b64_e32 v[52:53], 0
	v_mov_b64_e32 v[54:55], 0
	v_mov_b64_e32 v[56:57], 0
	v_mov_b64_e32 v[58:59], 0
	v_mov_b64_e32 v[60:61], 0
	v_mov_b64_e32 v[62:63], 0
	v_mov_b64_e32 v[64:65], 0
	v_mov_b64_e32 v[66:67], 0
	v_xor_b32_e32 v192, 64, v250
	v_xor_b32_e32 v137, 64, v251
	ds_read_b128 v[224:227], v251
	ds_read_b128 v[228:231], v251 offset:2048
	ds_read_b128 v[240:243], v251 offset:4096
	ds_read_b128 v[244:247], v251 offset:6144
	ds_read_b128 v[176:179], v250
	ds_read_b128 v[180:183], v250 offset:2048
	ds_read_b128 v[184:187], v250 offset:4096
	ds_read_b128 v[188:191], v250 offset:6144
	ds_read_b128 v[132:135], v250 offset:8192
	ds_read_b128 v[208:211], v250 offset:10240
	ds_read_b128 v[216:219], v250 offset:12288
	ds_read_b128 v[220:223], v250 offset:14336
	ds_read_b128 v[232:235], v137
	ds_read_b128 v[236:239], v137 offset:2048
	ds_read_b128 v[164:167], v137 offset:4096
	s_waitcnt lgkmcnt(14)
	ds_read_b128 v[168:171], v137 offset:6144
	s_waitcnt lgkmcnt(14)
	ds_read_b128 v[148:151], v192
	s_waitcnt lgkmcnt(14)
	ds_read_b128 v[172:175], v192 offset:2048
	s_waitcnt lgkmcnt(14)
	ds_read_b128 v[152:155], v192 offset:4096
	s_waitcnt lgkmcnt(14)
	ds_read_b128 v[156:159], v192 offset:6144
	s_waitcnt lgkmcnt(14)
	ds_read_b128 v[160:163], v192 offset:8192
	v_mfma_f32_16x16x32_bf16 v[128:131], v[224:227], v[176:179], v[128:131]
	v_mfma_f32_16x16x32_bf16 v[124:127], v[228:231], v[176:179], v[124:127]
	v_mfma_f32_16x16x32_bf16 v[120:123], v[240:243], v[176:179], v[120:123]
	v_mfma_f32_16x16x32_bf16 v[112:115], v[244:247], v[176:179], v[112:115]
	s_waitcnt lgkmcnt(14)
	ds_read_b128 v[176:179], v192 offset:10240
	v_mfma_f32_16x16x32_bf16 v[116:119], v[224:227], v[180:183], v[116:119]
	v_mfma_f32_16x16x32_bf16 v[108:111], v[228:231], v[180:183], v[108:111]
	v_mfma_f32_16x16x32_bf16 v[104:107], v[240:243], v[180:183], v[104:107]
	v_mfma_f32_16x16x32_bf16 v[100:103], v[244:247], v[180:183], v[100:103]
	s_waitcnt lgkmcnt(14)
	ds_read_b128 v[180:183], v192 offset:12288
	v_mfma_f32_16x16x32_bf16 v[96:99], v[224:227], v[184:187], v[96:99]
	v_mfma_f32_16x16x32_bf16 v[92:95], v[228:231], v[184:187], v[92:95]
	v_mfma_f32_16x16x32_bf16 v[88:91], v[240:243], v[184:187], v[88:91]
	v_mfma_f32_16x16x32_bf16 v[84:87], v[244:247], v[184:187], v[84:87]
	s_waitcnt lgkmcnt(14)
	ds_read_b128 v[184:187], v192 offset:14336
	v_mfma_f32_16x16x32_bf16 v[80:83], v[224:227], v[188:191], v[80:83]
	v_mfma_f32_16x16x32_bf16 v[76:79], v[228:231], v[188:191], v[76:79]
	v_mfma_f32_16x16x32_bf16 v[72:75], v[240:243], v[188:191], v[72:75]
	v_mfma_f32_16x16x32_bf16 v[68:71], v[244:247], v[188:191], v[68:71]
	v_mfma_f32_16x16x32_bf16 v[4:7], v[224:227], v[132:135], v[4:7]
	v_mfma_f32_16x16x32_bf16 v[8:11], v[228:231], v[132:135], v[8:11]
	v_mfma_f32_16x16x32_bf16 v[12:15], v[240:243], v[132:135], v[12:15]
	v_mfma_f32_16x16x32_bf16 v[16:19], v[244:247], v[132:135], v[16:19]
	s_waitcnt lgkmcnt(0)
	s_barrier
	v_mfma_f32_16x16x32_bf16 v[20:23], v[224:227], v[208:211], v[20:23]
	v_mfma_f32_16x16x32_bf16 v[24:27], v[228:231], v[208:211], v[24:27]
	v_mfma_f32_16x16x32_bf16 v[28:31], v[240:243], v[208:211], v[28:31]
	v_mfma_f32_16x16x32_bf16 v[32:35], v[244:247], v[208:211], v[32:35]
	v_mfma_f32_16x16x32_bf16 v[36:39], v[224:227], v[216:219], v[36:39]
	v_mfma_f32_16x16x32_bf16 v[40:43], v[228:231], v[216:219], v[40:43]
	v_mfma_f32_16x16x32_bf16 v[44:47], v[240:243], v[216:219], v[44:47]
	v_mfma_f32_16x16x32_bf16 v[48:51], v[244:247], v[216:219], v[48:51]
	v_mfma_f32_16x16x32_bf16 v[52:55], v[224:227], v[220:223], v[52:55]
	v_mfma_f32_16x16x32_bf16 v[56:59], v[228:231], v[220:223], v[56:59]
	v_mfma_f32_16x16x32_bf16 v[60:63], v[240:243], v[220:223], v[60:63]
	v_mfma_f32_16x16x32_bf16 v[64:67], v[244:247], v[220:223], v[64:67]
	v_mfma_f32_16x16x32_bf16 v[128:131], v[232:235], v[148:151], v[128:131]
	v_mfma_f32_16x16x32_bf16 v[124:127], v[236:239], v[148:151], v[124:127]
	v_mfma_f32_16x16x32_bf16 v[120:123], v[164:167], v[148:151], v[120:123]
	v_mfma_f32_16x16x32_bf16 v[112:115], v[168:171], v[148:151], v[112:115]
	v_mfma_f32_16x16x32_bf16 v[116:119], v[232:235], v[172:175], v[116:119]
	v_mfma_f32_16x16x32_bf16 v[108:111], v[236:239], v[172:175], v[108:111]
	v_mfma_f32_16x16x32_bf16 v[104:107], v[164:167], v[172:175], v[104:107]
	v_mfma_f32_16x16x32_bf16 v[100:103], v[168:171], v[172:175], v[100:103]
	v_mfma_f32_16x16x32_bf16 v[96:99], v[232:235], v[152:155], v[96:99]
	v_mfma_f32_16x16x32_bf16 v[92:95], v[236:239], v[152:155], v[92:95]
	v_mfma_f32_16x16x32_bf16 v[88:91], v[164:167], v[152:155], v[88:91]
	v_mfma_f32_16x16x32_bf16 v[84:87], v[168:171], v[152:155], v[84:87]
	v_mfma_f32_16x16x32_bf16 v[20:23], v[232:235], v[176:179], v[20:23]
	v_mfma_f32_16x16x32_bf16 v[24:27], v[236:239], v[176:179], v[24:27]
	v_mfma_f32_16x16x32_bf16 v[28:31], v[164:167], v[176:179], v[28:31]
	v_mfma_f32_16x16x32_bf16 v[32:35], v[168:171], v[176:179], v[32:35]
	v_mfma_f32_16x16x32_bf16 v[36:39], v[232:235], v[180:183], v[36:39]
	v_mfma_f32_16x16x32_bf16 v[40:43], v[236:239], v[180:183], v[40:43]
	v_mfma_f32_16x16x32_bf16 v[44:47], v[164:167], v[180:183], v[44:47]
	v_mfma_f32_16x16x32_bf16 v[48:51], v[168:171], v[180:183], v[48:51]
	v_mfma_f32_16x16x32_bf16 v[52:55], v[232:235], v[184:187], v[52:55]
	v_mfma_f32_16x16x32_bf16 v[56:59], v[236:239], v[184:187], v[56:59]
	v_mfma_f32_16x16x32_bf16 v[60:63], v[164:167], v[184:187], v[60:63]
	v_mfma_f32_16x16x32_bf16 v[64:67], v[168:171], v[184:187], v[64:67]
	s_barrier
	s_branch .Lpc_ck1_5
.Lpc_ctop_5:
	ds_read_b128 v[224:227], v251
	ds_read_b128 v[228:231], v251 offset:2048
	ds_read_b128 v[240:243], v251 offset:4096
	ds_read_b128 v[244:247], v251 offset:6144
	ds_read_b128 v[176:179], v250
	ds_read_b128 v[180:183], v250 offset:2048
	ds_read_b128 v[184:187], v250 offset:4096
	ds_read_b128 v[188:191], v250 offset:6144
	ds_read_b128 v[132:135], v250 offset:8192
	ds_read_b128 v[208:211], v250 offset:10240
	v_mfma_f32_16x16x32_bf16 v[80:83], v[232:235], v[156:159], v[80:83]
	v_mfma_f32_16x16x32_bf16 v[76:79], v[236:239], v[156:159], v[76:79]
	v_mfma_f32_16x16x32_bf16 v[72:75], v[164:167], v[156:159], v[72:75]
	v_mfma_f32_16x16x32_bf16 v[68:71], v[168:171], v[156:159], v[68:71]
	v_mfma_f32_16x16x32_bf16 v[4:7], v[232:235], v[160:163], v[4:7]
	v_mfma_f32_16x16x32_bf16 v[8:11], v[236:239], v[160:163], v[8:11]
	v_mfma_f32_16x16x32_bf16 v[12:15], v[164:167], v[160:163], v[12:15]
	v_mfma_f32_16x16x32_bf16 v[16:19], v[168:171], v[160:163], v[16:19]
	ds_read_b128 v[216:219], v250 offset:12288
	ds_read_b128 v[220:223], v250 offset:14336
	ds_read_b128 v[232:235], v137
	ds_read_b128 v[236:239], v137 offset:2048
	ds_read_b128 v[164:167], v137 offset:4096
	s_waitcnt lgkmcnt(14)
	ds_read_b128 v[168:171], v137 offset:6144
	s_waitcnt lgkmcnt(14)
	ds_read_b128 v[148:151], v192
	s_waitcnt lgkmcnt(14)
	ds_read_b128 v[172:175], v192 offset:2048
	s_waitcnt lgkmcnt(14)
	ds_read_b128 v[152:155], v192 offset:4096
	s_waitcnt lgkmcnt(14)
	ds_read_b128 v[156:159], v192 offset:6144
	s_waitcnt lgkmcnt(14)
	ds_read_b128 v[160:163], v192 offset:8192
	v_mfma_f32_16x16x32_bf16 v[128:131], v[224:227], v[176:179], v[128:131]
	v_mfma_f32_16x16x32_bf16 v[124:127], v[228:231], v[176:179], v[124:127]
	v_mfma_f32_16x16x32_bf16 v[120:123], v[240:243], v[176:179], v[120:123]
	v_mfma_f32_16x16x32_bf16 v[112:115], v[244:247], v[176:179], v[112:115]
	s_waitcnt lgkmcnt(14)
	ds_read_b128 v[176:179], v192 offset:10240
	v_mfma_f32_16x16x32_bf16 v[116:119], v[224:227], v[180:183], v[116:119]
	v_mfma_f32_16x16x32_bf16 v[108:111], v[228:231], v[180:183], v[108:111]
	v_mfma_f32_16x16x32_bf16 v[104:107], v[240:243], v[180:183], v[104:107]
	v_mfma_f32_16x16x32_bf16 v[100:103], v[244:247], v[180:183], v[100:103]
	s_waitcnt lgkmcnt(14)
	ds_read_b128 v[180:183], v192 offset:12288
	v_mfma_f32_16x16x32_bf16 v[96:99], v[224:227], v[184:187], v[96:99]
	v_mfma_f32_16x16x32_bf16 v[92:95], v[228:231], v[184:187], v[92:95]
	v_mfma_f32_16x16x32_bf16 v[88:91], v[240:243], v[184:187], v[88:91]
	v_mfma_f32_16x16x32_bf16 v[84:87], v[244:247], v[184:187], v[84:87]
	s_waitcnt lgkmcnt(14)
	ds_read_b128 v[184:187], v192 offset:14336
	v_mfma_f32_16x16x32_bf16 v[80:83], v[224:227], v[188:191], v[80:83]
	v_mfma_f32_16x16x32_bf16 v[76:79], v[228:231], v[188:191], v[76:79]
	v_mfma_f32_16x16x32_bf16 v[72:75], v[240:243], v[188:191], v[72:75]
	v_mfma_f32_16x16x32_bf16 v[68:71], v[244:247], v[188:191], v[68:71]
	v_mfma_f32_16x16x32_bf16 v[4:7], v[224:227], v[132:135], v[4:7]
	v_mfma_f32_16x16x32_bf16 v[8:11], v[228:231], v[132:135], v[8:11]
	v_mfma_f32_16x16x32_bf16 v[12:15], v[240:243], v[132:135], v[12:15]
	v_mfma_f32_16x16x32_bf16 v[16:19], v[244:247], v[132:135], v[16:19]
	s_waitcnt lgkmcnt(0)
	s_barrier
	v_mfma_f32_16x16x32_bf16 v[20:23], v[224:227], v[208:211], v[20:23]
	v_mfma_f32_16x16x32_bf16 v[24:27], v[228:231], v[208:211], v[24:27]
	v_mfma_f32_16x16x32_bf16 v[28:31], v[240:243], v[208:211], v[28:31]
	v_mfma_f32_16x16x32_bf16 v[32:35], v[244:247], v[208:211], v[32:35]
	v_mfma_f32_16x16x32_bf16 v[36:39], v[224:227], v[216:219], v[36:39]
	v_mfma_f32_16x16x32_bf16 v[40:43], v[228:231], v[216:219], v[40:43]
	v_mfma_f32_16x16x32_bf16 v[44:47], v[240:243], v[216:219], v[44:47]
	v_mfma_f32_16x16x32_bf16 v[48:51], v[244:247], v[216:219], v[48:51]
	v_mfma_f32_16x16x32_bf16 v[52:55], v[224:227], v[220:223], v[52:55]
	v_mfma_f32_16x16x32_bf16 v[56:59], v[228:231], v[220:223], v[56:59]
	v_mfma_f32_16x16x32_bf16 v[60:63], v[240:243], v[220:223], v[60:63]
	v_mfma_f32_16x16x32_bf16 v[64:67], v[244:247], v[220:223], v[64:67]
	v_mfma_f32_16x16x32_bf16 v[128:131], v[232:235], v[148:151], v[128:131]
	v_mfma_f32_16x16x32_bf16 v[124:127], v[236:239], v[148:151], v[124:127]
	v_mfma_f32_16x16x32_bf16 v[120:123], v[164:167], v[148:151], v[120:123]
	v_mfma_f32_16x16x32_bf16 v[112:115], v[168:171], v[148:151], v[112:115]
	v_mfma_f32_16x16x32_bf16 v[116:119], v[232:235], v[172:175], v[116:119]
	v_mfma_f32_16x16x32_bf16 v[108:111], v[236:239], v[172:175], v[108:111]
	v_mfma_f32_16x16x32_bf16 v[104:107], v[164:167], v[172:175], v[104:107]
	v_mfma_f32_16x16x32_bf16 v[100:103], v[168:171], v[172:175], v[100:103]
	v_mfma_f32_16x16x32_bf16 v[96:99], v[232:235], v[152:155], v[96:99]
	v_mfma_f32_16x16x32_bf16 v[92:95], v[236:239], v[152:155], v[92:95]
	v_mfma_f32_16x16x32_bf16 v[88:91], v[164:167], v[152:155], v[88:91]
	v_mfma_f32_16x16x32_bf16 v[84:87], v[168:171], v[152:155], v[84:87]
	v_mfma_f32_16x16x32_bf16 v[20:23], v[232:235], v[176:179], v[20:23]
	v_mfma_f32_16x16x32_bf16 v[24:27], v[236:239], v[176:179], v[24:27]
	v_mfma_f32_16x16x32_bf16 v[28:31], v[164:167], v[176:179], v[28:31]
	v_mfma_f32_16x16x32_bf16 v[32:35], v[168:171], v[176:179], v[32:35]
	v_mfma_f32_16x16x32_bf16 v[36:39], v[232:235], v[180:183], v[36:39]
	v_mfma_f32_16x16x32_bf16 v[40:43], v[236:239], v[180:183], v[40:43]
	v_mfma_f32_16x16x32_bf16 v[44:47], v[164:167], v[180:183], v[44:47]
	v_mfma_f32_16x16x32_bf16 v[48:51], v[168:171], v[180:183], v[48:51]
	v_mfma_f32_16x16x32_bf16 v[52:55], v[232:235], v[184:187], v[52:55]
	v_mfma_f32_16x16x32_bf16 v[56:59], v[236:239], v[184:187], v[56:59]
	v_mfma_f32_16x16x32_bf16 v[60:63], v[164:167], v[184:187], v[60:63]
	v_mfma_f32_16x16x32_bf16 v[64:67], v[168:171], v[184:187], v[64:67]
	s_barrier
.Lpc_ck1_5:
	ds_read_b128 v[224:227], v251 offset:32768
	ds_read_b128 v[228:231], v251 offset:34816
	ds_read_b128 v[240:243], v251 offset:36864
	ds_read_b128 v[244:247], v251 offset:38912
	ds_read_b128 v[176:179], v250 offset:32768
	ds_read_b128 v[180:183], v250 offset:34816
	ds_read_b128 v[184:187], v250 offset:36864
	ds_read_b128 v[188:191], v250 offset:38912
	ds_read_b128 v[132:135], v250 offset:40960
	ds_read_b128 v[208:211], v250 offset:43008
	v_mfma_f32_16x16x32_bf16 v[80:83], v[232:235], v[156:159], v[80:83]
	v_mfma_f32_16x16x32_bf16 v[76:79], v[236:239], v[156:159], v[76:79]
	v_mfma_f32_16x16x32_bf16 v[72:75], v[164:167], v[156:159], v[72:75]
	v_mfma_f32_16x16x32_bf16 v[68:71], v[168:171], v[156:159], v[68:71]
	v_mfma_f32_16x16x32_bf16 v[4:7], v[232:235], v[160:163], v[4:7]
	v_mfma_f32_16x16x32_bf16 v[8:11], v[236:239], v[160:163], v[8:11]
	v_mfma_f32_16x16x32_bf16 v[12:15], v[164:167], v[160:163], v[12:15]
	v_mfma_f32_16x16x32_bf16 v[16:19], v[168:171], v[160:163], v[16:19]
	ds_read_b128 v[216:219], v250 offset:45056
	ds_read_b128 v[220:223], v250 offset:47104
	ds_read_b128 v[232:235], v137 offset:32768
	ds_read_b128 v[236:239], v137 offset:34816
	ds_read_b128 v[164:167], v137 offset:36864
	s_waitcnt lgkmcnt(14)
	ds_read_b128 v[168:171], v137 offset:38912
	s_waitcnt lgkmcnt(14)
	ds_read_b128 v[148:151], v192 offset:32768
	s_waitcnt lgkmcnt(14)
	ds_read_b128 v[172:175], v192 offset:34816
	s_waitcnt lgkmcnt(14)
	ds_read_b128 v[152:155], v192 offset:36864
	s_waitcnt lgkmcnt(14)
	ds_read_b128 v[156:159], v192 offset:38912
	s_waitcnt lgkmcnt(14)
	ds_read_b128 v[160:163], v192 offset:40960
	v_mfma_f32_16x16x32_bf16 v[128:131], v[224:227], v[176:179], v[128:131]
	v_mfma_f32_16x16x32_bf16 v[124:127], v[228:231], v[176:179], v[124:127]
	v_mfma_f32_16x16x32_bf16 v[120:123], v[240:243], v[176:179], v[120:123]
	v_mfma_f32_16x16x32_bf16 v[112:115], v[244:247], v[176:179], v[112:115]
	s_waitcnt lgkmcnt(14)
	ds_read_b128 v[176:179], v192 offset:43008
	v_mfma_f32_16x16x32_bf16 v[116:119], v[224:227], v[180:183], v[116:119]
	v_mfma_f32_16x16x32_bf16 v[108:111], v[228:231], v[180:183], v[108:111]
	v_mfma_f32_16x16x32_bf16 v[104:107], v[240:243], v[180:183], v[104:107]
	v_mfma_f32_16x16x32_bf16 v[100:103], v[244:247], v[180:183], v[100:103]
	s_waitcnt lgkmcnt(14)
	ds_read_b128 v[180:183], v192 offset:45056
	v_mfma_f32_16x16x32_bf16 v[96:99], v[224:227], v[184:187], v[96:99]
	v_mfma_f32_16x16x32_bf16 v[92:95], v[228:231], v[184:187], v[92:95]
	v_mfma_f32_16x16x32_bf16 v[88:91], v[240:243], v[184:187], v[88:91]
	v_mfma_f32_16x16x32_bf16 v[84:87], v[244:247], v[184:187], v[84:87]
	s_waitcnt lgkmcnt(14)
	ds_read_b128 v[184:187], v192 offset:47104
	v_mfma_f32_16x16x32_bf16 v[80:83], v[224:227], v[188:191], v[80:83]
	v_mfma_f32_16x16x32_bf16 v[76:79], v[228:231], v[188:191], v[76:79]
	v_mfma_f32_16x16x32_bf16 v[72:75], v[240:243], v[188:191], v[72:75]
	v_mfma_f32_16x16x32_bf16 v[68:71], v[244:247], v[188:191], v[68:71]
	v_mfma_f32_16x16x32_bf16 v[4:7], v[224:227], v[132:135], v[4:7]
	v_mfma_f32_16x16x32_bf16 v[8:11], v[228:231], v[132:135], v[8:11]
	v_mfma_f32_16x16x32_bf16 v[12:15], v[240:243], v[132:135], v[12:15]
	v_mfma_f32_16x16x32_bf16 v[16:19], v[244:247], v[132:135], v[16:19]
	s_waitcnt lgkmcnt(0)
	s_barrier
	v_mfma_f32_16x16x32_bf16 v[20:23], v[224:227], v[208:211], v[20:23]
	v_mfma_f32_16x16x32_bf16 v[24:27], v[228:231], v[208:211], v[24:27]
	v_mfma_f32_16x16x32_bf16 v[28:31], v[240:243], v[208:211], v[28:31]
	v_mfma_f32_16x16x32_bf16 v[32:35], v[244:247], v[208:211], v[32:35]
	v_mfma_f32_16x16x32_bf16 v[36:39], v[224:227], v[216:219], v[36:39]
	v_mfma_f32_16x16x32_bf16 v[40:43], v[228:231], v[216:219], v[40:43]
	v_mfma_f32_16x16x32_bf16 v[44:47], v[240:243], v[216:219], v[44:47]
	v_mfma_f32_16x16x32_bf16 v[48:51], v[244:247], v[216:219], v[48:51]
	v_mfma_f32_16x16x32_bf16 v[52:55], v[224:227], v[220:223], v[52:55]
	v_mfma_f32_16x16x32_bf16 v[56:59], v[228:231], v[220:223], v[56:59]
	v_mfma_f32_16x16x32_bf16 v[60:63], v[240:243], v[220:223], v[60:63]
	v_mfma_f32_16x16x32_bf16 v[64:67], v[244:247], v[220:223], v[64:67]
	v_mfma_f32_16x16x32_bf16 v[128:131], v[232:235], v[148:151], v[128:131]
	v_mfma_f32_16x16x32_bf16 v[124:127], v[236:239], v[148:151], v[124:127]
	v_mfma_f32_16x16x32_bf16 v[120:123], v[164:167], v[148:151], v[120:123]
	v_mfma_f32_16x16x32_bf16 v[112:115], v[168:171], v[148:151], v[112:115]
	v_mfma_f32_16x16x32_bf16 v[116:119], v[232:235], v[172:175], v[116:119]
	v_mfma_f32_16x16x32_bf16 v[108:111], v[236:239], v[172:175], v[108:111]
	v_mfma_f32_16x16x32_bf16 v[104:107], v[164:167], v[172:175], v[104:107]
	v_mfma_f32_16x16x32_bf16 v[100:103], v[168:171], v[172:175], v[100:103]
	v_mfma_f32_16x16x32_bf16 v[96:99], v[232:235], v[152:155], v[96:99]
	v_mfma_f32_16x16x32_bf16 v[92:95], v[236:239], v[152:155], v[92:95]
	v_mfma_f32_16x16x32_bf16 v[88:91], v[164:167], v[152:155], v[88:91]
	v_mfma_f32_16x16x32_bf16 v[84:87], v[168:171], v[152:155], v[84:87]
	v_mfma_f32_16x16x32_bf16 v[20:23], v[232:235], v[176:179], v[20:23]
	v_mfma_f32_16x16x32_bf16 v[24:27], v[236:239], v[176:179], v[24:27]
	v_mfma_f32_16x16x32_bf16 v[28:31], v[164:167], v[176:179], v[28:31]
	v_mfma_f32_16x16x32_bf16 v[32:35], v[168:171], v[176:179], v[32:35]
	v_mfma_f32_16x16x32_bf16 v[36:39], v[232:235], v[180:183], v[36:39]
	v_mfma_f32_16x16x32_bf16 v[40:43], v[236:239], v[180:183], v[40:43]
	v_mfma_f32_16x16x32_bf16 v[44:47], v[164:167], v[180:183], v[44:47]
	v_mfma_f32_16x16x32_bf16 v[48:51], v[168:171], v[180:183], v[48:51]
	v_mfma_f32_16x16x32_bf16 v[52:55], v[232:235], v[184:187], v[52:55]
	v_mfma_f32_16x16x32_bf16 v[56:59], v[236:239], v[184:187], v[56:59]
	v_mfma_f32_16x16x32_bf16 v[60:63], v[164:167], v[184:187], v[60:63]
	v_mfma_f32_16x16x32_bf16 v[64:67], v[168:171], v[184:187], v[64:67]
	s_barrier
	s_add_i32 s53, s53, 2
	s_cmp_le_i32 s53, s52
	s_cbranch_scc1 .Lpc_ctop_5
	v_mfma_f32_16x16x32_bf16 v[80:83], v[232:235], v[156:159], v[80:83]
	v_mfma_f32_16x16x32_bf16 v[76:79], v[236:239], v[156:159], v[76:79]
	v_mfma_f32_16x16x32_bf16 v[72:75], v[164:167], v[156:159], v[72:75]
	v_mfma_f32_16x16x32_bf16 v[68:71], v[168:171], v[156:159], v[68:71]
	v_mfma_f32_16x16x32_bf16 v[4:7], v[232:235], v[160:163], v[4:7]
	v_mfma_f32_16x16x32_bf16 v[8:11], v[236:239], v[160:163], v[8:11]
	v_mfma_f32_16x16x32_bf16 v[12:15], v[164:167], v[160:163], v[12:15]
	v_mfma_f32_16x16x32_bf16 v[16:19], v[168:171], v[160:163], v[16:19]
	s_mov_b32 s98, s46
	s_mov_b32 s99, s47
	s_mov_b32 s100, -2
	s_bfe_u32 vcc_lo, s101, 0x10001
	s_lshl_b32 vcc_lo, vcc_lo, 6
	v_add_u32_e32 v194, vcc_lo, v202
	s_branch .LBB0_162
.Lpc_edone_5:
	s_cmp_eq_u32 s100, -2
	s_cbranch_scc0 .Lpc_efin_5
	s_mov_b32 s100, -3
	s_mov_b32 s46, s98
	s_mov_b32 s47, s99
	s_sub_i32 s42, s42, 1
	s_cmp_eq_u32 s42, 2
	s_cselect_b64 s[0:1], -1, 0
	v_mov_b64_e32 v[128:129], v[4:5]
	v_mov_b64_e32 v[130:131], v[6:7]
	v_mov_b64_e32 v[124:125], v[8:9]
	v_mov_b64_e32 v[126:127], v[10:11]
	v_mov_b64_e32 v[120:121], v[12:13]
	v_mov_b64_e32 v[122:123], v[14:15]
	v_mov_b64_e32 v[112:113], v[16:17]
	v_mov_b64_e32 v[114:115], v[18:19]
	v_mov_b64_e32 v[116:117], v[20:21]
	v_mov_b64_e32 v[118:119], v[22:23]
	v_mov_b64_e32 v[108:109], v[24:25]
	v_mov_b64_e32 v[110:111], v[26:27]
	v_mov_b64_e32 v[104:105], v[28:29]
	v_mov_b64_e32 v[106:107], v[30:31]
	v_mov_b64_e32 v[100:101], v[32:33]
	v_mov_b64_e32 v[102:103], v[34:35]
	v_mov_b64_e32 v[96:97], v[36:37]
	v_mov_b64_e32 v[98:99], v[38:39]
	v_mov_b64_e32 v[92:93], v[40:41]
	v_mov_b64_e32 v[94:95], v[42:43]
	v_mov_b64_e32 v[88:89], v[44:45]
	v_mov_b64_e32 v[90:91], v[46:47]
	v_mov_b64_e32 v[84:85], v[48:49]
	v_mov_b64_e32 v[86:87], v[50:51]
	v_mov_b64_e32 v[80:81], v[52:53]
	v_mov_b64_e32 v[82:83], v[54:55]
	v_mov_b64_e32 v[76:77], v[56:57]
	v_mov_b64_e32 v[78:79], v[58:59]
	v_mov_b64_e32 v[72:73], v[60:61]
	v_mov_b64_e32 v[74:75], v[62:63]
	v_mov_b64_e32 v[68:69], v[64:65]
	v_mov_b64_e32 v[70:71], v[66:67]
	v_add_u32_e32 v194, 0x80, v194
	s_branch .LBB0_162
.Lpc_efin_5:
	s_mov_b32 s100, -1
	s_bfe_u32 s98, s101, 0x20002
	s_lshl_b32 s98, s98, 6
	v_add_u32_e32 v194, s98, v202
	s_cmp_eq_u32 s42, 3
	s_cbranch_scc1 .LBB0_165
	s_branch .LBB0_138
.Lpc_prod_5:
.Lpc_ptop_5:
	s_cmp_lt_i32 s53, s52
	s_cbranch_scc1 .Lpc_pcur_5
	s_mov_b32 vcc_lo, 0
	s_cmp_lg_u64 s[22:23], 0
	s_cbranch_scc1 .Lpc_pnext_5
	v_readfirstlane_b32 s26, v150
	v_readfirstlane_b32 s27, v151
	v_readfirstlane_b32 s38, v148
	v_readfirstlane_b32 s39, v149
	s_branch .Lpc_pgo_5
.Lpc_pnext_5:
	v_readfirstlane_b32 s26, v0
	v_readfirstlane_b32 s27, v1
	v_readfirstlane_b32 s38, v138
	v_readfirstlane_b32 s39, v139
	s_branch .Lpc_pgo_5
.Lpc_pcur_5:
	s_mov_b32 vcc_lo, s53
	v_readfirstlane_b32 s26, v150
	v_readfirstlane_b32 s27, v151
	v_readfirstlane_b32 s38, v148
	v_readfirstlane_b32 s39, v149
.Lpc_pgo_5:
	s_nop 0
	s_sub_u32 s26, s26, s98
	s_subb_u32 s27, s27, 0
	s_sub_u32 s38, s38, s99
	s_subb_u32 s39, s39, 0
	s_mov_b32 vcc_hi, vcc_lo
	s_add_u32 m0, s52, -1
	s_and_b32 vcc_hi, vcc_hi, m0
	s_lshl_b32 vcc_hi, vcc_hi, 7
	v_add_u32_e32 v20, vcc_hi, v4
	v_add_u32_e32 v21, vcc_hi, v5
	v_add_u32_e32 v22, vcc_hi, v6
	v_add_u32_e32 v23, vcc_hi, v7
	v_add_u32_e32 v24, vcc_hi, v8
	v_add_u32_e32 v25, vcc_hi, v9
	v_add_u32_e32 v26, vcc_hi, v10
	v_add_u32_e32 v27, vcc_hi, v11
	v_add_u32_e32 v28, vcc_hi, v12
	v_add_u32_e32 v29, vcc_hi, v13
	v_add_u32_e32 v30, vcc_hi, v14
	v_add_u32_e32 v31, vcc_hi, v15
	v_add_u32_e32 v32, vcc_hi, v16
	v_add_u32_e32 v33, vcc_hi, v17
	v_add_u32_e32 v34, vcc_hi, v18
	v_add_u32_e32 v35, vcc_hi, v19
	s_add_u32 vcc_lo, vcc_lo, 1
	s_barrier
	s_add_u32 m0, s100, 0x0
	s_nop 0
	global_load_lds_dwordx4 v20, s[26:27]
	s_add_u32 m0, s100, 0x400
	s_nop 0
	global_load_lds_dwordx4 v21, s[26:27]
	s_add_u32 m0, s100, 0x1000
	s_nop 0
	global_load_lds_dwordx4 v22, s[26:27]
	s_add_u32 m0, s100, 0x1400
	s_nop 0
	global_load_lds_dwordx4 v23, s[26:27]
	s_add_u32 m0, s100, 0x2000
	s_nop 0
	global_load_lds_dwordx4 v24, s[26:27]
	s_add_u32 m0, s100, 0x2400
	s_nop 0
	global_load_lds_dwordx4 v25, s[26:27]
	s_add_u32 m0, s100, 0x3000
	s_nop 0
	global_load_lds_dwordx4 v26, s[26:27]
	s_add_u32 m0, s100, 0x3400
	s_nop 0
	global_load_lds_dwordx4 v27, s[26:27]
	s_waitcnt vmcnt(8)
	s_barrier
	s_add_u32 m0, s100, 0x4000
	s_nop 0
	global_load_lds_dwordx4 v28, s[38:39]
	s_add_u32 m0, s100, 0x4400
	s_nop 0
	global_load_lds_dwordx4 v29, s[38:39]
	s_add_u32 m0, s100, 0x5000
	s_nop 0
	global_load_lds_dwordx4 v30, s[38:39]
	s_add_u32 m0, s100, 0x5400
	s_nop 0
	global_load_lds_dwordx4 v31, s[38:39]
	s_add_u32 m0, s100, 0x6000
	s_nop 0
	global_load_lds_dwordx4 v32, s[38:39]
	s_add_u32 m0, s100, 0x6400
	s_nop 0
	global_load_lds_dwordx4 v33, s[38:39]
	s_add_u32 m0, s100, 0x7000
	s_nop 0
	global_load_lds_dwordx4 v34, s[38:39]
	s_add_u32 m0, s100, 0x7400
	s_nop 0
	global_load_lds_dwordx4 v35, s[38:39]
	s_mov_b32 vcc_hi, vcc_lo
	s_add_u32 m0, s52, -1
	s_and_b32 vcc_hi, vcc_hi, m0
	s_lshl_b32 vcc_hi, vcc_hi, 7
	v_add_u32_e32 v20, vcc_hi, v4
	v_add_u32_e32 v21, vcc_hi, v5
	v_add_u32_e32 v22, vcc_hi, v6
	v_add_u32_e32 v23, vcc_hi, v7
	v_add_u32_e32 v24, vcc_hi, v8
	v_add_u32_e32 v25, vcc_hi, v9
	v_add_u32_e32 v26, vcc_hi, v10
	v_add_u32_e32 v27, vcc_hi, v11
	v_add_u32_e32 v28, vcc_hi, v12
	v_add_u32_e32 v29, vcc_hi, v13
	v_add_u32_e32 v30, vcc_hi, v14
	v_add_u32_e32 v31, vcc_hi, v15
	v_add_u32_e32 v32, vcc_hi, v16
	v_add_u32_e32 v33, vcc_hi, v17
	v_add_u32_e32 v34, vcc_hi, v18
	v_add_u32_e32 v35, vcc_hi, v19
	s_add_u32 vcc_lo, vcc_lo, 1
	s_barrier
	s_add_u32 m0, s100, 0x8000
	s_nop 0
	global_load_lds_dwordx4 v20, s[26:27]
	s_add_u32 m0, s100, 0x8400
	s_nop 0
	global_load_lds_dwordx4 v21, s[26:27]
	s_add_u32 m0, s100, 0x9000
	s_nop 0
	global_load_lds_dwordx4 v22, s[26:27]
	s_add_u32 m0, s100, 0x9400
	s_nop 0
	global_load_lds_dwordx4 v23, s[26:27]
	s_add_u32 m0, s100, 0xa000
	s_nop 0
	global_load_lds_dwordx4 v24, s[26:27]
	s_add_u32 m0, s100, 0xa400
	s_nop 0
	global_load_lds_dwordx4 v25, s[26:27]
	s_add_u32 m0, s100, 0xb000
	s_nop 0
	global_load_lds_dwordx4 v26, s[26:27]
	s_add_u32 m0, s100, 0xb400
	s_nop 0
	global_load_lds_dwordx4 v27, s[26:27]
	s_waitcnt vmcnt(8)
	s_barrier
	s_add_u32 m0, s100, 0xc000
	s_nop 0
	global_load_lds_dwordx4 v28, s[38:39]
	s_add_u32 m0, s100, 0xc400
	s_nop 0
	global_load_lds_dwordx4 v29, s[38:39]
	s_add_u32 m0, s100, 0xd000
	s_nop 0
	global_load_lds_dwordx4 v30, s[38:39]
	s_add_u32 m0, s100, 0xd400
	s_nop 0
	global_load_lds_dwordx4 v31, s[38:39]
	s_add_u32 m0, s100, 0xe000
	s_nop 0
	global_load_lds_dwordx4 v32, s[38:39]
	s_add_u32 m0, s100, 0xe400
	s_nop 0
	global_load_lds_dwordx4 v33, s[38:39]
	s_add_u32 m0, s100, 0xf000
	s_nop 0
	global_load_lds_dwordx4 v34, s[38:39]
	s_add_u32 m0, s100, 0xf400
	s_nop 0
	global_load_lds_dwordx4 v35, s[38:39]
	s_add_u32 s24, s24, 0x100
	s_addc_u32 s25, s25, 0
	s_add_i32 s53, s53, 2
	s_cmp_le_i32 s53, s52
	s_cbranch_scc1 .Lpc_ptop_5
	s_add_i32 s42, s42, 1
	s_mov_b32 s46, s44
	s_mov_b32 s47, s45
	s_cmp_eq_u32 s42, 3
	s_cbranch_scc0 .Lpc_pnd_5
	s_waitcnt vmcnt(0)
	s_branch .LBB0_165
.Lpc_pnd_5:
	s_branch .LBB0_138
.LBB0_161:
	v_mov_b32_e32 v131, 0
	v_mov_b32_e32 v130, v131
	v_mov_b32_e32 v129, v131
	v_mov_b32_e32 v128, v131
	v_mov_b32_e32 v127, v131
	v_mov_b32_e32 v126, v131
	v_mov_b32_e32 v125, v131
	v_mov_b32_e32 v124, v131
	v_mov_b32_e32 v123, v131
	v_mov_b32_e32 v122, v131
	v_mov_b32_e32 v121, v131
	v_mov_b32_e32 v120, v131
	v_mov_b32_e32 v115, v131
	v_mov_b32_e32 v114, v131
	v_mov_b32_e32 v113, v131
	v_mov_b32_e32 v112, v131
	v_mov_b32_e32 v119, v131
	v_mov_b32_e32 v118, v131
	v_mov_b32_e32 v117, v131
	v_mov_b32_e32 v116, v131
	v_mov_b32_e32 v111, v131
	v_mov_b32_e32 v110, v131
	v_mov_b32_e32 v109, v131
	v_mov_b32_e32 v108, v131
	v_mov_b32_e32 v107, v131
	v_mov_b32_e32 v106, v131
	v_mov_b32_e32 v105, v131
	v_mov_b32_e32 v104, v131
	v_mov_b32_e32 v103, v131
	v_mov_b32_e32 v102, v131
	v_mov_b32_e32 v101, v131
	v_mov_b32_e32 v100, v131
	v_mov_b32_e32 v99, v131
	v_mov_b32_e32 v98, v131
	v_mov_b32_e32 v97, v131
	v_mov_b32_e32 v96, v131
	v_mov_b32_e32 v95, v131
	v_mov_b32_e32 v94, v131
	v_mov_b32_e32 v93, v131
	v_mov_b32_e32 v92, v131
	v_mov_b32_e32 v91, v131
	v_mov_b32_e32 v90, v131
	v_mov_b32_e32 v89, v131
	v_mov_b32_e32 v88, v131
	v_mov_b32_e32 v87, v131
	v_mov_b32_e32 v86, v131
	v_mov_b32_e32 v85, v131
	v_mov_b32_e32 v84, v131
	v_mov_b32_e32 v83, v131
	v_mov_b32_e32 v82, v131
	v_mov_b32_e32 v81, v131
	v_mov_b32_e32 v80, v131
	v_mov_b32_e32 v79, v131
	v_mov_b32_e32 v78, v131
	v_mov_b32_e32 v77, v131
	v_mov_b32_e32 v76, v131
	v_mov_b32_e32 v75, v131
	v_mov_b32_e32 v74, v131
	v_mov_b32_e32 v73, v131
	v_mov_b32_e32 v72, v131
	v_mov_b32_e32 v71, v131
	v_mov_b32_e32 v70, v131
	v_mov_b32_e32 v69, v131
	v_mov_b32_e32 v68, v131

.LBB0_166:
	s_andn2_b64 vcc, exec, s[0:1]
	s_cbranch_vccnz .LBB0_191
	v_readlane_b32 s6, v253, 13
	s_waitcnt vmcnt(1)
	v_mov_b32_e32 v68, v194
	s_movk_i32 s0, 0x400
	s_movk_i32 s2, 0x400
	s_movk_i32 s3, 0x400
	v_readlane_b32 s7, v253, 14
	s_load_dword s1, s[6:7], 0x0
	v_readlane_b32 s6, v254, 30
	s_waitcnt lgkmcnt(0)
	s_lshr_b32 s46, s1, 3
	v_readlane_b32 s1, v254, 36
	s_mul_i32 s1, s46, s1
	s_add_i32 s1, s1, s6
	s_cmpk_gt_i32 s1, 0x10ff
	s_cbranch_scc1 .LBB0_191
	s_ashr_i32 s47, s3, 6
	s_lshl_b32 s3, s8, 1
	v_readlane_b32 s8, v252, 37
	v_readlane_b32 s18, v252, 47
	v_readlane_b32 s19, v252, 48
	s_add_u32 s24, s18, s3
	s_addc_u32 s25, s19, 0
	s_ashr_i32 s3, s1, 31
	s_lshr_b32 s3, s3, 24
	v_readlane_b32 s21, v252, 50
	s_add_i32 s3, s1, s3
	v_readlane_b32 s20, v252, 49
	s_ashr_i32 s3, s3, 8
	s_lshl_b32 s21, s1, 7
	v_lshlrev_b32_e32 v0, 3, v68
	v_ashrrev_i32_e32 v3, 3, v68
	s_lshl_b32 s20, s3, 10
	s_and_b32 s21, s21, 0x380
	v_and_b32_e32 v0, 56, v0
	v_lshrrev_b32_e32 v132, 4, v68
	v_xor_b32_e32 v132, v132, v68
	v_and_b32_e32 v132, 7, v132
	v_lshlrev_b32_e32 v0, 3, v132
	v_mov_b32_e32 v1, v2
	s_or_b32 s53, s20, s21
	s_lshl_b32 s3, s3, 12
	s_lshl_b32 s1, s1, 4
	v_mad_i64_i32 v[4:5], s[20:21], s0, v3, v[0:1]
	v_mad_i64_i32 v[0:1], s[20:21], s2, v3, v[0:1]
	s_sub_i32 s1, s1, s3
	s_mul_hi_i32 s21, s53, s0
	s_mul_i32 s20, s53, s0
	s_and_b32 s52, s1, 0xffffff80
	s_ashr_i32 s1, s0, 31
	s_ashr_i32 s3, s2, 31
	s_lshl_b64 s[20:21], s[20:21], 1
	s_add_u32 s20, s76, s20
	s_addc_u32 s21, s77, s21
	v_lshlrev_b64 v[70:71], 1, v[4:5]
	v_lshl_add_u64 v[144:145], s[20:21], 0, v[70:71]
	s_mul_hi_i32 s21, s52, s2
	s_mul_i32 s20, s52, s2
	s_lshl_b64 s[20:21], s[20:21], 1
	s_add_u32 s20, s24, s20
	s_addc_u32 s21, s25, s21
	s_waitcnt vmcnt(0)
	v_lshlrev_b64 v[72:73], 1, v[0:1]
	v_readlane_b32 s22, v252, 51
	v_readlane_b32 s23, v252, 52
	v_lshl_add_u64 v[146:147], s[20:21], 0, v[72:73]
	s_lshl_b64 s[20:21], s[0:1], 6
	v_lshl_add_u64 v[0:1], v[144:145], 0, s[20:21]
	s_lshl_b64 s[22:23], s[2:3], 6
	s_waitcnt vmcnt(0)
	v_lshl_add_u64 v[36:37], v[0:1], 0, s[20:21]
	s_waitcnt vmcnt(0)
	v_lshl_add_u64 v[56:57], v[146:147], 0, s[22:23]
	v_lshl_add_u64 v[40:41], v[36:37], 0, s[20:21]
	s_waitcnt vmcnt(0)
	v_lshl_add_u64 v[60:61], v[56:57], 0, s[22:23]
	s_waitcnt vmcnt(0)
	v_lshl_add_u64 v[64:65], v[60:61], 0, s[22:23]
	s_bfe_u32 s100, s101, 0x20002
	s_lshl_b32 s100, s100, 10
	s_bfe_u32 vcc_lo, s101, 0x80008
	s_add_u32 vcc_lo, vcc_lo, 0
	s_add_u32 vcc_hi, s47, -1
	s_and_b32 vcc_lo, vcc_lo, vcc_hi
	s_lshl_b32 vcc_lo, vcc_lo, 7
	s_mov_b32 vcc_hi, 0
	v_lshl_add_u64 v[20:21], v[144:145], 0, vcc
	s_add_u32 m0, s100, 0x0
	s_nop 0
	global_load_lds_dwordx4 v[20:21], off
	v_lshl_add_u64 v[20:21], v[0:1], 0, vcc
	s_add_u32 m0, s100, 0x1000
	s_nop 0
	global_load_lds_dwordx4 v[20:21], off
	v_lshl_add_u64 v[20:21], v[36:37], 0, vcc
	s_add_u32 m0, s100, 0x2000
	s_nop 0
	global_load_lds_dwordx4 v[20:21], off
	v_lshl_add_u64 v[20:21], v[40:41], 0, vcc
	s_add_u32 m0, s100, 0x3000
	s_nop 0
	global_load_lds_dwordx4 v[20:21], off
	v_lshl_add_u64 v[20:21], v[146:147], 0, vcc
	s_add_u32 m0, s100, 0x4000
	s_nop 0
	global_load_lds_dwordx4 v[20:21], off
	v_lshl_add_u64 v[20:21], v[56:57], 0, vcc
	s_add_u32 m0, s100, 0x5000
	s_nop 0
	global_load_lds_dwordx4 v[20:21], off
	v_lshl_add_u64 v[20:21], v[60:61], 0, vcc
	s_add_u32 m0, s100, 0x6000
	s_nop 0
	global_load_lds_dwordx4 v[20:21], off
	v_lshl_add_u64 v[20:21], v[64:65], 0, vcc
	s_add_u32 m0, s100, 0x7000
	s_nop 0
	global_load_lds_dwordx4 v[20:21], off
	s_bfe_u32 vcc_lo, s101, 0x80008
	s_add_u32 vcc_lo, vcc_lo, 1
	s_add_u32 vcc_hi, s47, -1
	s_and_b32 vcc_lo, vcc_lo, vcc_hi
	s_lshl_b32 vcc_lo, vcc_lo, 7
	s_mov_b32 vcc_hi, 0
	v_lshl_add_u64 v[20:21], v[144:145], 0, vcc
	s_add_u32 m0, s100, 0x8000
	s_nop 0
	global_load_lds_dwordx4 v[20:21], off
	v_lshl_add_u64 v[20:21], v[0:1], 0, vcc
	s_add_u32 m0, s100, 0x9000
	s_nop 0
	global_load_lds_dwordx4 v[20:21], off
	v_lshl_add_u64 v[20:21], v[36:37], 0, vcc
	s_add_u32 m0, s100, 0xa000
	s_nop 0
	global_load_lds_dwordx4 v[20:21], off
	v_lshl_add_u64 v[20:21], v[40:41], 0, vcc
	s_add_u32 m0, s100, 0xb000
	s_nop 0
	global_load_lds_dwordx4 v[20:21], off
	v_lshl_add_u64 v[20:21], v[146:147], 0, vcc
	s_add_u32 m0, s100, 0xc000
	s_nop 0
	global_load_lds_dwordx4 v[20:21], off
	v_lshl_add_u64 v[20:21], v[56:57], 0, vcc
	s_add_u32 m0, s100, 0xd000
	s_nop 0
	global_load_lds_dwordx4 v[20:21], off
	v_lshl_add_u64 v[20:21], v[60:61], 0, vcc
	s_add_u32 m0, s100, 0xe000
	s_nop 0
	global_load_lds_dwordx4 v[20:21], off
	v_lshl_add_u64 v[20:21], v[64:65], 0, vcc
	s_add_u32 m0, s100, 0xf000
	s_nop 0
	global_load_lds_dwordx4 v[20:21], off
	v_lshrrev_b32_e32 v1, 1, v3
	v_xor_b32_e32 v1, v1, v68
	v_lshlrev_b32_e32 v0, 7, v3
	v_lshlrev_b32_e32 v1, 4, v1
	s_movk_i32 s1, 0x70
	v_lshrrev_b32_e32 v69, 4, v68
	v_bfe_u32 v74, v68, 4, 2
	v_and_or_b32 v3, v1, s1, v0
	v_lshl_add_u64 v[0:1], s[76:77], 0, v[70:71]
	v_bfe_u32 v70, v68, 1, 3
	v_bitop3_b32 v69, v69, v70, 3 bitop3:0x6c
	v_lshlrev_b32_e32 v71, 6, v68
	v_lshlrev_b32_e32 v68, 7, v68
	v_bitop3_b32 v70, v74, v70, 4 bitop3:0x36
	v_lshl_add_u64 v[138:139], s[24:25], 0, v[72:73]
	v_lshlrev_b32_e32 v69, 4, v69
	v_and_b32_e32 v71, 0xffffe000, v71
	v_and_b32_e32 v72, 0x780, v68
	v_and_b32_e32 v68, 0x2000, v68
	v_lshlrev_b32_e32 v70, 4, v70
	s_cmp_gt_i32 s47, 0
	v_or_b32_e32 v73, v69, v71
	v_or_b32_e32 v69, v69, v68
	v_or_b32_e32 v71, v70, v71
	v_or_b32_e32 v68, v70, v68
	s_mov_b32 s1, 0
	s_cselect_b64 s[24:25], -1, 0
	v_add_u32_e32 v137, v73, v72
	v_add_u32_e32 v188, v69, v72
	v_add_u32_e32 v189, v71, v72
	v_add_u32_e32 v190, v68, v72
	s_mov_b32 s3, 0
	s_mov_b32 s49, 0
	v_readlane_b32 s9, v252, 38
	v_readlane_b32 s10, v252, 39
	v_readlane_b32 s11, v252, 40
	v_readlane_b32 s12, v252, 41
	v_readlane_b32 s13, v252, 42
	v_readlane_b32 s14, v252, 43
	v_readlane_b32 s15, v252, 44
	v_readlane_b32 s16, v252, 45
	v_readlane_b32 s17, v252, 46
	s_bfe_u32 vcc_lo, s101, 0x10001
	v_and_b32_e32 v20, 15, v194
	v_lshrrev_b32_e32 v21, 1, v20
	v_bfe_u32 v22, v194, 4, 2
	v_xor_b32_e32 v21, v21, v22
	v_lshlrev_b32_e32 v21, 4, v21
	v_lshl_or_b32 v250, v20, 7, v21
	v_mov_b32_e32 v22, vcc_lo
	v_lshl_or_b32 v22, v22, 13, v250
	v_or_b32_e32 v251, 0x4000, v22
	v_and_b32_e32 v20, 63, v194
	v_mov_b32_e32 v21, vcc_lo
	v_lshlrev_b32_e32 v21, 4, v21
	v_lshrrev_b32_e32 v22, 3, v20
	v_add_u32_e32 v21, v21, v22
	v_lshrrev_b32_e32 v22, 4, v20
	v_and_b32_e32 v23, 7, v20
	v_xor_b32_e32 v24, v23, v22
	v_lshlrev_b32_e32 v24, 4, v24
	v_or_b32_e32 v22, 4, v22
	v_xor_b32_e32 v25, v23, v22
	v_lshlrev_b32_e32 v25, 4, v25
	s_movk_i32 s98, 0x800
	s_movk_i32 s99, 0x800
	v_add_u32_e32 v26, 0, v21
	v_mad_u32_u24 v4, v26, s98, v24
	v_add_u32_e32 v26, 8, v21
	v_mad_u32_u24 v5, v26, s98, v25
	v_add_u32_e32 v26, 32, v21
	v_mad_u32_u24 v6, v26, s98, v24
	v_add_u32_e32 v26, 40, v21
	v_mad_u32_u24 v7, v26, s98, v25
	v_add_u32_e32 v26, 64, v21
	v_mad_u32_u24 v8, v26, s98, v24
	v_add_u32_e32 v26, 72, v21
	v_mad_u32_u24 v9, v26, s98, v25
	v_add_u32_e32 v26, 96, v21
	v_mad_u32_u24 v10, v26, s98, v24
	v_add_u32_e32 v26, 104, v21
	v_mad_u32_u24 v11, v26, s98, v25
	v_add_u32_e32 v26, 0, v21
	v_mad_u32_u24 v12, v26, s99, v24
	v_add_u32_e32 v26, 8, v21
	v_mad_u32_u24 v13, v26, s99, v25
	v_add_u32_e32 v26, 32, v21
	v_mad_u32_u24 v14, v26, s99, v24
	v_add_u32_e32 v26, 40, v21
	v_mad_u32_u24 v15, v26, s99, v25
	v_add_u32_e32 v26, 64, v21
	v_mad_u32_u24 v16, v26, s99, v24
	v_add_u32_e32 v26, 72, v21
	v_mad_u32_u24 v17, v26, s99, v25
	v_add_u32_e32 v26, 96, v21
	v_mad_u32_u24 v18, v26, s99, v24
	v_add_u32_e32 v26, 104, v21
	v_mad_u32_u24 v19, v26, s99, v25
	s_bfe_u32 vcc_hi, s101, 0x20002
	s_lshl_b32 vcc_hi, vcc_hi, 3
	s_mul_i32 s98, s98, vcc_hi
	s_mul_i32 s99, s99, vcc_hi
	s_lshl_b32 vcc_hi, vcc_hi, 3
	s_and_b32 vcc_hi, vcc_hi, 0x70
	s_add_u32 s98, s98, vcc_hi
	s_add_u32 s99, s99, vcc_hi
	s_lshl_b32 s100, vcc_lo, 11
	s_bitcmp1_b32 s101, 0
	s_cselect_b32 s100, -1, s100
	s_waitcnt vmcnt(0) lgkmcnt(0)
	s_barrier
	s_branch .LBB0_171

.LBB0_245:
	s_andn2_b64 vcc, exec, s[2:3]
	s_cbranch_vccnz .LBB0_276
	s_waitcnt vmcnt(0)
	v_mov_b32_e32 v74, v194
	s_movk_i32 s22, 0x400
	s_movk_i32 s24, 0x400
	s_movk_i32 s2, 0x400
	v_lshlrev_b32_e32 v0, 3, v74
	v_ashrrev_i32_e32 v3, 3, v74
	v_and_b32_e32 v0, 56, v0
	v_lshrrev_b32_e32 v132, 4, v74
	v_xor_b32_e32 v132, v132, v74
	v_and_b32_e32 v132, 7, v132
	v_lshlrev_b32_e32 v0, 3, v132
	v_mov_b32_e32 v1, v2
	s_ashr_i32 s40, s2, 6
	s_ashr_i32 s41, s2, 9
	v_mad_i64_i32 v[4:5], s[2:3], s22, v3, v[0:1]
	v_mad_i64_i32 v[6:7], s[2:3], s24, v3, v[0:1]
	v_readlane_b32 s47, v254, 35
	s_mul_hi_i32 s3, s22, s47
	s_mul_i32 s2, s22, s47
	s_ashr_i32 s23, s22, 31
	s_ashr_i32 s25, s24, 31
	s_lshl_b64 s[2:3], s[2:3], 1
	s_add_u32 s2, s76, s2
	s_addc_u32 s3, s77, s3
	v_lshlrev_b64 v[68:69], 1, v[4:5]
	v_readlane_b32 s46, v254, 33
	v_lshl_add_u64 v[0:1], s[2:3], 0, v[68:69]
	s_mul_hi_i32 s3, s24, s46
	s_mul_i32 s2, s24, s46
	s_lshl_b64 s[26:27], s[2:3], 1
	s_add_u32 s2, s0, s26
	s_addc_u32 s3, s1, s27
	v_lshlrev_b64 v[70:71], 1, v[6:7]
	v_lshl_add_u64 v[138:139], s[2:3], 0, v[70:71]
	s_lshl_b64 s[2:3], s[22:23], 6
	s_waitcnt vmcnt(0)
	v_lshl_add_u64 v[28:29], v[0:1], 0, s[2:3]
	s_lshl_b64 s[20:21], s[24:25], 6
	s_waitcnt vmcnt(0)
	v_lshl_add_u64 v[36:37], v[28:29], 0, s[2:3]
	s_waitcnt vmcnt(0)
	v_lshl_add_u64 v[56:57], v[138:139], 0, s[20:21]
	v_lshl_add_u64 v[40:41], v[36:37], 0, s[2:3]
	s_waitcnt vmcnt(0)
	v_lshl_add_u64 v[60:61], v[56:57], 0, s[20:21]
	s_waitcnt vmcnt(0)
	v_lshl_add_u64 v[64:65], v[60:61], 0, s[20:21]
	s_bfe_u32 s100, s101, 0x20002
	s_lshl_b32 s100, s100, 10
	s_add_u32 m0, s100, 0x0
	s_nop 0
	global_load_lds_dwordx4 v[0:1], off
	s_add_u32 m0, s100, 0x1000
	s_nop 0
	global_load_lds_dwordx4 v[28:29], off
	s_add_u32 m0, s100, 0x2000
	s_nop 0
	global_load_lds_dwordx4 v[36:37], off
	s_add_u32 m0, s100, 0x3000
	s_nop 0
	global_load_lds_dwordx4 v[40:41], off
	s_add_u32 m0, s100, 0x4000
	s_nop 0
	global_load_lds_dwordx4 v[138:139], off
	s_add_u32 m0, s100, 0x5000
	s_nop 0
	global_load_lds_dwordx4 v[56:57], off
	s_add_u32 m0, s100, 0x6000
	s_nop 0
	global_load_lds_dwordx4 v[60:61], off
	s_add_u32 m0, s100, 0x7000
	s_nop 0
	global_load_lds_dwordx4 v[64:65], off
	s_add_u32 m0, s100, 0x7f80
	s_nop 0
	global_load_lds_dwordx4 v[0:1], off offset:128
	s_add_u32 m0, s100, 0x8f80
	s_nop 0
	global_load_lds_dwordx4 v[28:29], off offset:128
	s_add_u32 m0, s100, 0x9f80
	s_nop 0
	global_load_lds_dwordx4 v[36:37], off offset:128
	s_add_u32 m0, s100, 0xaf80
	s_nop 0
	global_load_lds_dwordx4 v[40:41], off offset:128
	s_add_u32 m0, s100, 0xbf80
	s_nop 0
	global_load_lds_dwordx4 v[138:139], off offset:128
	s_add_u32 m0, s100, 0xcf80
	s_nop 0
	global_load_lds_dwordx4 v[56:57], off offset:128
	s_add_u32 m0, s100, 0xdf80
	s_nop 0
	global_load_lds_dwordx4 v[60:61], off offset:128
	s_add_u32 m0, s100, 0xef80
	s_nop 0
	global_load_lds_dwordx4 v[64:65], off offset:128
	v_lshlrev_b32_e32 v72, 7, v3
	v_lshrrev_b32_e32 v3, 1, v3
	v_xor_b32_e32 v3, v3, v74
	v_lshl_add_u64 v[70:71], s[0:1], 0, v[70:71]
	v_readlane_b32 s0, v254, 34
	v_lshlrev_b32_e32 v3, 4, v3
	s_movk_i32 s6, 0x70
	v_lshl_add_u64 v[68:69], s[76:77], 0, v[68:69]
	s_mul_hi_i32 s1, s22, s0
	s_mul_i32 s0, s22, s0
	v_and_or_b32 v3, v3, s6, v72
	v_lshl_add_u64 v[72:73], s[0:1], 1, v[68:69]
	v_readlane_b32 s0, v254, 31
	s_mul_hi_i32 s1, s41, s0
	s_mul_i32 s0, s41, s0
	v_readlane_b32 s6, v254, 32
	s_lshl_b64 s[0:1], s[0:1], 1
	s_mul_hi_i32 s25, s24, s6
	s_mul_i32 s24, s24, s6
	v_lshl_add_u64 v[140:141], v[72:73], 0, s[0:1]
	v_lshl_add_u64 v[72:73], s[24:25], 1, v[70:71]
	v_lshl_add_u64 v[142:143], v[72:73], 0, s[0:1]
	s_mul_hi_i32 s1, s22, s54
	s_mul_i32 s0, s22, s54
	v_lshrrev_b32_e32 v75, 4, v74
	v_bfe_u32 v76, v74, 4, 2
	v_lshl_add_u64 v[144:145], s[0:1], 1, v[68:69]
	v_bfe_u32 v68, v74, 1, 3
	v_lshl_add_u64 v[146:147], v[70:71], 0, s[26:27]
	v_bitop3_b32 v69, v75, v68, 3 bitop3:0x6c
	v_lshlrev_b32_e32 v70, 6, v74
	v_lshlrev_b32_e32 v71, 7, v74
	v_bitop3_b32 v68, v76, v68, 4 bitop3:0x36
	v_lshlrev_b32_e32 v69, 4, v69
	v_and_b32_e32 v70, 0xffffe000, v70
	v_and_b32_e32 v72, 0x780, v71
	v_and_b32_e32 v71, 0x2000, v71
	v_lshlrev_b32_e32 v68, 4, v68
	v_or_b32_e32 v73, v69, v70
	v_or_b32_e32 v69, v69, v71
	v_or_b32_e32 v70, v68, v70
	v_or_b32_e32 v68, v68, v71
	s_mov_b32 s42, 0
	v_add_u32_e32 v137, v73, v72
	v_add_u32_e32 v192, v69, v72
	v_add_u32_e32 v193, v70, v72
	v_add_u32_e32 v214, v68, v72
	s_mov_b32 s43, s40
	s_mov_b32 s44, 0
	s_mov_b32 s45, 0
	s_bfe_u32 vcc_lo, s101, 0x10001
	v_and_b32_e32 v20, 15, v194
	v_lshrrev_b32_e32 v21, 1, v20
	v_bfe_u32 v22, v194, 4, 2
	v_xor_b32_e32 v21, v21, v22
	v_lshlrev_b32_e32 v21, 4, v21
	v_lshl_or_b32 v250, v20, 7, v21
	v_mov_b32_e32 v22, vcc_lo
	v_lshl_or_b32 v22, v22, 13, v250
	v_or_b32_e32 v251, 0x4000, v22
	v_and_b32_e32 v20, 63, v194
	v_mov_b32_e32 v21, vcc_lo
	v_lshlrev_b32_e32 v21, 4, v21
	v_lshrrev_b32_e32 v22, 3, v20
	v_add_u32_e32 v21, v21, v22
	v_lshrrev_b32_e32 v22, 4, v20
	v_and_b32_e32 v23, 7, v20
	v_xor_b32_e32 v24, v23, v22
	v_lshlrev_b32_e32 v24, 4, v24
	v_or_b32_e32 v22, 4, v22
	v_xor_b32_e32 v25, v23, v22
	v_lshlrev_b32_e32 v25, 4, v25
	s_movk_i32 s98, 0x800
	s_movk_i32 s99, 0x800
	v_add_u32_e32 v26, 0, v21
	v_mad_u32_u24 v4, v26, s98, v24
	v_add_u32_e32 v26, 8, v21
	v_mad_u32_u24 v5, v26, s98, v25
	v_add_u32_e32 v26, 32, v21
	v_mad_u32_u24 v6, v26, s98, v24
	v_add_u32_e32 v26, 40, v21
	v_mad_u32_u24 v7, v26, s98, v25
	v_add_u32_e32 v26, 64, v21
	v_mad_u32_u24 v8, v26, s98, v24
	v_add_u32_e32 v26, 72, v21
	v_mad_u32_u24 v9, v26, s98, v25
	v_add_u32_e32 v26, 96, v21
	v_mad_u32_u24 v10, v26, s98, v24
	v_add_u32_e32 v26, 104, v21
	v_mad_u32_u24 v11, v26, s98, v25
	v_add_u32_e32 v26, 0, v21
	v_mad_u32_u24 v12, v26, s99, v24
	v_add_u32_e32 v26, 8, v21
	v_mad_u32_u24 v13, v26, s99, v25
	v_add_u32_e32 v26, 32, v21
	v_mad_u32_u24 v14, v26, s99, v24
	v_add_u32_e32 v26, 40, v21
	v_mad_u32_u24 v15, v26, s99, v25
	v_add_u32_e32 v26, 64, v21
	v_mad_u32_u24 v16, v26, s99, v24
	v_add_u32_e32 v26, 72, v21
	v_mad_u32_u24 v17, v26, s99, v25
	v_add_u32_e32 v26, 96, v21
	v_mad_u32_u24 v18, v26, s99, v24
	v_add_u32_e32 v26, 104, v21
	v_mad_u32_u24 v19, v26, s99, v25
	s_bfe_u32 vcc_hi, s101, 0x20002
	s_lshl_b32 vcc_hi, vcc_hi, 3
	s_mul_i32 s98, s98, vcc_hi
	s_mul_i32 s99, s99, vcc_hi
	s_lshl_b32 vcc_hi, vcc_hi, 3
	s_and_b32 vcc_hi, vcc_hi, 0x70
	s_add_u32 s98, s98, vcc_hi
	s_add_u32 s99, s99, vcc_hi
	s_lshl_b32 s100, vcc_lo, 11
	s_bitcmp1_b32 s101, 0
	s_cselect_b32 s100, -1, s100
	s_waitcnt vmcnt(0) lgkmcnt(0)
	s_barrier
	s_branch .LBB0_249

.LBB0_255:
	s_cmp_lg_u32 s42, 2
	s_cselect_b64 s[22:23], -1, 0
	s_cmp_eq_u32 s42, 2
	s_cselect_b64 s[0:1], -1, 0
	s_cmp_lt_i32 s49, 1
	s_cbranch_scc1 .LBB0_272
	v_lshl_add_u64 v[152:153], v[0:1], 0, s[2:3]
	v_lshl_add_u64 v[158:159], v[138:139], 0, s[20:21]
	v_lshl_add_u64 v[164:165], v[150:151], 0, s[2:3]
	v_lshl_add_u64 v[170:171], v[148:149], 0, s[20:21]
	v_lshl_add_u64 v[154:155], v[152:153], 0, s[2:3]
	v_lshl_add_u64 v[160:161], v[158:159], 0, s[20:21]
	v_lshl_add_u64 v[166:167], v[164:165], 0, s[2:3]
	v_lshl_add_u64 v[172:173], v[170:171], 0, s[20:21]
	v_mov_b32_e32 v68, 0
	v_lshl_add_u64 v[156:157], v[154:155], 0, s[2:3]
	v_lshl_add_u64 v[162:163], v[160:161], 0, s[20:21]
	v_lshl_add_u64 v[168:169], v[166:167], 0, s[2:3]
	v_lshl_add_u64 v[174:175], v[172:173], 0, s[20:21]
	s_mov_b64 s[24:25], 0x100
	s_mov_b32 s52, 2
	v_mov_b32_e32 v69, v68
	v_mov_b32_e32 v70, v68
	v_mov_b32_e32 v71, v68
	v_mov_b32_e32 v72, v68
	v_mov_b32_e32 v73, v68
	v_mov_b32_e32 v74, v68
	v_mov_b32_e32 v75, v68
	v_mov_b32_e32 v76, v68
	v_mov_b32_e32 v77, v68
	v_mov_b32_e32 v78, v68
	v_mov_b32_e32 v79, v68
	v_mov_b32_e32 v80, v68
	v_mov_b32_e32 v81, v68
	v_mov_b32_e32 v82, v68
	v_mov_b32_e32 v83, v68
	v_mov_b32_e32 v84, v68
	v_mov_b32_e32 v85, v68
	v_mov_b32_e32 v86, v68
	v_mov_b32_e32 v87, v68
	v_mov_b32_e32 v88, v68
	v_mov_b32_e32 v89, v68
	v_mov_b32_e32 v90, v68
	v_mov_b32_e32 v91, v68
	v_mov_b32_e32 v92, v68
	v_mov_b32_e32 v93, v68
	v_mov_b32_e32 v94, v68
	v_mov_b32_e32 v95, v68
	v_mov_b32_e32 v96, v68
	v_mov_b32_e32 v97, v68
	v_mov_b32_e32 v98, v68
	v_mov_b32_e32 v99, v68
	v_mov_b32_e32 v100, v68
	v_mov_b32_e32 v101, v68
	v_mov_b32_e32 v102, v68
	v_mov_b32_e32 v103, v68
	v_mov_b32_e32 v104, v68
	v_mov_b32_e32 v105, v68
	v_mov_b32_e32 v106, v68
	v_mov_b32_e32 v107, v68
	v_mov_b32_e32 v108, v68
	v_mov_b32_e32 v109, v68
	v_mov_b32_e32 v110, v68
	v_mov_b32_e32 v111, v68
	v_mov_b32_e32 v116, v68
	v_mov_b32_e32 v117, v68
	v_mov_b32_e32 v118, v68
	v_mov_b32_e32 v119, v68
	v_mov_b32_e32 v112, v68
	v_mov_b32_e32 v113, v68
	v_mov_b32_e32 v114, v68
	v_mov_b32_e32 v115, v68
	v_mov_b32_e32 v120, v68
	v_mov_b32_e32 v121, v68
	v_mov_b32_e32 v122, v68
	v_mov_b32_e32 v123, v68
	v_mov_b32_e32 v124, v68
	v_mov_b32_e32 v125, v68
	v_mov_b32_e32 v126, v68
	v_mov_b32_e32 v127, v68
	v_mov_b32_e32 v128, v68
	v_mov_b32_e32 v129, v68
	v_mov_b32_e32 v130, v68
	v_mov_b32_e32 v131, v68
	s_branch .LBB0_258

.Lpc_ck1_6:
	ds_read_b128 v[224:227], v251 offset:32768
	ds_read_b128 v[228:231], v251 offset:34816
	ds_read_b128 v[240:243], v251 offset:36864
	ds_read_b128 v[244:247], v251 offset:38912
	ds_read_b128 v[176:179], v250 offset:32768
	ds_read_b128 v[180:183], v250 offset:34816
	ds_read_b128 v[184:187], v250 offset:36864
	ds_read_b128 v[188:191], v250 offset:38912
	ds_read_b128 v[132:135], v250 offset:40960
	ds_read_b128 v[208:211], v250 offset:43008
	v_mfma_f32_16x16x32_bf16 v[80:83], v[232:235], v[156:159], v[80:83]
	v_mfma_f32_16x16x32_bf16 v[76:79], v[236:239], v[156:159], v[76:79]
	v_mfma_f32_16x16x32_bf16 v[72:75], v[164:167], v[156:159], v[72:75]
	v_mfma_f32_16x16x32_bf16 v[68:71], v[168:171], v[156:159], v[68:71]
	v_mfma_f32_16x16x32_bf16 v[4:7], v[232:235], v[160:163], v[4:7]
	v_mfma_f32_16x16x32_bf16 v[8:11], v[236:239], v[160:163], v[8:11]
	v_mfma_f32_16x16x32_bf16 v[12:15], v[164:167], v[160:163], v[12:15]
	v_mfma_f32_16x16x32_bf16 v[16:19], v[168:171], v[160:163], v[16:19]
	ds_read_b128 v[216:219], v250 offset:45056
	ds_read_b128 v[220:223], v250 offset:47104
	ds_read_b128 v[232:235], v137 offset:32768
	ds_read_b128 v[236:239], v137 offset:34816
	ds_read_b128 v[164:167], v137 offset:36864
	s_waitcnt lgkmcnt(14)
	ds_read_b128 v[168:171], v137 offset:38912
	s_waitcnt lgkmcnt(14)
	ds_read_b128 v[148:151], v192 offset:32768
	s_waitcnt lgkmcnt(14)
	ds_read_b128 v[172:175], v192 offset:34816
	s_waitcnt lgkmcnt(14)
	ds_read_b128 v[152:155], v192 offset:36864
	s_waitcnt lgkmcnt(14)
	ds_read_b128 v[156:159], v192 offset:38912
	s_waitcnt lgkmcnt(14)
	ds_read_b128 v[160:163], v192 offset:40960
	v_mfma_f32_16x16x32_bf16 v[128:131], v[224:227], v[176:179], v[128:131]
	v_mfma_f32_16x16x32_bf16 v[124:127], v[228:231], v[176:179], v[124:127]
	v_mfma_f32_16x16x32_bf16 v[120:123], v[240:243], v[176:179], v[120:123]
	v_mfma_f32_16x16x32_bf16 v[112:115], v[244:247], v[176:179], v[112:115]
	s_waitcnt lgkmcnt(14)
	ds_read_b128 v[176:179], v192 offset:43008
	v_mfma_f32_16x16x32_bf16 v[116:119], v[224:227], v[180:183], v[116:119]
	v_mfma_f32_16x16x32_bf16 v[108:111], v[228:231], v[180:183], v[108:111]
	v_mfma_f32_16x16x32_bf16 v[104:107], v[240:243], v[180:183], v[104:107]
	v_mfma_f32_16x16x32_bf16 v[100:103], v[244:247], v[180:183], v[100:103]
	s_waitcnt lgkmcnt(14)
	ds_read_b128 v[180:183], v192 offset:45056
	v_mfma_f32_16x16x32_bf16 v[96:99], v[224:227], v[184:187], v[96:99]
	v_mfma_f32_16x16x32_bf16 v[92:95], v[228:231], v[184:187], v[92:95]
	v_mfma_f32_16x16x32_bf16 v[88:91], v[240:243], v[184:187], v[88:91]
	v_mfma_f32_16x16x32_bf16 v[84:87], v[244:247], v[184:187], v[84:87]
	s_waitcnt lgkmcnt(14)
	ds_read_b128 v[184:187], v192 offset:47104
	v_mfma_f32_16x16x32_bf16 v[80:83], v[224:227], v[188:191], v[80:83]
	v_mfma_f32_16x16x32_bf16 v[76:79], v[228:231], v[188:191], v[76:79]
	v_mfma_f32_16x16x32_bf16 v[72:75], v[240:243], v[188:191], v[72:75]
	v_mfma_f32_16x16x32_bf16 v[68:71], v[244:247], v[188:191], v[68:71]
	v_mfma_f32_16x16x32_bf16 v[4:7], v[224:227], v[132:135], v[4:7]
	v_mfma_f32_16x16x32_bf16 v[8:11], v[228:231], v[132:135], v[8:11]
	v_mfma_f32_16x16x32_bf16 v[12:15], v[240:243], v[132:135], v[12:15]
	v_mfma_f32_16x16x32_bf16 v[16:19], v[244:247], v[132:135], v[16:19]
	s_waitcnt lgkmcnt(0)
	s_barrier
	v_mfma_f32_16x16x32_bf16 v[20:23], v[224:227], v[208:211], v[20:23]
	v_mfma_f32_16x16x32_bf16 v[24:27], v[228:231], v[208:211], v[24:27]
	v_mfma_f32_16x16x32_bf16 v[28:31], v[240:243], v[208:211], v[28:31]
	v_mfma_f32_16x16x32_bf16 v[32:35], v[244:247], v[208:211], v[32:35]
	v_mfma_f32_16x16x32_bf16 v[36:39], v[224:227], v[216:219], v[36:39]
	v_mfma_f32_16x16x32_bf16 v[40:43], v[228:231], v[216:219], v[40:43]
	v_mfma_f32_16x16x32_bf16 v[44:47], v[240:243], v[216:219], v[44:47]
	v_mfma_f32_16x16x32_bf16 v[48:51], v[244:247], v[216:219], v[48:51]
	v_mfma_f32_16x16x32_bf16 v[52:55], v[224:227], v[220:223], v[52:55]
	v_mfma_f32_16x16x32_bf16 v[56:59], v[228:231], v[220:223], v[56:59]
	v_mfma_f32_16x16x32_bf16 v[60:63], v[240:243], v[220:223], v[60:63]
	v_mfma_f32_16x16x32_bf16 v[64:67], v[244:247], v[220:223], v[64:67]
	v_mfma_f32_16x16x32_bf16 v[128:131], v[232:235], v[148:151], v[128:131]
	v_mfma_f32_16x16x32_bf16 v[124:127], v[236:239], v[148:151], v[124:127]
	v_mfma_f32_16x16x32_bf16 v[120:123], v[164:167], v[148:151], v[120:123]
	v_mfma_f32_16x16x32_bf16 v[112:115], v[168:171], v[148:151], v[112:115]
	v_mfma_f32_16x16x32_bf16 v[116:119], v[232:235], v[172:175], v[116:119]
	v_mfma_f32_16x16x32_bf16 v[108:111], v[236:239], v[172:175], v[108:111]
	v_mfma_f32_16x16x32_bf16 v[104:107], v[164:167], v[172:175], v[104:107]
	v_mfma_f32_16x16x32_bf16 v[100:103], v[168:171], v[172:175], v[100:103]
	v_mfma_f32_16x16x32_bf16 v[96:99], v[232:235], v[152:155], v[96:99]
	v_mfma_f32_16x16x32_bf16 v[92:95], v[236:239], v[152:155], v[92:95]
	v_mfma_f32_16x16x32_bf16 v[88:91], v[164:167], v[152:155], v[88:91]
	v_mfma_f32_16x16x32_bf16 v[84:87], v[168:171], v[152:155], v[84:87]
	v_mfma_f32_16x16x32_bf16 v[20:23], v[232:235], v[176:179], v[20:23]
	v_mfma_f32_16x16x32_bf16 v[24:27], v[236:239], v[176:179], v[24:27]
	v_mfma_f32_16x16x32_bf16 v[28:31], v[164:167], v[176:179], v[28:31]
	v_mfma_f32_16x16x32_bf16 v[32:35], v[168:171], v[176:179], v[32:35]
	v_mfma_f32_16x16x32_bf16 v[36:39], v[232:235], v[180:183], v[36:39]
	v_mfma_f32_16x16x32_bf16 v[40:43], v[236:239], v[180:183], v[40:43]
	v_mfma_f32_16x16x32_bf16 v[44:47], v[164:167], v[180:183], v[44:47]
	v_mfma_f32_16x16x32_bf16 v[48:51], v[168:171], v[180:183], v[48:51]
	v_mfma_f32_16x16x32_bf16 v[52:55], v[232:235], v[184:187], v[52:55]
	v_mfma_f32_16x16x32_bf16 v[56:59], v[236:239], v[184:187], v[56:59]
	v_mfma_f32_16x16x32_bf16 v[60:63], v[164:167], v[184:187], v[60:63]
	v_mfma_f32_16x16x32_bf16 v[64:67], v[168:171], v[184:187], v[64:67]
	s_barrier
	s_add_i32 s52, s52, 2
	s_cmp_le_i32 s52, s49
	s_cbranch_scc1 .Lpc_ctop_6
	v_mfma_f32_16x16x32_bf16 v[80:83], v[232:235], v[156:159], v[80:83]
	v_mfma_f32_16x16x32_bf16 v[76:79], v[236:239], v[156:159], v[76:79]
	v_mfma_f32_16x16x32_bf16 v[72:75], v[164:167], v[156:159], v[72:75]
	v_mfma_f32_16x16x32_bf16 v[68:71], v[168:171], v[156:159], v[68:71]
	v_mfma_f32_16x16x32_bf16 v[4:7], v[232:235], v[160:163], v[4:7]
	v_mfma_f32_16x16x32_bf16 v[8:11], v[236:239], v[160:163], v[8:11]
	v_mfma_f32_16x16x32_bf16 v[12:15], v[164:167], v[160:163], v[12:15]
	v_mfma_f32_16x16x32_bf16 v[16:19], v[168:171], v[160:163], v[16:19]
	s_mov_b32 s98, s46
	s_mov_b32 s99, s47
	s_mov_b32 s100, -2
	s_bfe_u32 vcc_lo, s101, 0x10001
	s_lshl_b32 vcc_lo, vcc_lo, 6
	v_add_u32_e32 v194, vcc_lo, v202
	s_branch .LBB0_273

.Lpc_prod_6:
.Lpc_ptop_6:
	s_cmp_lt_i32 s52, s49
	s_cbranch_scc1 .Lpc_pcur_6
	s_mov_b32 vcc_lo, 0
	s_cmp_lg_u64 s[22:23], 0
	s_cbranch_scc1 .Lpc_pnext_6
	v_readfirstlane_b32 s26, v150
	v_readfirstlane_b32 s27, v151
	v_readfirstlane_b32 s38, v148
	v_readfirstlane_b32 s39, v149
	s_branch .Lpc_pgo_6

.Lpc_pcur_6:
	s_mov_b32 vcc_lo, s52
	v_readfirstlane_b32 s26, v150
	v_readfirstlane_b32 s27, v151
	v_readfirstlane_b32 s38, v148
	v_readfirstlane_b32 s39, v149
.Lpc_pgo_6:
	s_nop 0
	s_sub_u32 s26, s26, s98
	s_subb_u32 s27, s27, 0
	s_sub_u32 s38, s38, s99
	s_subb_u32 s39, s39, 0
	s_mov_b32 vcc_hi, vcc_lo
	s_add_u32 m0, s49, -1
	s_and_b32 vcc_hi, vcc_hi, m0
	s_lshl_b32 vcc_hi, vcc_hi, 7
	v_add_u32_e32 v20, vcc_hi, v4
	v_add_u32_e32 v21, vcc_hi, v5
	v_add_u32_e32 v22, vcc_hi, v6
	v_add_u32_e32 v23, vcc_hi, v7
	v_add_u32_e32 v24, vcc_hi, v8
	v_add_u32_e32 v25, vcc_hi, v9
	v_add_u32_e32 v26, vcc_hi, v10
	v_add_u32_e32 v27, vcc_hi, v11
	v_add_u32_e32 v28, vcc_hi, v12
	v_add_u32_e32 v29, vcc_hi, v13
	v_add_u32_e32 v30, vcc_hi, v14
	v_add_u32_e32 v31, vcc_hi, v15
	v_add_u32_e32 v32, vcc_hi, v16
	v_add_u32_e32 v33, vcc_hi, v17
	v_add_u32_e32 v34, vcc_hi, v18
	v_add_u32_e32 v35, vcc_hi, v19
	s_add_u32 vcc_lo, vcc_lo, 1
	s_barrier
	s_add_u32 m0, s100, 0x0
	s_nop 0
	global_load_lds_dwordx4 v20, s[26:27]
	s_add_u32 m0, s100, 0x400
	s_nop 0
	global_load_lds_dwordx4 v21, s[26:27]
	s_add_u32 m0, s100, 0x1000
	s_nop 0
	global_load_lds_dwordx4 v22, s[26:27]
	s_add_u32 m0, s100, 0x1400
	s_nop 0
	global_load_lds_dwordx4 v23, s[26:27]
	s_add_u32 m0, s100, 0x2000
	s_nop 0
	global_load_lds_dwordx4 v24, s[26:27]
	s_add_u32 m0, s100, 0x2400
	s_nop 0
	global_load_lds_dwordx4 v25, s[26:27]
	s_add_u32 m0, s100, 0x3000
	s_nop 0
	global_load_lds_dwordx4 v26, s[26:27]
	s_add_u32 m0, s100, 0x3400
	s_nop 0
	global_load_lds_dwordx4 v27, s[26:27]
	s_waitcnt vmcnt(8)
	s_barrier
	s_add_u32 m0, s100, 0x4000
	s_nop 0
	global_load_lds_dwordx4 v28, s[38:39]
	s_add_u32 m0, s100, 0x4400
	s_nop 0
	global_load_lds_dwordx4 v29, s[38:39]
	s_add_u32 m0, s100, 0x5000
	s_nop 0
	global_load_lds_dwordx4 v30, s[38:39]
	s_add_u32 m0, s100, 0x5400
	s_nop 0
	global_load_lds_dwordx4 v31, s[38:39]
	s_add_u32 m0, s100, 0x6000
	s_nop 0
	global_load_lds_dwordx4 v32, s[38:39]
	s_add_u32 m0, s100, 0x6400
	s_nop 0
	global_load_lds_dwordx4 v33, s[38:39]
	s_add_u32 m0, s100, 0x7000
	s_nop 0
	global_load_lds_dwordx4 v34, s[38:39]
	s_add_u32 m0, s100, 0x7400
	s_nop 0
	global_load_lds_dwordx4 v35, s[38:39]
	s_mov_b32 vcc_hi, vcc_lo
	s_add_u32 m0, s49, -1
	s_and_b32 vcc_hi, vcc_hi, m0
	s_lshl_b32 vcc_hi, vcc_hi, 7
	v_add_u32_e32 v20, vcc_hi, v4
	v_add_u32_e32 v21, vcc_hi, v5
	v_add_u32_e32 v22, vcc_hi, v6
	v_add_u32_e32 v23, vcc_hi, v7
	v_add_u32_e32 v24, vcc_hi, v8
	v_add_u32_e32 v25, vcc_hi, v9
	v_add_u32_e32 v26, vcc_hi, v10
	v_add_u32_e32 v27, vcc_hi, v11
	v_add_u32_e32 v28, vcc_hi, v12
	v_add_u32_e32 v29, vcc_hi, v13
	v_add_u32_e32 v30, vcc_hi, v14
	v_add_u32_e32 v31, vcc_hi, v15
	v_add_u32_e32 v32, vcc_hi, v16
	v_add_u32_e32 v33, vcc_hi, v17
	v_add_u32_e32 v34, vcc_hi, v18
	v_add_u32_e32 v35, vcc_hi, v19
	s_add_u32 vcc_lo, vcc_lo, 1
	s_barrier
	s_add_u32 m0, s100, 0x8000
	s_nop 0
	global_load_lds_dwordx4 v20, s[26:27]
	s_add_u32 m0, s100, 0x8400
	s_nop 0
	global_load_lds_dwordx4 v21, s[26:27]
	s_add_u32 m0, s100, 0x9000
	s_nop 0
	global_load_lds_dwordx4 v22, s[26:27]
	s_add_u32 m0, s100, 0x9400
	s_nop 0
	global_load_lds_dwordx4 v23, s[26:27]
	s_add_u32 m0, s100, 0xa000
	s_nop 0
	global_load_lds_dwordx4 v24, s[26:27]
	s_add_u32 m0, s100, 0xa400
	s_nop 0
	global_load_lds_dwordx4 v25, s[26:27]
	s_add_u32 m0, s100, 0xb000
	s_nop 0
	global_load_lds_dwordx4 v26, s[26:27]
	s_add_u32 m0, s100, 0xb400
	s_nop 0
	global_load_lds_dwordx4 v27, s[26:27]
	s_waitcnt vmcnt(8)
	s_barrier
	s_add_u32 m0, s100, 0xc000
	s_nop 0
	global_load_lds_dwordx4 v28, s[38:39]
	s_add_u32 m0, s100, 0xc400
	s_nop 0
	global_load_lds_dwordx4 v29, s[38:39]
	s_add_u32 m0, s100, 0xd000
	s_nop 0
	global_load_lds_dwordx4 v30, s[38:39]
	s_add_u32 m0, s100, 0xd400
	s_nop 0
	global_load_lds_dwordx4 v31, s[38:39]
	s_add_u32 m0, s100, 0xe000
	s_nop 0
	global_load_lds_dwordx4 v32, s[38:39]
	s_add_u32 m0, s100, 0xe400
	s_nop 0
	global_load_lds_dwordx4 v33, s[38:39]
	s_add_u32 m0, s100, 0xf000
	s_nop 0
	global_load_lds_dwordx4 v34, s[38:39]
	s_add_u32 m0, s100, 0xf400
	s_nop 0
	global_load_lds_dwordx4 v35, s[38:39]
	s_add_u32 s24, s24, 0x100
	s_addc_u32 s25, s25, 0
	s_add_i32 s52, s52, 2
	s_cmp_le_i32 s52, s49
	s_cbranch_scc1 .Lpc_ptop_6
	s_add_i32 s42, s42, 1
	s_mov_b32 s46, s44
	s_mov_b32 s47, s45
	s_cmp_eq_u32 s42, 3
	s_cbranch_scc0 .Lpc_pnd_6
	s_waitcnt vmcnt(0)
	s_branch .LBB0_276
.Lpc_pnd_6:
	s_branch .LBB0_249
.LBB0_272:
	v_mov_b32_e32 v131, 0
	v_mov_b32_e32 v130, v131
	v_mov_b32_e32 v129, v131
	v_mov_b32_e32 v128, v131
	v_mov_b32_e32 v127, v131
	v_mov_b32_e32 v126, v131
	v_mov_b32_e32 v125, v131
	v_mov_b32_e32 v124, v131
	v_mov_b32_e32 v123, v131
	v_mov_b32_e32 v122, v131
	v_mov_b32_e32 v121, v131
	v_mov_b32_e32 v120, v131
	v_mov_b32_e32 v115, v131
	v_mov_b32_e32 v114, v131
	v_mov_b32_e32 v113, v131
	v_mov_b32_e32 v112, v131
	v_mov_b32_e32 v119, v131
	v_mov_b32_e32 v118, v131
	v_mov_b32_e32 v117, v131
	v_mov_b32_e32 v116, v131
	v_mov_b32_e32 v111, v131
	v_mov_b32_e32 v110, v131
	v_mov_b32_e32 v109, v131
	v_mov_b32_e32 v108, v131
	v_mov_b32_e32 v107, v131
	v_mov_b32_e32 v106, v131
	v_mov_b32_e32 v105, v131
	v_mov_b32_e32 v104, v131
	v_mov_b32_e32 v103, v131
	v_mov_b32_e32 v102, v131
	v_mov_b32_e32 v101, v131
	v_mov_b32_e32 v100, v131
	v_mov_b32_e32 v99, v131
	v_mov_b32_e32 v98, v131
	v_mov_b32_e32 v97, v131
	v_mov_b32_e32 v96, v131
	v_mov_b32_e32 v95, v131
	v_mov_b32_e32 v94, v131
	v_mov_b32_e32 v93, v131
	v_mov_b32_e32 v92, v131
	v_mov_b32_e32 v91, v131
	v_mov_b32_e32 v90, v131
	v_mov_b32_e32 v89, v131
	v_mov_b32_e32 v88, v131
	v_mov_b32_e32 v87, v131
	v_mov_b32_e32 v86, v131
	v_mov_b32_e32 v85, v131
	v_mov_b32_e32 v84, v131
	v_mov_b32_e32 v83, v131
	v_mov_b32_e32 v82, v131
	v_mov_b32_e32 v81, v131
	v_mov_b32_e32 v80, v131
	v_mov_b32_e32 v79, v131
	v_mov_b32_e32 v78, v131
	v_mov_b32_e32 v77, v131
	v_mov_b32_e32 v76, v131
	v_mov_b32_e32 v75, v131
	v_mov_b32_e32 v74, v131
	v_mov_b32_e32 v73, v131
	v_mov_b32_e32 v72, v131
	v_mov_b32_e32 v71, v131
	v_mov_b32_e32 v70, v131
	v_mov_b32_e32 v69, v131
	v_mov_b32_e32 v68, v131

.LBB0_277:
	s_andn2_b64 vcc, exec, s[0:1]
	s_cbranch_vccnz .LBB0_284
	v_readlane_b32 s20, v253, 13
	v_readlane_b32 s21, v253, 14
	v_readlane_b32 s34, v252, 0
	v_readlane_b32 s99, v254, 62
	s_load_dword s16, s[20:21], 0x0
	s_sub_u32 s20, s20, 0x218
	s_subb_u32 s21, s21, 0
	s_load_dwordx2 s[2:3], s[20:21], 0x138
	s_load_dwordx2 s[8:9], s[20:21], 0x150
	s_load_dwordx2 s[6:7], s[20:21], 0x158
	s_load_dwordx2 s[0:1], s[20:21], 0x160
	v_lshrrev_b32_e32 v0, 3, v194
	v_lshrrev_b32_e32 v1, 4, v194
	v_xor_b32_e32 v1, v1, v194
	v_and_b32_e32 v1, 7, v1
	v_lshlrev_b32_e32 v1, 4, v1
	v_add_u32_e32 v3, 0, v0
	v_lshl_or_b32 v132, v3, 12, v1
	v_lshl_or_b32 v222, v3, 10, v1
	v_add_u32_e32 v3, 32, v0
	v_lshl_or_b32 v133, v3, 12, v1
	v_lshl_or_b32 v223, v3, 10, v1
	v_add_u32_e32 v3, 64, v0
	v_lshl_or_b32 v134, v3, 12, v1
	v_lshl_or_b32 v224, v3, 10, v1
	v_add_u32_e32 v3, 96, v0
	v_lshl_or_b32 v135, v3, 12, v1
	v_lshl_or_b32 v225, v3, 10, v1
	v_and_b32_e32 v0, 15, v194
	v_lshrrev_b32_e32 v1, 1, v0
	v_bfe_u32 v3, v194, 4, 2
	v_xor_b32_e32 v1, v1, v3
	v_lshlrev_b32_e32 v1, 4, v1
	v_lshl_or_b32 v1, v0, 7, v1
	v_lshrrev_b32_e32 v3, 7, v194
	v_lshl_or_b32 v226, v3, 13, v1
	v_bfe_u32 v3, v194, 6, 1
	v_lshl_or_b32 v3, v3, 13, v1
	v_or_b32_e32 v228, 0x4000, v3
	v_xor_b32_e32 v227, 64, v226
	v_xor_b32_e32 v229, 64, v228
	v_lshrrev_b32_e32 v1, 7, v194
	v_lshl_or_b32 v0, v1, 6, v0
	v_bfe_u32 v1, v194, 6, 1
	v_lshlrev_b32_e32 v1, 6, v1
	v_bfe_u32 v3, v194, 4, 2
	v_lshl_or_b32 v1, v3, 2, v1
	v_lshlrev_b32_e32 v1, 1, v1
	v_add_u32_e32 v3, 0, v0
	v_lshl_or_b32 v230, v3, 13, v1
	v_lshl_or_b32 v234, v3, 11, v1
	v_add_u32_e32 v3, 16, v0
	v_lshl_or_b32 v231, v3, 13, v1
	v_lshl_or_b32 v235, v3, 11, v1
	v_add_u32_e32 v3, 32, v0
	v_lshl_or_b32 v232, v3, 13, v1
	v_lshl_or_b32 v236, v3, 11, v1
	v_add_u32_e32 v3, 48, v0
	v_lshl_or_b32 v233, v3, 13, v1
	v_lshl_or_b32 v237, v3, 11, v1
	v_lshrrev_b32_e32 v0, 6, v194
	v_lshlrev_b32_e32 v0, 10, v0
	s_nop 0
	v_readfirstlane_b32 s100, v0
	v_mov_b64_e32 v[4:5], 0
	v_mov_b64_e32 v[6:7], 0
	v_mov_b64_e32 v[8:9], 0
	v_mov_b64_e32 v[10:11], 0
	v_mov_b64_e32 v[12:13], 0
	v_mov_b64_e32 v[14:15], 0
	v_mov_b64_e32 v[16:17], 0
	v_mov_b64_e32 v[18:19], 0
	v_mov_b64_e32 v[20:21], 0
	v_mov_b64_e32 v[22:23], 0
	v_mov_b64_e32 v[24:25], 0
	v_mov_b64_e32 v[26:27], 0
	v_mov_b64_e32 v[28:29], 0
	v_mov_b64_e32 v[30:31], 0
	v_mov_b64_e32 v[32:33], 0
	v_mov_b64_e32 v[34:35], 0
	v_mov_b64_e32 v[36:37], 0
	v_mov_b64_e32 v[38:39], 0
	v_mov_b64_e32 v[40:41], 0
	v_mov_b64_e32 v[42:43], 0
	v_mov_b64_e32 v[44:45], 0
	v_mov_b64_e32 v[46:47], 0
	v_mov_b64_e32 v[48:49], 0
	v_mov_b64_e32 v[50:51], 0
	v_mov_b64_e32 v[52:53], 0
	v_mov_b64_e32 v[54:55], 0
	v_mov_b64_e32 v[56:57], 0
	v_mov_b64_e32 v[58:59], 0
	v_mov_b64_e32 v[60:61], 0
	v_mov_b64_e32 v[62:63], 0
	v_mov_b64_e32 v[64:65], 0
	v_mov_b64_e32 v[66:67], 0
	v_mov_b64_e32 v[68:69], 0
	v_mov_b64_e32 v[70:71], 0
	v_mov_b64_e32 v[72:73], 0
	v_mov_b64_e32 v[74:75], 0
	v_mov_b64_e32 v[76:77], 0
	v_mov_b64_e32 v[78:79], 0
	v_mov_b64_e32 v[80:81], 0
	v_mov_b64_e32 v[82:83], 0
	v_mov_b64_e32 v[84:85], 0
	v_mov_b64_e32 v[86:87], 0
	v_mov_b64_e32 v[88:89], 0
	v_mov_b64_e32 v[90:91], 0
	v_mov_b64_e32 v[92:93], 0
	v_mov_b64_e32 v[94:95], 0
	v_mov_b64_e32 v[96:97], 0
	v_mov_b64_e32 v[98:99], 0
	v_mov_b64_e32 v[100:101], 0
	v_mov_b64_e32 v[102:103], 0
	v_mov_b64_e32 v[104:105], 0
	v_mov_b64_e32 v[106:107], 0
	v_mov_b64_e32 v[108:109], 0
	v_mov_b64_e32 v[110:111], 0
	v_mov_b64_e32 v[112:113], 0
	v_mov_b64_e32 v[114:115], 0
	v_mov_b64_e32 v[116:117], 0
	v_mov_b64_e32 v[118:119], 0
	v_mov_b64_e32 v[120:121], 0
	v_mov_b64_e32 v[122:123], 0
	v_mov_b64_e32 v[124:125], 0
	v_mov_b64_e32 v[126:127], 0
	v_mov_b64_e32 v[128:129], 0
	v_mov_b64_e32 v[130:131], 0
	s_waitcnt lgkmcnt(0)
	s_cmp_gt_i32 s99, 9
	s_cselect_b32 s99, 0x400000, 0
	s_add_u32 s2, s2, s99
	s_addc_u32 s3, s3, 0
	s_lshr_b32 s16, s16, 3
	s_mov_b32 s15, 0
	s_and_b32 s99, s34, 7
	s_lshl_b32 vcc_lo, s15, 3
	s_add_u32 s99, s99, vcc_lo
	s_mul_i32 s99, s99, s16
	s_lshr_b32 vcc_lo, s34, 3
	s_add_u32 s99, s99, vcc_lo
	s_cmp_lt_u32 s99, 0x440
	s_cselect_b32 s17, 1, 0
	s_lshr_b32 vcc_lo, s99, 6
	s_lshl_b32 vcc_lo, vcc_lo, 3
	s_and_b32 vcc_hi, s99, 7
	s_add_u32 vcc_lo, vcc_lo, vcc_hi
	s_lshl_b32 s10, vcc_lo, 7
	s_bfe_u32 vcc_lo, s99, 0x30003
	s_lshl_b32 s11, vcc_lo, 7
	s_cmp_eq_u32 s17, 0
	s_cbranch_scc1 .Lmg_exit
	s_mov_b32 s15, 1
	s_and_b32 s99, s34, 7
	s_lshl_b32 vcc_lo, s15, 3
	s_add_u32 s99, s99, vcc_lo
	s_mul_i32 s99, s99, s16
	s_lshr_b32 vcc_lo, s34, 3
	s_add_u32 s99, s99, vcc_lo
	s_cmp_lt_u32 s99, 0x440
	s_cselect_b32 s17, 1, 0
	s_lshr_b32 vcc_lo, s99, 6
	s_lshl_b32 vcc_lo, vcc_lo, 3
	s_and_b32 vcc_hi, s99, 7
	s_add_u32 vcc_lo, vcc_lo, vcc_hi
	s_lshl_b32 s12, vcc_lo, 7
	s_bfe_u32 vcc_lo, s99, 0x30003
	s_lshl_b32 s13, vcc_lo, 7
	s_mov_b32 s14, 0
	s_lshl_b32 vcc_lo, s10, 12
	s_lshl_b32 vcc_hi, s14, 10
	s_add_u32 vcc_lo, vcc_lo, vcc_hi
	s_add_u32 s18, s0, vcc_lo
	s_addc_u32 s19, s1, 0
	s_lshl_b32 vcc_lo, s11, 10
	s_lshl_b32 vcc_hi, s14, 20
	s_add_u32 vcc_lo, vcc_lo, vcc_hi
	s_add_u32 s20, s2, vcc_lo
	s_addc_u32 s21, s3, 0
	s_lshl_b32 vcc_lo, s10, 13
	s_lshl_b32 vcc_hi, s14, 11
	s_add_u32 vcc_lo, vcc_lo, vcc_hi
	s_lshl_b32 vcc_hi, s11, 1
	s_add_u32 vcc_lo, vcc_lo, vcc_hi
	s_add_u32 s38, s6, vcc_lo
	s_addc_u32 s39, s7, 0
	s_lshl_b32 vcc_lo, s10, 11
	s_lshl_b32 vcc_hi, s11, 1
	s_add_u32 vcc_lo, vcc_lo, vcc_hi
	s_add_u32 s40, s8, vcc_lo
	s_addc_u32 s41, s9, 0
	s_cmp_lt_u32 s14, 3
	s_cbranch_scc0 .Lmg_nt_0
	s_add_u32 s99, s14, 1
	s_lshl_b32 vcc_lo, s10, 12
	s_lshl_b32 vcc_hi, s99, 10
	s_add_u32 vcc_lo, vcc_lo, vcc_hi
	s_add_u32 s22, s0, vcc_lo
	s_addc_u32 s23, s1, 0
	s_lshl_b32 vcc_lo, s11, 10
	s_lshl_b32 vcc_hi, s99, 20
	s_add_u32 vcc_lo, vcc_lo, vcc_hi
	s_add_u32 s24, s2, vcc_lo
	s_addc_u32 s25, s3, 0
	s_mov_b32 s35, 1
	s_branch .Lmg_nd_0
.Lmg_nt_0:
	s_mov_b32 s99, 0
	s_lshl_b32 vcc_lo, s12, 12
	s_lshl_b32 vcc_hi, s99, 10
	s_add_u32 vcc_lo, vcc_lo, vcc_hi
	s_add_u32 s22, s0, vcc_lo
	s_addc_u32 s23, s1, 0
	s_lshl_b32 vcc_lo, s13, 10
	s_lshl_b32 vcc_hi, s99, 20
	s_add_u32 vcc_lo, vcc_lo, vcc_hi
	s_add_u32 s24, s2, vcc_lo
	s_addc_u32 s25, s3, 0
	s_mov_b32 s35, s17
.Lmg_nd_0:
	s_mov_b64 s[26:27], s[18:19]
	s_mov_b64 s[30:31], s[20:21]
	s_add_u32 m0, s100, 0x0
	s_nop 0
	global_load_lds_dwordx4 v132, s[26:27]
	s_add_u32 m0, s100, 0x1000
	s_nop 0
	global_load_lds_dwordx4 v133, s[26:27]
	s_add_u32 m0, s100, 0x2000
	s_nop 0
	global_load_lds_dwordx4 v134, s[26:27]
	s_add_u32 m0, s100, 0x3000
	s_nop 0
	global_load_lds_dwordx4 v135, s[26:27]
	s_add_u32 m0, s100, 0x4000
	s_nop 0
	global_load_lds_dwordx4 v222, s[30:31]
	s_add_u32 m0, s100, 0x5000
	s_nop 0
	global_load_lds_dwordx4 v223, s[30:31]
	s_add_u32 m0, s100, 0x6000
	s_nop 0
	global_load_lds_dwordx4 v224, s[30:31]
	s_add_u32 m0, s100, 0x7000
	s_nop 0
	global_load_lds_dwordx4 v225, s[30:31]
	s_add_u32 s26, s26, 0x80
	s_addc_u32 s27, s27, 0
	s_add_u32 s30, s30, 0x80
	s_addc_u32 s31, s31, 0
	s_waitcnt vmcnt(0)
	s_barrier
.Lmg_sub:
	s_mov_b32 s98, 2
	ds_read_b128 v[140:143], v228
	ds_read_b128 v[144:147], v226
	ds_read_b128 v[148:151], v228 offset:2048
	ds_read_b128 v[152:155], v228 offset:4096
	ds_read_b128 v[156:159], v228 offset:6144
	ds_read_b128 v[160:163], v226 offset:2048
	ds_read_b128 v[164:167], v226 offset:4096
	ds_read_b128 v[168:171], v226 offset:6144
	s_branch .Lmg_body0
.Lmg_top:
	ds_read_b128 v[140:143], v228
	ds_read_b128 v[144:147], v226
	ds_read_b128 v[148:151], v228 offset:2048
	ds_read_b128 v[152:155], v228 offset:4096
	ds_read_b128 v[156:159], v228 offset:6144
	ds_read_b128 v[160:163], v226 offset:2048
	ds_read_b128 v[164:167], v226 offset:4096
	ds_read_b128 v[168:171], v226 offset:6144
	v_mfma_f32_16x16x32_bf16 v[100:103], v[172:175], v[214:217], v[100:103]
	v_mfma_f32_16x16x32_bf16 v[104:107], v[180:183], v[214:217], v[104:107]
	v_mfma_f32_16x16x32_bf16 v[108:111], v[184:187], v[214:217], v[108:111]
	v_mfma_f32_16x16x32_bf16 v[112:115], v[188:191], v[214:217], v[112:115]
	v_mfma_f32_16x16x32_bf16 v[116:119], v[172:175], v[218:221], v[116:119]
	v_mfma_f32_16x16x32_bf16 v[120:123], v[180:183], v[218:221], v[120:123]
	v_mfma_f32_16x16x32_bf16 v[124:127], v[184:187], v[218:221], v[124:127]
	v_mfma_f32_16x16x32_bf16 v[128:131], v[188:191], v[218:221], v[128:131]
.Lmg_body0:
	s_add_u32 m0, s100, 0x8000
	s_nop 0
	global_load_lds_dwordx4 v132, s[26:27]
	s_add_u32 m0, s100, 0x9000
	s_nop 0
	global_load_lds_dwordx4 v133, s[26:27]
	s_add_u32 m0, s100, 0xa000
	s_nop 0
	global_load_lds_dwordx4 v134, s[26:27]
	s_add_u32 m0, s100, 0xb000
	s_nop 0
	global_load_lds_dwordx4 v135, s[26:27]
	s_waitcnt lgkmcnt(7)
	ds_read_b128 v[172:175], v229
	ds_read_b128 v[176:179], v227
	ds_read_b128 v[180:183], v229 offset:2048
	ds_read_b128 v[184:187], v229 offset:4096
	ds_read_b128 v[188:191], v229 offset:6144
	ds_read_b128 v[208:211], v227 offset:2048
	ds_read_b128 v[214:217], v227 offset:4096
	ds_read_b128 v[218:221], v227 offset:6144
	s_add_u32 m0, s100, 0xc000
	s_waitcnt lgkmcnt(14)
	v_mfma_f32_16x16x32_bf16 v[68:71], v[140:143], v[144:147], v[68:71]
	global_load_lds_dwordx4 v222, s[30:31]
	s_waitcnt lgkmcnt(13)
	v_mfma_f32_16x16x32_bf16 v[72:75], v[148:151], v[144:147], v[72:75]
	s_waitcnt lgkmcnt(12)
	v_mfma_f32_16x16x32_bf16 v[76:79], v[152:155], v[144:147], v[76:79]
	s_waitcnt lgkmcnt(11)
	v_mfma_f32_16x16x32_bf16 v[80:83], v[156:159], v[144:147], v[80:83]
	s_add_u32 m0, s100, 0xd000
	s_waitcnt lgkmcnt(10)
	v_mfma_f32_16x16x32_bf16 v[84:87], v[140:143], v[160:163], v[84:87]
	global_load_lds_dwordx4 v223, s[30:31]
	v_mfma_f32_16x16x32_bf16 v[88:91], v[148:151], v[160:163], v[88:91]
	v_mfma_f32_16x16x32_bf16 v[92:95], v[152:155], v[160:163], v[92:95]
	v_mfma_f32_16x16x32_bf16 v[96:99], v[156:159], v[160:163], v[96:99]
	s_add_u32 m0, s100, 0xe000
	s_waitcnt lgkmcnt(9)
	v_mfma_f32_16x16x32_bf16 v[100:103], v[140:143], v[164:167], v[100:103]
	global_load_lds_dwordx4 v224, s[30:31]
	v_mfma_f32_16x16x32_bf16 v[104:107], v[148:151], v[164:167], v[104:107]
	v_mfma_f32_16x16x32_bf16 v[108:111], v[152:155], v[164:167], v[108:111]
	v_mfma_f32_16x16x32_bf16 v[112:115], v[156:159], v[164:167], v[112:115]
	s_add_u32 m0, s100, 0xf000
	s_waitcnt lgkmcnt(8)
	v_mfma_f32_16x16x32_bf16 v[116:119], v[140:143], v[168:171], v[116:119]
	global_load_lds_dwordx4 v225, s[30:31]
	v_mfma_f32_16x16x32_bf16 v[120:123], v[148:151], v[168:171], v[120:123]
	v_mfma_f32_16x16x32_bf16 v[124:127], v[152:155], v[168:171], v[124:127]
	v_mfma_f32_16x16x32_bf16 v[128:131], v[156:159], v[168:171], v[128:131]
	s_add_u32 s26, s26, 0x80
	s_addc_u32 s27, s27, 0
	s_add_u32 s30, s30, 0x80
	s_addc_u32 s31, s31, 0
	s_waitcnt lgkmcnt(6)
	v_mfma_f32_16x16x32_bf16 v[68:71], v[172:175], v[176:179], v[68:71]
	s_waitcnt lgkmcnt(5)
	v_mfma_f32_16x16x32_bf16 v[72:75], v[180:183], v[176:179], v[72:75]
	s_waitcnt lgkmcnt(4)
	v_mfma_f32_16x16x32_bf16 v[76:79], v[184:187], v[176:179], v[76:79]
	s_waitcnt lgkmcnt(3)
	v_mfma_f32_16x16x32_bf16 v[80:83], v[188:191], v[176:179], v[80:83]
	s_waitcnt lgkmcnt(2)
	v_mfma_f32_16x16x32_bf16 v[84:87], v[172:175], v[208:211], v[84:87]
	v_mfma_f32_16x16x32_bf16 v[88:91], v[180:183], v[208:211], v[88:91]
	v_mfma_f32_16x16x32_bf16 v[92:95], v[184:187], v[208:211], v[92:95]
	v_mfma_f32_16x16x32_bf16 v[96:99], v[188:191], v[208:211], v[96:99]
	s_cmp_lt_u32 s98, 8
	s_cbranch_scc1 .Lmg_go
	s_cmp_eq_u32 s35, 0
	s_cbranch_scc1 .Lmg_cur
	s_mov_b64 s[26:27], s[22:23]
	s_mov_b64 s[30:31], s[24:25]
	s_branch .Lmg_go
.Lmg_cur:
	s_mov_b64 s[26:27], s[18:19]
	s_mov_b64 s[30:31], s[20:21]
.Lmg_go:
	s_waitcnt vmcnt(0) lgkmcnt(0)
	s_barrier
	ds_read_b128 v[140:143], v228 offset:32768
	ds_read_b128 v[144:147], v226 offset:32768
	ds_read_b128 v[148:151], v228 offset:34816
	ds_read_b128 v[152:155], v228 offset:36864
	ds_read_b128 v[156:159], v228 offset:38912
	ds_read_b128 v[160:163], v226 offset:34816
	ds_read_b128 v[164:167], v226 offset:36864
	ds_read_b128 v[168:171], v226 offset:38912
	v_mfma_f32_16x16x32_bf16 v[100:103], v[172:175], v[214:217], v[100:103]
	v_mfma_f32_16x16x32_bf16 v[104:107], v[180:183], v[214:217], v[104:107]
	v_mfma_f32_16x16x32_bf16 v[108:111], v[184:187], v[214:217], v[108:111]
	v_mfma_f32_16x16x32_bf16 v[112:115], v[188:191], v[214:217], v[112:115]
	v_mfma_f32_16x16x32_bf16 v[116:119], v[172:175], v[218:221], v[116:119]
	v_mfma_f32_16x16x32_bf16 v[120:123], v[180:183], v[218:221], v[120:123]
	v_mfma_f32_16x16x32_bf16 v[124:127], v[184:187], v[218:221], v[124:127]
	v_mfma_f32_16x16x32_bf16 v[128:131], v[188:191], v[218:221], v[128:131]
	s_cmp_lt_u32 s98, 8
	s_cbranch_scc1 .Lmg_nogp
	global_load_dwordx2 v[0:1], v230, s[38:39] offset:0
	global_load_dwordx2 v[138:139], v230, s[38:39] offset:32
	global_load_dwordx2 v[192:193], v230, s[38:39] offset:64
	global_load_dwordx2 v[238:239], v230, s[38:39] offset:96
	global_load_dwordx2 v[242:243], v231, s[38:39] offset:0
	global_load_dwordx2 v[244:245], v231, s[38:39] offset:32
	global_load_dwordx2 v[246:247], v231, s[38:39] offset:64
	global_load_dwordx2 v[248:249], v231, s[38:39] offset:96
.Lmg_nogp:
	s_add_u32 m0, s100, 0x0
	s_nop 0
	global_load_lds_dwordx4 v132, s[26:27]
	s_add_u32 m0, s100, 0x1000
	s_nop 0
	global_load_lds_dwordx4 v133, s[26:27]
	s_add_u32 m0, s100, 0x2000
	s_nop 0
	global_load_lds_dwordx4 v134, s[26:27]
	s_add_u32 m0, s100, 0x3000
	s_nop 0
	global_load_lds_dwordx4 v135, s[26:27]
	s_waitcnt lgkmcnt(7)
	ds_read_b128 v[172:175], v229 offset:32768
	ds_read_b128 v[176:179], v227 offset:32768
	ds_read_b128 v[180:183], v229 offset:34816
	ds_read_b128 v[184:187], v229 offset:36864
	ds_read_b128 v[188:191], v229 offset:38912
	ds_read_b128 v[208:211], v227 offset:34816
	ds_read_b128 v[214:217], v227 offset:36864
	ds_read_b128 v[218:221], v227 offset:38912
	s_add_u32 m0, s100, 0x4000
	s_waitcnt lgkmcnt(14)
	v_mfma_f32_16x16x32_bf16 v[68:71], v[140:143], v[144:147], v[68:71]
	global_load_lds_dwordx4 v222, s[30:31]
	s_waitcnt lgkmcnt(13)
	v_mfma_f32_16x16x32_bf16 v[72:75], v[148:151], v[144:147], v[72:75]
	s_waitcnt lgkmcnt(12)
	v_mfma_f32_16x16x32_bf16 v[76:79], v[152:155], v[144:147], v[76:79]
	s_waitcnt lgkmcnt(11)
	v_mfma_f32_16x16x32_bf16 v[80:83], v[156:159], v[144:147], v[80:83]
	s_add_u32 m0, s100, 0x5000
	s_waitcnt lgkmcnt(10)
	v_mfma_f32_16x16x32_bf16 v[84:87], v[140:143], v[160:163], v[84:87]
	global_load_lds_dwordx4 v223, s[30:31]
	v_mfma_f32_16x16x32_bf16 v[88:91], v[148:151], v[160:163], v[88:91]
	v_mfma_f32_16x16x32_bf16 v[92:95], v[152:155], v[160:163], v[92:95]
	v_mfma_f32_16x16x32_bf16 v[96:99], v[156:159], v[160:163], v[96:99]
	s_add_u32 m0, s100, 0x6000
	s_waitcnt lgkmcnt(9)
	v_mfma_f32_16x16x32_bf16 v[100:103], v[140:143], v[164:167], v[100:103]
	global_load_lds_dwordx4 v224, s[30:31]
	v_mfma_f32_16x16x32_bf16 v[104:107], v[148:151], v[164:167], v[104:107]
	v_mfma_f32_16x16x32_bf16 v[108:111], v[152:155], v[164:167], v[108:111]
	v_mfma_f32_16x16x32_bf16 v[112:115], v[156:159], v[164:167], v[112:115]
	s_add_u32 m0, s100, 0x7000
	s_waitcnt lgkmcnt(8)
	v_mfma_f32_16x16x32_bf16 v[116:119], v[140:143], v[168:171], v[116:119]
	global_load_lds_dwordx4 v225, s[30:31]
	v_mfma_f32_16x16x32_bf16 v[120:123], v[148:151], v[168:171], v[120:123]
	v_mfma_f32_16x16x32_bf16 v[124:127], v[152:155], v[168:171], v[124:127]
	v_mfma_f32_16x16x32_bf16 v[128:131], v[156:159], v[168:171], v[128:131]
	s_add_u32 s26, s26, 0x80
	s_addc_u32 s27, s27, 0
	s_add_u32 s30, s30, 0x80
	s_addc_u32 s31, s31, 0
	s_cmp_lt_u32 s98, 8
	s_cbranch_scc1 .Lmg_nogp2
	global_load_dwordx2 v[140:141], v232, s[38:39] offset:0
	global_load_dwordx2 v[144:145], v232, s[38:39] offset:32
	global_load_dwordx2 v[148:149], v232, s[38:39] offset:64
	global_load_dwordx2 v[152:153], v232, s[38:39] offset:96
	global_load_dwordx2 v[156:157], v233, s[38:39] offset:0
	global_load_dwordx2 v[160:161], v233, s[38:39] offset:32
	global_load_dwordx2 v[164:165], v233, s[38:39] offset:64
	global_load_dwordx2 v[168:169], v233, s[38:39] offset:96
.Lmg_nogp2:
	s_waitcnt lgkmcnt(6)
	v_mfma_f32_16x16x32_bf16 v[68:71], v[172:175], v[176:179], v[68:71]
	s_waitcnt lgkmcnt(5)
	v_mfma_f32_16x16x32_bf16 v[72:75], v[180:183], v[176:179], v[72:75]
	s_waitcnt lgkmcnt(4)
	v_mfma_f32_16x16x32_bf16 v[76:79], v[184:187], v[176:179], v[76:79]
	s_waitcnt lgkmcnt(3)
	v_mfma_f32_16x16x32_bf16 v[80:83], v[188:191], v[176:179], v[80:83]
	s_waitcnt lgkmcnt(2)
	v_mfma_f32_16x16x32_bf16 v[84:87], v[172:175], v[208:211], v[84:87]
	v_mfma_f32_16x16x32_bf16 v[88:91], v[180:183], v[208:211], v[88:91]
	v_mfma_f32_16x16x32_bf16 v[92:95], v[184:187], v[208:211], v[92:95]
	v_mfma_f32_16x16x32_bf16 v[96:99], v[188:191], v[208:211], v[96:99]
	s_add_u32 s98, s98, 2
	s_waitcnt vmcnt(0) lgkmcnt(0)
	s_barrier
	s_cmp_le_u32 s98, 8
	s_cbranch_scc1 .Lmg_top
	v_mfma_f32_16x16x32_bf16 v[100:103], v[172:175], v[214:217], v[100:103]
	v_mfma_f32_16x16x32_bf16 v[104:107], v[180:183], v[214:217], v[104:107]
	v_mfma_f32_16x16x32_bf16 v[108:111], v[184:187], v[214:217], v[108:111]
	v_mfma_f32_16x16x32_bf16 v[112:115], v[188:191], v[214:217], v[112:115]
	v_mfma_f32_16x16x32_bf16 v[116:119], v[172:175], v[218:221], v[116:119]
	v_mfma_f32_16x16x32_bf16 v[120:123], v[180:183], v[218:221], v[120:123]
	v_mfma_f32_16x16x32_bf16 v[124:127], v[184:187], v[218:221], v[124:127]
	v_mfma_f32_16x16x32_bf16 v[128:131], v[188:191], v[218:221], v[128:131]
	v_lshlrev_b32_e32 v3, 16, v0
	v_and_b32_e32 v137, 0xffff0000, v0
	v_lshlrev_b32_e32 v240, 16, v1
	v_and_b32_e32 v241, 0xffff0000, v1
	v_fmac_f32_e32 v4, v3, v68
	v_fmac_f32_e32 v5, v137, v69
	v_fmac_f32_e32 v6, v240, v70
	v_fmac_f32_e32 v7, v241, v71
	v_lshlrev_b32_e32 v3, 16, v138
	v_and_b32_e32 v137, 0xffff0000, v138
	v_lshlrev_b32_e32 v240, 16, v139
	v_and_b32_e32 v241, 0xffff0000, v139
	v_fmac_f32_e32 v8, v3, v72
	v_fmac_f32_e32 v9, v137, v73
	v_fmac_f32_e32 v10, v240, v74
	v_fmac_f32_e32 v11, v241, v75
	v_lshlrev_b32_e32 v3, 16, v192
	v_and_b32_e32 v137, 0xffff0000, v192
	v_lshlrev_b32_e32 v240, 16, v193
	v_and_b32_e32 v241, 0xffff0000, v193
	v_fmac_f32_e32 v12, v3, v76
	v_fmac_f32_e32 v13, v137, v77
	v_fmac_f32_e32 v14, v240, v78
	v_fmac_f32_e32 v15, v241, v79
	v_lshlrev_b32_e32 v3, 16, v238
	v_and_b32_e32 v137, 0xffff0000, v238
	v_lshlrev_b32_e32 v240, 16, v239
	v_and_b32_e32 v241, 0xffff0000, v239
	v_fmac_f32_e32 v16, v3, v80
	v_fmac_f32_e32 v17, v137, v81
	v_fmac_f32_e32 v18, v240, v82
	v_fmac_f32_e32 v19, v241, v83
	v_lshlrev_b32_e32 v3, 16, v242
	v_and_b32_e32 v137, 0xffff0000, v242
	v_lshlrev_b32_e32 v240, 16, v243
	v_and_b32_e32 v241, 0xffff0000, v243
	v_fmac_f32_e32 v20, v3, v84
	v_fmac_f32_e32 v21, v137, v85
	v_fmac_f32_e32 v22, v240, v86
	v_fmac_f32_e32 v23, v241, v87
	v_lshlrev_b32_e32 v3, 16, v244
	v_and_b32_e32 v137, 0xffff0000, v244
	v_lshlrev_b32_e32 v240, 16, v245
	v_and_b32_e32 v241, 0xffff0000, v245
	v_fmac_f32_e32 v24, v3, v88
	v_fmac_f32_e32 v25, v137, v89
	v_fmac_f32_e32 v26, v240, v90
	v_fmac_f32_e32 v27, v241, v91
	v_lshlrev_b32_e32 v3, 16, v246
	v_and_b32_e32 v137, 0xffff0000, v246
	v_lshlrev_b32_e32 v240, 16, v247
	v_and_b32_e32 v241, 0xffff0000, v247
	v_fmac_f32_e32 v28, v3, v92
	v_fmac_f32_e32 v29, v137, v93
	v_fmac_f32_e32 v30, v240, v94
	v_fmac_f32_e32 v31, v241, v95
	v_lshlrev_b32_e32 v3, 16, v248
	v_and_b32_e32 v137, 0xffff0000, v248
	v_lshlrev_b32_e32 v240, 16, v249
	v_and_b32_e32 v241, 0xffff0000, v249
	v_fmac_f32_e32 v32, v3, v96
	v_fmac_f32_e32 v33, v137, v97
	v_fmac_f32_e32 v34, v240, v98
	v_fmac_f32_e32 v35, v241, v99
	v_lshlrev_b32_e32 v3, 16, v140
	v_and_b32_e32 v137, 0xffff0000, v140
	v_lshlrev_b32_e32 v240, 16, v141
	v_and_b32_e32 v241, 0xffff0000, v141
	v_fmac_f32_e32 v36, v3, v100
	v_fmac_f32_e32 v37, v137, v101
	v_fmac_f32_e32 v38, v240, v102
	v_fmac_f32_e32 v39, v241, v103
	v_lshlrev_b32_e32 v3, 16, v144
	v_and_b32_e32 v137, 0xffff0000, v144
	v_lshlrev_b32_e32 v240, 16, v145
	v_and_b32_e32 v241, 0xffff0000, v145
	v_fmac_f32_e32 v40, v3, v104
	v_fmac_f32_e32 v41, v137, v105
	v_fmac_f32_e32 v42, v240, v106
	v_fmac_f32_e32 v43, v241, v107
	v_lshlrev_b32_e32 v3, 16, v148
	v_and_b32_e32 v137, 0xffff0000, v148
	v_lshlrev_b32_e32 v240, 16, v149
	v_and_b32_e32 v241, 0xffff0000, v149
	v_fmac_f32_e32 v44, v3, v108
	v_fmac_f32_e32 v45, v137, v109
	v_fmac_f32_e32 v46, v240, v110
	v_fmac_f32_e32 v47, v241, v111
	v_lshlrev_b32_e32 v3, 16, v152
	v_and_b32_e32 v137, 0xffff0000, v152
	v_lshlrev_b32_e32 v240, 16, v153
	v_and_b32_e32 v241, 0xffff0000, v153
	v_fmac_f32_e32 v48, v3, v112
	v_fmac_f32_e32 v49, v137, v113
	v_fmac_f32_e32 v50, v240, v114
	v_fmac_f32_e32 v51, v241, v115
	v_lshlrev_b32_e32 v3, 16, v156
	v_and_b32_e32 v137, 0xffff0000, v156
	v_lshlrev_b32_e32 v240, 16, v157
	v_and_b32_e32 v241, 0xffff0000, v157
	v_fmac_f32_e32 v52, v3, v116
	v_fmac_f32_e32 v53, v137, v117
	v_fmac_f32_e32 v54, v240, v118
	v_fmac_f32_e32 v55, v241, v119
	v_lshlrev_b32_e32 v3, 16, v160
	v_and_b32_e32 v137, 0xffff0000, v160
	v_lshlrev_b32_e32 v240, 16, v161
	v_and_b32_e32 v241, 0xffff0000, v161
	v_fmac_f32_e32 v56, v3, v120
	v_fmac_f32_e32 v57, v137, v121
	v_fmac_f32_e32 v58, v240, v122
	v_fmac_f32_e32 v59, v241, v123
	v_lshlrev_b32_e32 v3, 16, v164
	v_and_b32_e32 v137, 0xffff0000, v164
	v_lshlrev_b32_e32 v240, 16, v165
	v_and_b32_e32 v241, 0xffff0000, v165
	v_fmac_f32_e32 v60, v3, v124
	v_fmac_f32_e32 v61, v137, v125
	v_fmac_f32_e32 v62, v240, v126
	v_fmac_f32_e32 v63, v241, v127
	v_lshlrev_b32_e32 v3, 16, v168
	v_and_b32_e32 v137, 0xffff0000, v168
	v_lshlrev_b32_e32 v240, 16, v169
	v_and_b32_e32 v241, 0xffff0000, v169
	v_fmac_f32_e32 v64, v3, v128
	v_fmac_f32_e32 v65, v137, v129
	v_fmac_f32_e32 v66, v240, v130
	v_fmac_f32_e32 v67, v241, v131
	s_cmp_lt_u32 s14, 3
	s_cbranch_scc1 .Lmg_nostore
	v_cvt_pk_bf16_f32 v240, v4, v5
	v_cvt_pk_bf16_f32 v241, v6, v7
	global_store_dwordx2 v234, v[240:241], s[40:41] offset:0
	v_cvt_pk_bf16_f32 v238, v8, v9
	v_cvt_pk_bf16_f32 v239, v10, v11
	global_store_dwordx2 v234, v[238:239], s[40:41] offset:32
	v_cvt_pk_bf16_f32 v240, v12, v13
	v_cvt_pk_bf16_f32 v241, v14, v15
	global_store_dwordx2 v234, v[240:241], s[40:41] offset:64
	v_cvt_pk_bf16_f32 v238, v16, v17
	v_cvt_pk_bf16_f32 v239, v18, v19
	global_store_dwordx2 v234, v[238:239], s[40:41] offset:96
	v_cvt_pk_bf16_f32 v240, v20, v21
	v_cvt_pk_bf16_f32 v241, v22, v23
	global_store_dwordx2 v235, v[240:241], s[40:41] offset:0
	v_cvt_pk_bf16_f32 v238, v24, v25
	v_cvt_pk_bf16_f32 v239, v26, v27
	global_store_dwordx2 v235, v[238:239], s[40:41] offset:32
	v_cvt_pk_bf16_f32 v240, v28, v29
	v_cvt_pk_bf16_f32 v241, v30, v31
	global_store_dwordx2 v235, v[240:241], s[40:41] offset:64
	v_cvt_pk_bf16_f32 v238, v32, v33
	v_cvt_pk_bf16_f32 v239, v34, v35
	global_store_dwordx2 v235, v[238:239], s[40:41] offset:96
	v_cvt_pk_bf16_f32 v240, v36, v37
	v_cvt_pk_bf16_f32 v241, v38, v39
	global_store_dwordx2 v236, v[240:241], s[40:41] offset:0
	v_cvt_pk_bf16_f32 v238, v40, v41
	v_cvt_pk_bf16_f32 v239, v42, v43
	global_store_dwordx2 v236, v[238:239], s[40:41] offset:32
	v_cvt_pk_bf16_f32 v240, v44, v45
	v_cvt_pk_bf16_f32 v241, v46, v47
	global_store_dwordx2 v236, v[240:241], s[40:41] offset:64
	v_cvt_pk_bf16_f32 v238, v48, v49
	v_cvt_pk_bf16_f32 v239, v50, v51
	global_store_dwordx2 v236, v[238:239], s[40:41] offset:96
	v_cvt_pk_bf16_f32 v240, v52, v53
	v_cvt_pk_bf16_f32 v241, v54, v55
	global_store_dwordx2 v237, v[240:241], s[40:41] offset:0
	v_cvt_pk_bf16_f32 v238, v56, v57
	v_cvt_pk_bf16_f32 v239, v58, v59
	global_store_dwordx2 v237, v[238:239], s[40:41] offset:32
	v_cvt_pk_bf16_f32 v240, v60, v61
	v_cvt_pk_bf16_f32 v241, v62, v63
	global_store_dwordx2 v237, v[240:241], s[40:41] offset:64
	v_cvt_pk_bf16_f32 v238, v64, v65
	v_cvt_pk_bf16_f32 v239, v66, v67
	global_store_dwordx2 v237, v[238:239], s[40:41] offset:96
	v_mov_b64_e32 v[4:5], 0
	v_mov_b64_e32 v[6:7], 0
	v_mov_b64_e32 v[8:9], 0
	v_mov_b64_e32 v[10:11], 0
	v_mov_b64_e32 v[12:13], 0
	v_mov_b64_e32 v[14:15], 0
	v_mov_b64_e32 v[16:17], 0
	v_mov_b64_e32 v[18:19], 0
	v_mov_b64_e32 v[20:21], 0
	v_mov_b64_e32 v[22:23], 0
	v_mov_b64_e32 v[24:25], 0
	v_mov_b64_e32 v[26:27], 0
	v_mov_b64_e32 v[28:29], 0
	v_mov_b64_e32 v[30:31], 0
	v_mov_b64_e32 v[32:33], 0
	v_mov_b64_e32 v[34:35], 0
	v_mov_b64_e32 v[36:37], 0
	v_mov_b64_e32 v[38:39], 0
	v_mov_b64_e32 v[40:41], 0
	v_mov_b64_e32 v[42:43], 0
	v_mov_b64_e32 v[44:45], 0
	v_mov_b64_e32 v[46:47], 0
	v_mov_b64_e32 v[48:49], 0
	v_mov_b64_e32 v[50:51], 0
	v_mov_b64_e32 v[52:53], 0
	v_mov_b64_e32 v[54:55], 0
	v_mov_b64_e32 v[56:57], 0
	v_mov_b64_e32 v[58:59], 0
	v_mov_b64_e32 v[60:61], 0
	v_mov_b64_e32 v[62:63], 0
	v_mov_b64_e32 v[64:65], 0
	v_mov_b64_e32 v[66:67], 0
.Lmg_nostore:
	v_mov_b64_e32 v[68:69], 0
	v_mov_b64_e32 v[70:71], 0
	v_mov_b64_e32 v[72:73], 0
	v_mov_b64_e32 v[74:75], 0
	v_mov_b64_e32 v[76:77], 0
	v_mov_b64_e32 v[78:79], 0
	v_mov_b64_e32 v[80:81], 0
	v_mov_b64_e32 v[82:83], 0
	v_mov_b64_e32 v[84:85], 0
	v_mov_b64_e32 v[86:87], 0
	v_mov_b64_e32 v[88:89], 0
	v_mov_b64_e32 v[90:91], 0
	v_mov_b64_e32 v[92:93], 0
	v_mov_b64_e32 v[94:95], 0
	v_mov_b64_e32 v[96:97], 0
	v_mov_b64_e32 v[98:99], 0
	v_mov_b64_e32 v[100:101], 0
	v_mov_b64_e32 v[102:103], 0
	v_mov_b64_e32 v[104:105], 0
	v_mov_b64_e32 v[106:107], 0
	v_mov_b64_e32 v[108:109], 0
	v_mov_b64_e32 v[110:111], 0
	v_mov_b64_e32 v[112:113], 0
	v_mov_b64_e32 v[114:115], 0
	v_mov_b64_e32 v[116:117], 0
	v_mov_b64_e32 v[118:119], 0
	v_mov_b64_e32 v[120:121], 0
	v_mov_b64_e32 v[122:123], 0
	v_mov_b64_e32 v[124:125], 0
	v_mov_b64_e32 v[126:127], 0
	v_mov_b64_e32 v[128:129], 0
	v_mov_b64_e32 v[130:131], 0
	s_cmp_eq_u32 s35, 0
	s_cbranch_scc1 .Lmg_exit
	s_mov_b64 s[18:19], s[22:23]
	s_mov_b64 s[20:21], s[24:25]
	s_cmp_lt_u32 s14, 3
	s_cbranch_scc1 .Lmg_sameb
	s_mov_b32 s14, 0
	s_mov_b32 s10, s12
	s_mov_b32 s11, s13
	s_add_u32 s15, s15, 1
	s_and_b32 s99, s34, 7
	s_lshl_b32 vcc_lo, s15, 3
	s_add_u32 s99, s99, vcc_lo
	s_mul_i32 s99, s99, s16
	s_lshr_b32 vcc_lo, s34, 3
	s_add_u32 s99, s99, vcc_lo
	s_cmp_lt_u32 s99, 0x440
	s_cselect_b32 s17, 1, 0
	s_lshr_b32 vcc_lo, s99, 6
	s_lshl_b32 vcc_lo, vcc_lo, 3
	s_and_b32 vcc_hi, s99, 7
	s_add_u32 vcc_lo, vcc_lo, vcc_hi
	s_lshl_b32 s12, vcc_lo, 7
	s_bfe_u32 vcc_lo, s99, 0x30003
	s_lshl_b32 s13, vcc_lo, 7
	s_branch .Lmg_advd
.Lmg_sameb:
	s_add_u32 s14, s14, 1
.Lmg_advd:
	s_lshl_b32 vcc_lo, s10, 13
	s_lshl_b32 vcc_hi, s14, 11
	s_add_u32 vcc_lo, vcc_lo, vcc_hi
	s_lshl_b32 vcc_hi, s11, 1
	s_add_u32 vcc_lo, vcc_lo, vcc_hi
	s_add_u32 s38, s6, vcc_lo
	s_addc_u32 s39, s7, 0
	s_lshl_b32 vcc_lo, s10, 11
	s_lshl_b32 vcc_hi, s11, 1
	s_add_u32 vcc_lo, vcc_lo, vcc_hi
	s_add_u32 s40, s8, vcc_lo
	s_addc_u32 s41, s9, 0
	s_cmp_lt_u32 s14, 3
	s_cbranch_scc0 .Lmg_nt_1
	s_add_u32 s99, s14, 1
	s_lshl_b32 vcc_lo, s10, 12
	s_lshl_b32 vcc_hi, s99, 10
	s_add_u32 vcc_lo, vcc_lo, vcc_hi
	s_add_u32 s22, s0, vcc_lo
	s_addc_u32 s23, s1, 0
	s_lshl_b32 vcc_lo, s11, 10
	s_lshl_b32 vcc_hi, s99, 20
	s_add_u32 vcc_lo, vcc_lo, vcc_hi
	s_add_u32 s24, s2, vcc_lo
	s_addc_u32 s25, s3, 0
	s_mov_b32 s35, 1
	s_branch .Lmg_nd_1

.Lmg_exit:
	s_waitcnt vmcnt(0) lgkmcnt(0)
	v_readlane_b32 s2, v254, 62

.LBB0_295:
	s_or_b64 exec, exec, s[2:3]
	v_readlane_b32 s6, v253, 13
	s_waitcnt vmcnt(1)
	v_mov_b32_e32 v68, v194
	s_movk_i32 s0, 0x400
	s_movk_i32 s2, 0x400
	s_movk_i32 s1, 0x400
	v_readlane_b32 s7, v253, 14
	s_load_dword s3, s[6:7], 0x10
	s_load_dword s22, s[6:7], 0x0
	s_waitcnt lgkmcnt(0)
	s_lshr_b32 s3, s3, 16
	s_cmp_lg_u32 s3, 0
	s_cselect_b64 s[20:21], -1, 0
	s_cmp_lg_u64 s[20:21], 0
	s_addc_u32 s3, s22, 0
	s_lshr_b32 s46, s3, 3
	v_readlane_b32 s3, v254, 36
	s_mul_i32 s52, s46, s3
	v_readlane_b32 s3, v254, 30
	s_add_i32 s52, s52, s3
	s_cmpk_gt_i32 s52, 0x10ff
	s_cbranch_scc1 .LBB0_319
	v_readlane_b32 s6, v254, 63
	s_ashr_i32 s47, s1, 6
	v_readlane_b32 s7, v255, 0
	s_and_b64 s[20:21], s[6:7], exec
	s_mov_b32 s1, 0x2080000
	v_readlane_b32 s8, v252, 37
	s_cselect_b32 s1, s1, 0xc40000
	v_readlane_b32 s16, v252, 45
	v_readlane_b32 s17, v252, 46
	s_add_u32 s24, s16, s1
	s_addc_u32 s25, s17, 0
	s_ashr_i32 s1, s52, 31
	s_lshr_b32 s1, s1, 24
	v_readlane_b32 s20, v252, 49
	s_add_i32 s1, s52, s1
	s_ashr_i32 s1, s1, 8
	s_lshl_b32 s20, s52, 7
	v_lshlrev_b32_e32 v0, 3, v68
	v_readlane_b32 s21, v252, 50
	v_ashrrev_i32_e32 v3, 3, v68
	s_lshl_b32 s3, s1, 10
	s_and_b32 s20, s20, 0x380
	v_and_b32_e32 v0, 56, v0
	v_lshrrev_b32_e32 v132, 4, v68
	v_xor_b32_e32 v132, v132, v68
	v_and_b32_e32 v132, 7, v132
	v_lshlrev_b32_e32 v0, 3, v132
	v_mov_b32_e32 v1, v2
	s_or_b32 s55, s3, s20
	s_lshl_b32 s1, s1, 12
	s_lshl_b32 s3, s52, 4
	v_mad_i64_i32 v[4:5], s[20:21], s0, v3, v[0:1]
	v_mad_i64_i32 v[0:1], s[20:21], s2, v3, v[0:1]
	s_sub_i32 s1, s3, s1
	s_mul_hi_i32 s21, s55, s0
	s_mul_i32 s20, s55, s0
	s_and_b32 s53, s1, 0xffffff80
	s_ashr_i32 s1, s0, 31
	s_ashr_i32 s3, s2, 31
	s_lshl_b64 s[20:21], s[20:21], 1
	s_add_u32 s20, s76, s20
	s_addc_u32 s21, s77, s21
	v_lshlrev_b64 v[70:71], 1, v[4:5]
	v_lshl_add_u64 v[144:145], s[20:21], 0, v[70:71]
	s_mul_hi_i32 s21, s53, s2
	s_mul_i32 s20, s53, s2
	s_lshl_b64 s[20:21], s[20:21], 1
	s_add_u32 s20, s24, s20
	s_addc_u32 s21, s25, s21
	s_waitcnt vmcnt(0)
	v_lshlrev_b64 v[72:73], 1, v[0:1]
	v_readlane_b32 s22, v252, 51
	v_readlane_b32 s23, v252, 52
	v_lshl_add_u64 v[146:147], s[20:21], 0, v[72:73]
	s_lshl_b64 s[20:21], s[0:1], 6
	v_lshl_add_u64 v[0:1], v[144:145], 0, s[20:21]
	s_lshl_b64 s[22:23], s[2:3], 6
	s_waitcnt vmcnt(0)
	v_lshl_add_u64 v[36:37], v[0:1], 0, s[20:21]
	s_waitcnt vmcnt(0)
	v_lshl_add_u64 v[56:57], v[146:147], 0, s[22:23]
	v_lshl_add_u64 v[40:41], v[36:37], 0, s[20:21]
	s_waitcnt vmcnt(0)
	v_lshl_add_u64 v[60:61], v[56:57], 0, s[22:23]
	s_waitcnt vmcnt(0)
	v_lshl_add_u64 v[64:65], v[60:61], 0, s[22:23]
	s_bfe_u32 s100, s101, 0x20002
	s_lshl_b32 s100, s100, 10
	s_bfe_u32 vcc_lo, s101, 0x80008
	s_add_u32 vcc_lo, vcc_lo, 0
	s_add_u32 vcc_hi, s47, -1
	s_and_b32 vcc_lo, vcc_lo, vcc_hi
	s_lshl_b32 vcc_lo, vcc_lo, 7
	s_mov_b32 vcc_hi, 0
	v_lshl_add_u64 v[20:21], v[144:145], 0, vcc
	s_add_u32 m0, s100, 0x0
	s_nop 0
	global_load_lds_dwordx4 v[20:21], off
	v_lshl_add_u64 v[20:21], v[0:1], 0, vcc
	s_add_u32 m0, s100, 0x1000
	s_nop 0
	global_load_lds_dwordx4 v[20:21], off
	v_lshl_add_u64 v[20:21], v[36:37], 0, vcc
	s_add_u32 m0, s100, 0x2000
	s_nop 0
	global_load_lds_dwordx4 v[20:21], off
	v_lshl_add_u64 v[20:21], v[40:41], 0, vcc
	s_add_u32 m0, s100, 0x3000
	s_nop 0
	global_load_lds_dwordx4 v[20:21], off
	v_lshl_add_u64 v[20:21], v[146:147], 0, vcc
	s_add_u32 m0, s100, 0x4000
	s_nop 0
	global_load_lds_dwordx4 v[20:21], off
	v_lshl_add_u64 v[20:21], v[56:57], 0, vcc
	s_add_u32 m0, s100, 0x5000
	s_nop 0
	global_load_lds_dwordx4 v[20:21], off
	v_lshl_add_u64 v[20:21], v[60:61], 0, vcc
	s_add_u32 m0, s100, 0x6000
	s_nop 0
	global_load_lds_dwordx4 v[20:21], off
	v_lshl_add_u64 v[20:21], v[64:65], 0, vcc
	s_add_u32 m0, s100, 0x7000
	s_nop 0
	global_load_lds_dwordx4 v[20:21], off
	s_bfe_u32 vcc_lo, s101, 0x80008
	s_add_u32 vcc_lo, vcc_lo, 1
	s_add_u32 vcc_hi, s47, -1
	s_and_b32 vcc_lo, vcc_lo, vcc_hi
	s_lshl_b32 vcc_lo, vcc_lo, 7
	s_mov_b32 vcc_hi, 0
	v_lshl_add_u64 v[20:21], v[144:145], 0, vcc
	s_add_u32 m0, s100, 0x8000
	s_nop 0
	global_load_lds_dwordx4 v[20:21], off
	v_lshl_add_u64 v[20:21], v[0:1], 0, vcc
	s_add_u32 m0, s100, 0x9000
	s_nop 0
	global_load_lds_dwordx4 v[20:21], off
	v_lshl_add_u64 v[20:21], v[36:37], 0, vcc
	s_add_u32 m0, s100, 0xa000
	s_nop 0
	global_load_lds_dwordx4 v[20:21], off
	v_lshl_add_u64 v[20:21], v[40:41], 0, vcc
	s_add_u32 m0, s100, 0xb000
	s_nop 0
	global_load_lds_dwordx4 v[20:21], off
	v_lshl_add_u64 v[20:21], v[146:147], 0, vcc
	s_add_u32 m0, s100, 0xc000
	s_nop 0
	global_load_lds_dwordx4 v[20:21], off
	v_lshl_add_u64 v[20:21], v[56:57], 0, vcc
	s_add_u32 m0, s100, 0xd000
	s_nop 0
	global_load_lds_dwordx4 v[20:21], off
	v_lshl_add_u64 v[20:21], v[60:61], 0, vcc
	s_add_u32 m0, s100, 0xe000
	s_nop 0
	global_load_lds_dwordx4 v[20:21], off
	v_lshl_add_u64 v[20:21], v[64:65], 0, vcc
	s_add_u32 m0, s100, 0xf000
	s_nop 0
	global_load_lds_dwordx4 v[20:21], off
	v_lshrrev_b32_e32 v1, 1, v3
	v_xor_b32_e32 v1, v1, v68
	v_lshlrev_b32_e32 v0, 7, v3
	v_lshlrev_b32_e32 v1, 4, v1
	s_movk_i32 s1, 0x70
	v_lshrrev_b32_e32 v69, 4, v68
	v_bfe_u32 v74, v68, 4, 2
	v_and_or_b32 v3, v1, s1, v0
	v_lshl_add_u64 v[0:1], s[76:77], 0, v[70:71]
	v_bfe_u32 v70, v68, 1, 3
	v_bitop3_b32 v69, v69, v70, 3 bitop3:0x6c
	v_lshlrev_b32_e32 v71, 6, v68
	v_lshlrev_b32_e32 v68, 7, v68
	v_bitop3_b32 v70, v74, v70, 4 bitop3:0x36
	v_lshl_add_u64 v[138:139], s[24:25], 0, v[72:73]
	v_lshlrev_b32_e32 v69, 4, v69
	v_and_b32_e32 v71, 0xffffe000, v71
	v_and_b32_e32 v72, 0x780, v68
	v_and_b32_e32 v68, 0x2000, v68
	v_lshlrev_b32_e32 v70, 4, v70
	s_cmp_gt_i32 s47, 0
	v_or_b32_e32 v73, v69, v71
	v_or_b32_e32 v69, v69, v68
	v_or_b32_e32 v71, v70, v71
	v_or_b32_e32 v68, v70, v68
	s_mov_b32 s49, 0
	s_cselect_b64 s[24:25], -1, 0
	v_add_u32_e32 v137, v73, v72
	v_add_u32_e32 v188, v69, v72
	v_add_u32_e32 v189, v71, v72
	v_add_u32_e32 v190, v68, v72
	s_mov_b32 s1, 0
	s_mov_b32 s3, 0
	v_readlane_b32 s9, v252, 38
	v_readlane_b32 s10, v252, 39
	v_readlane_b32 s11, v252, 40
	v_readlane_b32 s12, v252, 41
	v_readlane_b32 s13, v252, 42
	v_readlane_b32 s14, v252, 43
	v_readlane_b32 s15, v252, 44
	v_readlane_b32 s18, v252, 47
	v_readlane_b32 s19, v252, 48
	s_bfe_u32 vcc_lo, s101, 0x10001
	v_and_b32_e32 v20, 15, v194
	v_lshrrev_b32_e32 v21, 1, v20
	v_bfe_u32 v22, v194, 4, 2
	v_xor_b32_e32 v21, v21, v22
	v_lshlrev_b32_e32 v21, 4, v21
	v_lshl_or_b32 v250, v20, 7, v21
	v_mov_b32_e32 v22, vcc_lo
	v_lshl_or_b32 v22, v22, 13, v250
	v_or_b32_e32 v251, 0x4000, v22
	v_and_b32_e32 v20, 63, v194
	v_mov_b32_e32 v21, vcc_lo
	v_lshlrev_b32_e32 v21, 4, v21
	v_lshrrev_b32_e32 v22, 3, v20
	v_add_u32_e32 v21, v21, v22
	v_lshrrev_b32_e32 v22, 4, v20
	v_and_b32_e32 v23, 7, v20
	v_xor_b32_e32 v24, v23, v22
	v_lshlrev_b32_e32 v24, 4, v24
	v_or_b32_e32 v22, 4, v22
	v_xor_b32_e32 v25, v23, v22
	v_lshlrev_b32_e32 v25, 4, v25
	s_movk_i32 s98, 0x800
	s_movk_i32 s99, 0x800
	v_add_u32_e32 v26, 0, v21
	v_mad_u32_u24 v4, v26, s98, v24
	v_add_u32_e32 v26, 8, v21
	v_mad_u32_u24 v5, v26, s98, v25
	v_add_u32_e32 v26, 32, v21
	v_mad_u32_u24 v6, v26, s98, v24
	v_add_u32_e32 v26, 40, v21
	v_mad_u32_u24 v7, v26, s98, v25
	v_add_u32_e32 v26, 64, v21
	v_mad_u32_u24 v8, v26, s98, v24
	v_add_u32_e32 v26, 72, v21
	v_mad_u32_u24 v9, v26, s98, v25
	v_add_u32_e32 v26, 96, v21
	v_mad_u32_u24 v10, v26, s98, v24
	v_add_u32_e32 v26, 104, v21
	v_mad_u32_u24 v11, v26, s98, v25
	v_add_u32_e32 v26, 0, v21
	v_mad_u32_u24 v12, v26, s99, v24
	v_add_u32_e32 v26, 8, v21
	v_mad_u32_u24 v13, v26, s99, v25
	v_add_u32_e32 v26, 32, v21
	v_mad_u32_u24 v14, v26, s99, v24
	v_add_u32_e32 v26, 40, v21
	v_mad_u32_u24 v15, v26, s99, v25
	v_add_u32_e32 v26, 64, v21
	v_mad_u32_u24 v16, v26, s99, v24
	v_add_u32_e32 v26, 72, v21
	v_mad_u32_u24 v17, v26, s99, v25
	v_add_u32_e32 v26, 96, v21
	v_mad_u32_u24 v18, v26, s99, v24
	v_add_u32_e32 v26, 104, v21
	v_mad_u32_u24 v19, v26, s99, v25
	s_bfe_u32 vcc_hi, s101, 0x20002
	s_lshl_b32 vcc_hi, vcc_hi, 3
	s_mul_i32 s98, s98, vcc_hi
	s_mul_i32 s99, s99, vcc_hi
	s_lshl_b32 vcc_hi, vcc_hi, 3
	s_and_b32 vcc_hi, vcc_hi, 0x70
	s_add_u32 s98, s98, vcc_hi
	s_add_u32 s99, s99, vcc_hi
	s_lshl_b32 s100, vcc_lo, 11
	s_bitcmp1_b32 s101, 0
	s_cselect_b32 s100, -1, s100
	s_waitcnt vmcnt(0) lgkmcnt(0)
	s_barrier
	s_branch .LBB0_299

.LBB0_319:
	s_nop 0
	v_mov_b32_e32 v68, v194
	s_movk_i32 s0, 0x200
	s_movk_i32 s2, 0x200
	s_movk_i32 s1, 0x200
	s_cmpk_gt_i32 s52, 0x21f
	s_cbranch_scc1 .LBB0_342
	v_readlane_b32 s6, v254, 63
	s_ashr_i32 s47, s1, 6
	v_readlane_b32 s7, v255, 0
	s_and_b64 s[20:21], s[6:7], exec
	s_cselect_b32 s1, 0x80000, 0
	s_add_u32 s24, s74, s1
	s_addc_u32 s25, s75, 0
	s_ashr_i32 s1, s52, 31
	s_lshr_b32 s1, s1, 27
	s_add_i32 s1, s52, s1
	s_ashr_i32 s1, s1, 5
	s_lshl_b32 s20, s52, 7
	v_lshlrev_b32_e32 v0, 3, v68
	v_ashrrev_i32_e32 v3, 3, v68
	s_lshl_b32 s3, s1, 10
	s_and_b32 s20, s20, 0x380
	v_and_b32_e32 v0, 56, v0
	v_lshrrev_b32_e32 v132, 4, v68
	v_xor_b32_e32 v132, v132, v68
	v_and_b32_e32 v132, 7, v132
	v_lshlrev_b32_e32 v0, 3, v132
	v_mov_b32_e32 v1, v2
	s_or_b32 s53, s3, s20
	s_lshl_b32 s1, s1, 9
	s_lshl_b32 s3, s52, 4
	v_mad_i64_i32 v[4:5], s[20:21], s0, v3, v[0:1]
	v_mad_i64_i32 v[0:1], s[20:21], s2, v3, v[0:1]
	s_sub_i32 s1, s3, s1
	s_mul_hi_i32 s21, s0, s53
	s_mul_i32 s20, s0, s53
	s_and_b32 s52, s1, 0xffffff80
	s_ashr_i32 s1, s0, 31
	s_ashr_i32 s3, s2, 31
	s_lshl_b64 s[20:21], s[20:21], 1
	s_add_u32 s20, s82, s20
	s_addc_u32 s21, s83, s21
	v_lshlrev_b64 v[70:71], 1, v[4:5]
	v_lshl_add_u64 v[144:145], s[20:21], 0, v[70:71]
	s_mul_hi_i32 s21, s2, s52
	s_mul_i32 s20, s2, s52
	s_lshl_b64 s[20:21], s[20:21], 1
	s_add_u32 s20, s24, s20
	s_addc_u32 s21, s25, s21
	s_waitcnt vmcnt(0)
	v_lshlrev_b64 v[72:73], 1, v[0:1]
	v_lshl_add_u64 v[146:147], s[20:21], 0, v[72:73]
	s_lshl_b64 s[20:21], s[0:1], 6
	v_lshl_add_u64 v[0:1], v[144:145], 0, s[20:21]
	s_lshl_b64 s[22:23], s[2:3], 6
	s_waitcnt vmcnt(0)
	v_lshl_add_u64 v[36:37], v[0:1], 0, s[20:21]
	s_waitcnt vmcnt(0)
	v_lshl_add_u64 v[56:57], v[146:147], 0, s[22:23]
	v_lshl_add_u64 v[40:41], v[36:37], 0, s[20:21]
	s_waitcnt vmcnt(0)
	v_lshl_add_u64 v[60:61], v[56:57], 0, s[22:23]
	s_waitcnt vmcnt(0)
	v_lshl_add_u64 v[64:65], v[60:61], 0, s[22:23]
	s_bfe_u32 s100, s101, 0x20002
	s_lshl_b32 s100, s100, 10
	s_bfe_u32 vcc_lo, s101, 0x80008
	s_add_u32 vcc_lo, vcc_lo, 0
	s_add_u32 vcc_hi, s47, -1
	s_and_b32 vcc_lo, vcc_lo, vcc_hi
	s_lshl_b32 vcc_lo, vcc_lo, 7
	s_mov_b32 vcc_hi, 0
	v_lshl_add_u64 v[20:21], v[144:145], 0, vcc
	s_add_u32 m0, s100, 0x0
	s_nop 0
	global_load_lds_dwordx4 v[20:21], off
	v_lshl_add_u64 v[20:21], v[0:1], 0, vcc
	s_add_u32 m0, s100, 0x1000
	s_nop 0
	global_load_lds_dwordx4 v[20:21], off
	v_lshl_add_u64 v[20:21], v[36:37], 0, vcc
	s_add_u32 m0, s100, 0x2000
	s_nop 0
	global_load_lds_dwordx4 v[20:21], off
	v_lshl_add_u64 v[20:21], v[40:41], 0, vcc
	s_add_u32 m0, s100, 0x3000
	s_nop 0
	global_load_lds_dwordx4 v[20:21], off
	v_lshl_add_u64 v[20:21], v[146:147], 0, vcc
	s_add_u32 m0, s100, 0x4000
	s_nop 0
	global_load_lds_dwordx4 v[20:21], off
	v_lshl_add_u64 v[20:21], v[56:57], 0, vcc
	s_add_u32 m0, s100, 0x5000
	s_nop 0
	global_load_lds_dwordx4 v[20:21], off
	v_lshl_add_u64 v[20:21], v[60:61], 0, vcc
	s_add_u32 m0, s100, 0x6000
	s_nop 0
	global_load_lds_dwordx4 v[20:21], off
	v_lshl_add_u64 v[20:21], v[64:65], 0, vcc
	s_add_u32 m0, s100, 0x7000
	s_nop 0
	global_load_lds_dwordx4 v[20:21], off
	s_bfe_u32 vcc_lo, s101, 0x80008
	s_add_u32 vcc_lo, vcc_lo, 1
	s_add_u32 vcc_hi, s47, -1
	s_and_b32 vcc_lo, vcc_lo, vcc_hi
	s_lshl_b32 vcc_lo, vcc_lo, 7
	s_mov_b32 vcc_hi, 0
	v_lshl_add_u64 v[20:21], v[144:145], 0, vcc
	s_add_u32 m0, s100, 0x8000
	s_nop 0
	global_load_lds_dwordx4 v[20:21], off
	v_lshl_add_u64 v[20:21], v[0:1], 0, vcc
	s_add_u32 m0, s100, 0x9000
	s_nop 0
	global_load_lds_dwordx4 v[20:21], off
	v_lshl_add_u64 v[20:21], v[36:37], 0, vcc
	s_add_u32 m0, s100, 0xa000
	s_nop 0
	global_load_lds_dwordx4 v[20:21], off
	v_lshl_add_u64 v[20:21], v[40:41], 0, vcc
	s_add_u32 m0, s100, 0xb000
	s_nop 0
	global_load_lds_dwordx4 v[20:21], off
	v_lshl_add_u64 v[20:21], v[146:147], 0, vcc
	s_add_u32 m0, s100, 0xc000
	s_nop 0
	global_load_lds_dwordx4 v[20:21], off
	v_lshl_add_u64 v[20:21], v[56:57], 0, vcc
	s_add_u32 m0, s100, 0xd000
	s_nop 0
	global_load_lds_dwordx4 v[20:21], off
	v_lshl_add_u64 v[20:21], v[60:61], 0, vcc
	s_add_u32 m0, s100, 0xe000
	s_nop 0
	global_load_lds_dwordx4 v[20:21], off
	v_lshl_add_u64 v[20:21], v[64:65], 0, vcc
	s_add_u32 m0, s100, 0xf000
	s_nop 0
	global_load_lds_dwordx4 v[20:21], off
	v_lshrrev_b32_e32 v1, 1, v3
	v_xor_b32_e32 v1, v1, v68
	v_lshlrev_b32_e32 v0, 7, v3
	v_lshlrev_b32_e32 v1, 4, v1
	s_movk_i32 s1, 0x70
	v_lshrrev_b32_e32 v69, 4, v68
	v_bfe_u32 v74, v68, 4, 2
	v_and_or_b32 v3, v1, s1, v0
	v_lshl_add_u64 v[0:1], s[82:83], 0, v[70:71]
	v_bfe_u32 v70, v68, 1, 3
	v_bitop3_b32 v69, v69, v70, 3 bitop3:0x6c
	v_lshlrev_b32_e32 v71, 6, v68
	v_lshlrev_b32_e32 v68, 7, v68
	v_bitop3_b32 v70, v74, v70, 4 bitop3:0x36
	v_lshl_add_u64 v[138:139], s[24:25], 0, v[72:73]
	v_lshlrev_b32_e32 v69, 4, v69
	v_and_b32_e32 v71, 0xffffe000, v71
	v_and_b32_e32 v72, 0x780, v68
	v_and_b32_e32 v68, 0x2000, v68
	v_lshlrev_b32_e32 v70, 4, v70
	s_cmp_gt_i32 s47, 0
	v_or_b32_e32 v73, v69, v71
	v_or_b32_e32 v69, v69, v68
	v_or_b32_e32 v71, v70, v71
	v_or_b32_e32 v68, v70, v68
	s_mov_b32 s49, 0
	s_cselect_b64 s[24:25], -1, 0
	v_add_u32_e32 v137, v73, v72
	v_add_u32_e32 v188, v69, v72
	v_add_u32_e32 v189, v71, v72
	v_add_u32_e32 v190, v68, v72
	s_mov_b32 s1, 0
	s_mov_b32 s3, 0
	s_bfe_u32 vcc_lo, s101, 0x10001
	v_and_b32_e32 v20, 15, v194
	v_lshrrev_b32_e32 v21, 1, v20
	v_bfe_u32 v22, v194, 4, 2
	v_xor_b32_e32 v21, v21, v22
	v_lshlrev_b32_e32 v21, 4, v21
	v_lshl_or_b32 v250, v20, 7, v21
	v_mov_b32_e32 v22, vcc_lo
	v_lshl_or_b32 v22, v22, 13, v250
	v_or_b32_e32 v251, 0x4000, v22
	v_and_b32_e32 v20, 63, v194
	v_mov_b32_e32 v21, vcc_lo
	v_lshlrev_b32_e32 v21, 4, v21
	v_lshrrev_b32_e32 v22, 3, v20
	v_add_u32_e32 v21, v21, v22
	v_lshrrev_b32_e32 v22, 4, v20
	v_and_b32_e32 v23, 7, v20
	v_xor_b32_e32 v24, v23, v22
	v_lshlrev_b32_e32 v24, 4, v24
	v_or_b32_e32 v22, 4, v22
	v_xor_b32_e32 v25, v23, v22
	v_lshlrev_b32_e32 v25, 4, v25
	s_movk_i32 s98, 0x400
	s_movk_i32 s99, 0x400
	v_add_u32_e32 v26, 0, v21
	v_mad_u32_u24 v4, v26, s98, v24
	v_add_u32_e32 v26, 8, v21
	v_mad_u32_u24 v5, v26, s98, v25
	v_add_u32_e32 v26, 32, v21
	v_mad_u32_u24 v6, v26, s98, v24
	v_add_u32_e32 v26, 40, v21
	v_mad_u32_u24 v7, v26, s98, v25
	v_add_u32_e32 v26, 64, v21
	v_mad_u32_u24 v8, v26, s98, v24
	v_add_u32_e32 v26, 72, v21
	v_mad_u32_u24 v9, v26, s98, v25
	v_add_u32_e32 v26, 96, v21
	v_mad_u32_u24 v10, v26, s98, v24
	v_add_u32_e32 v26, 104, v21
	v_mad_u32_u24 v11, v26, s98, v25
	v_add_u32_e32 v26, 0, v21
	v_mad_u32_u24 v12, v26, s99, v24
	v_add_u32_e32 v26, 8, v21
	v_mad_u32_u24 v13, v26, s99, v25
	v_add_u32_e32 v26, 32, v21
	v_mad_u32_u24 v14, v26, s99, v24
	v_add_u32_e32 v26, 40, v21
	v_mad_u32_u24 v15, v26, s99, v25
	v_add_u32_e32 v26, 64, v21
	v_mad_u32_u24 v16, v26, s99, v24
	v_add_u32_e32 v26, 72, v21
	v_mad_u32_u24 v17, v26, s99, v25
	v_add_u32_e32 v26, 96, v21
	v_mad_u32_u24 v18, v26, s99, v24
	v_add_u32_e32 v26, 104, v21
	v_mad_u32_u24 v19, v26, s99, v25
	s_bfe_u32 vcc_hi, s101, 0x20002
	s_lshl_b32 vcc_hi, vcc_hi, 3
	s_mul_i32 s98, s98, vcc_hi
	s_mul_i32 s99, s99, vcc_hi
	s_lshl_b32 vcc_hi, vcc_hi, 3
	s_and_b32 vcc_hi, vcc_hi, 0x70
	s_add_u32 s98, s98, vcc_hi
	s_add_u32 s99, s99, vcc_hi
	s_lshl_b32 s100, vcc_lo, 11
	s_bitcmp1_b32 s101, 0
	s_cselect_b32 s100, -1, s100
	s_waitcnt vmcnt(0) lgkmcnt(0)
	s_barrier
	s_branch .LBB0_323

.LBB0_940:
	s_andn2_b64 vcc, exec, s[0:1]
	s_cbranch_vccnz .LBB0_992
	v_readlane_b32 s0, v255, 2
	s_cmp_gt_i32 s0, 0
	s_mov_b64 s[0:1], -1
	s_cbranch_scc0 .LBB0_966
	v_readlane_b32 s4, v253, 13
	s_waitcnt vmcnt(1)
	v_mov_b32_e32 v68, v194
	s_movk_i32 s0, 0x400
	s_movk_i32 s2, 0x400
	s_movk_i32 s3, 0x400
	v_readlane_b32 s5, v253, 14
	s_load_dword s1, s[4:5], 0x0
	v_readlane_b32 s4, v254, 30
	s_waitcnt lgkmcnt(0)
	s_lshr_b32 s46, s1, 3
	v_readlane_b32 s1, v254, 36
	s_mul_i32 s1, s46, s1
	s_add_i32 s1, s1, s4
	s_cmpk_gt_i32 s1, 0x1a07
	s_cbranch_scc1 .LBB0_965
	v_readlane_b32 s4, v254, 63
	s_ashr_i32 s47, s3, 6
	v_readlane_b32 s5, v255, 0
	s_and_b64 s[20:21], s[4:5], exec
	v_readlane_b32 s4, v252, 37
	s_cselect_b32 s3, 0x1440000, 0
	v_readlane_b32 s12, v252, 45
	v_readlane_b32 s13, v252, 46
	s_add_u32 s24, s12, s3
	s_mul_hi_i32 s3, s1, 0x5397829d
	s_addc_u32 s25, s13, 0
	s_lshr_b32 s20, s3, 31
	s_ashr_i32 s3, s3, 7
	s_add_i32 s3, s3, s20
	s_mul_i32 s20, s3, 0xfffffe78
	s_add_i32 s20, s20, s1
	s_lshl_b32 s1, s1, 7
	v_lshlrev_b32_e32 v0, 3, v68
	v_ashrrev_i32_e32 v3, 3, v68
	s_lshl_b32 s3, s3, 10
	s_and_b32 s1, s1, 0x380
	v_and_b32_e32 v0, 56, v0
	v_lshrrev_b32_e32 v132, 4, v68
	v_xor_b32_e32 v132, v132, v68
	v_and_b32_e32 v132, 7, v132
	v_lshlrev_b32_e32 v0, 3, v132
	v_mov_b32_e32 v1, v2
	s_or_b32 s52, s3, s1
	s_lshl_b32 s1, s20, 4
	v_mad_i64_i32 v[4:5], s[20:21], s0, v3, v[0:1]
	v_mad_i64_i32 v[0:1], s[20:21], s2, v3, v[0:1]
	s_mul_hi_i32 s21, s52, s0
	s_mul_i32 s20, s52, s0
	s_and_b32 s49, s1, 0xffffff80
	s_ashr_i32 s1, s0, 31
	s_ashr_i32 s3, s2, 31
	s_lshl_b64 s[20:21], s[20:21], 1
	s_add_u32 s20, s76, s20
	s_addc_u32 s21, s77, s21
	v_lshlrev_b64 v[70:71], 1, v[4:5]
	v_lshl_add_u64 v[144:145], s[20:21], 0, v[70:71]
	s_mul_hi_i32 s21, s49, s2
	s_mul_i32 s20, s49, s2
	s_lshl_b64 s[20:21], s[20:21], 1
	s_add_u32 s20, s24, s20
	s_addc_u32 s21, s25, s21
	s_waitcnt vmcnt(0)
	v_lshlrev_b64 v[72:73], 1, v[0:1]
	v_lshl_add_u64 v[146:147], s[20:21], 0, v[72:73]
	s_lshl_b64 s[20:21], s[0:1], 6
	v_lshl_add_u64 v[0:1], v[144:145], 0, s[20:21]
	s_lshl_b64 s[22:23], s[2:3], 6
	v_lshl_add_u64 v[36:37], v[0:1], 0, s[20:21]
	v_lshl_add_u64 v[56:57], v[146:147], 0, s[22:23]
	v_lshl_add_u64 v[40:41], v[36:37], 0, s[20:21]
	v_lshl_add_u64 v[60:61], v[56:57], 0, s[22:23]
	v_lshl_add_u64 v[64:65], v[60:61], 0, s[22:23]
	s_bfe_u32 s100, s101, 0x20002
	s_lshl_b32 s100, s100, 10
	s_bfe_u32 vcc_lo, s101, 0x80008
	s_add_u32 vcc_lo, vcc_lo, 0
	s_add_u32 vcc_hi, s47, -1
	s_and_b32 vcc_lo, vcc_lo, vcc_hi
	s_lshl_b32 vcc_lo, vcc_lo, 7
	s_mov_b32 vcc_hi, 0
	v_lshl_add_u64 v[20:21], v[144:145], 0, vcc
	s_add_u32 m0, s100, 0x0
	s_nop 0
	global_load_lds_dwordx4 v[20:21], off
	v_lshl_add_u64 v[20:21], v[0:1], 0, vcc
	s_add_u32 m0, s100, 0x1000
	s_nop 0
	global_load_lds_dwordx4 v[20:21], off
	v_lshl_add_u64 v[20:21], v[36:37], 0, vcc
	s_add_u32 m0, s100, 0x2000
	s_nop 0
	global_load_lds_dwordx4 v[20:21], off
	v_lshl_add_u64 v[20:21], v[40:41], 0, vcc
	s_add_u32 m0, s100, 0x3000
	s_nop 0
	global_load_lds_dwordx4 v[20:21], off
	v_lshl_add_u64 v[20:21], v[146:147], 0, vcc
	s_add_u32 m0, s100, 0x4000
	s_nop 0
	global_load_lds_dwordx4 v[20:21], off
	v_lshl_add_u64 v[20:21], v[56:57], 0, vcc
	s_add_u32 m0, s100, 0x5000
	s_nop 0
	global_load_lds_dwordx4 v[20:21], off
	v_lshl_add_u64 v[20:21], v[60:61], 0, vcc
	s_add_u32 m0, s100, 0x6000
	s_nop 0
	global_load_lds_dwordx4 v[20:21], off
	v_lshl_add_u64 v[20:21], v[64:65], 0, vcc
	s_add_u32 m0, s100, 0x7000
	s_nop 0
	global_load_lds_dwordx4 v[20:21], off
	s_bfe_u32 vcc_lo, s101, 0x80008
	s_add_u32 vcc_lo, vcc_lo, 1
	s_add_u32 vcc_hi, s47, -1
	s_and_b32 vcc_lo, vcc_lo, vcc_hi
	s_lshl_b32 vcc_lo, vcc_lo, 7
	s_mov_b32 vcc_hi, 0
	v_lshl_add_u64 v[20:21], v[144:145], 0, vcc
	s_add_u32 m0, s100, 0x8000
	s_nop 0
	global_load_lds_dwordx4 v[20:21], off
	v_lshl_add_u64 v[20:21], v[0:1], 0, vcc
	s_add_u32 m0, s100, 0x9000
	s_nop 0
	global_load_lds_dwordx4 v[20:21], off
	v_lshl_add_u64 v[20:21], v[36:37], 0, vcc
	s_add_u32 m0, s100, 0xa000
	s_nop 0
	global_load_lds_dwordx4 v[20:21], off
	v_lshl_add_u64 v[20:21], v[40:41], 0, vcc
	s_add_u32 m0, s100, 0xb000
	s_nop 0
	global_load_lds_dwordx4 v[20:21], off
	v_lshl_add_u64 v[20:21], v[146:147], 0, vcc
	s_add_u32 m0, s100, 0xc000
	s_nop 0
	global_load_lds_dwordx4 v[20:21], off
	v_lshl_add_u64 v[20:21], v[56:57], 0, vcc
	s_add_u32 m0, s100, 0xd000
	s_nop 0
	global_load_lds_dwordx4 v[20:21], off
	v_lshl_add_u64 v[20:21], v[60:61], 0, vcc
	s_add_u32 m0, s100, 0xe000
	s_nop 0
	global_load_lds_dwordx4 v[20:21], off
	v_lshl_add_u64 v[20:21], v[64:65], 0, vcc
	s_add_u32 m0, s100, 0xf000
	s_nop 0
	global_load_lds_dwordx4 v[20:21], off
	v_lshrrev_b32_e32 v1, 1, v3
	v_xor_b32_e32 v1, v1, v68
	v_lshlrev_b32_e32 v0, 7, v3
	v_lshlrev_b32_e32 v1, 4, v1
	s_movk_i32 s1, 0x70
	v_lshrrev_b32_e32 v69, 4, v68
	v_bfe_u32 v74, v68, 4, 2
	v_and_or_b32 v3, v1, s1, v0
	v_lshl_add_u64 v[0:1], s[76:77], 0, v[70:71]
	v_bfe_u32 v70, v68, 1, 3
	v_bitop3_b32 v69, v69, v70, 3 bitop3:0x6c
	v_lshlrev_b32_e32 v71, 6, v68
	v_lshlrev_b32_e32 v68, 7, v68
	v_bitop3_b32 v70, v74, v70, 4 bitop3:0x36
	v_lshl_add_u64 v[138:139], s[24:25], 0, v[72:73]
	v_lshlrev_b32_e32 v69, 4, v69
	v_and_b32_e32 v71, 0xffffe000, v71
	v_and_b32_e32 v72, 0x780, v68
	v_and_b32_e32 v68, 0x2000, v68
	v_lshlrev_b32_e32 v70, 4, v70
	s_cmp_gt_i32 s47, 0
	v_or_b32_e32 v73, v69, v71
	v_or_b32_e32 v69, v69, v68
	v_or_b32_e32 v71, v70, v71
	v_or_b32_e32 v68, v70, v68
	s_mov_b32 s48, 0
	s_cselect_b64 s[24:25], -1, 0
	v_add_u32_e32 v137, v73, v72
	v_add_u32_e32 v188, v69, v72
	v_add_u32_e32 v189, v71, v72
	v_add_u32_e32 v190, v68, v72
	s_mov_b32 s1, 0
	s_mov_b32 s3, 0
	v_readlane_b32 s5, v252, 38
	v_readlane_b32 s6, v252, 39
	v_readlane_b32 s7, v252, 40
	v_readlane_b32 s8, v252, 41
	v_readlane_b32 s9, v252, 42
	v_readlane_b32 s10, v252, 43
	v_readlane_b32 s11, v252, 44
	v_readlane_b32 s14, v252, 47
	v_readlane_b32 s15, v252, 48
	v_readlane_b32 s16, v252, 49
	v_readlane_b32 s17, v252, 50
	v_readlane_b32 s18, v252, 51
	v_readlane_b32 s19, v252, 52
	s_bfe_u32 vcc_lo, s101, 0x10001
	v_and_b32_e32 v20, 15, v194
	v_lshrrev_b32_e32 v21, 1, v20
	v_bfe_u32 v22, v194, 4, 2
	v_xor_b32_e32 v21, v21, v22
	v_lshlrev_b32_e32 v21, 4, v21
	v_lshl_or_b32 v250, v20, 7, v21
	v_mov_b32_e32 v22, vcc_lo
	v_lshl_or_b32 v22, v22, 13, v250
	v_or_b32_e32 v251, 0x4000, v22
	v_and_b32_e32 v20, 63, v194
	v_mov_b32_e32 v21, vcc_lo
	v_lshlrev_b32_e32 v21, 4, v21
	v_lshrrev_b32_e32 v22, 3, v20
	v_add_u32_e32 v21, v21, v22
	v_lshrrev_b32_e32 v22, 4, v20
	v_and_b32_e32 v23, 7, v20
	v_xor_b32_e32 v24, v23, v22
	v_lshlrev_b32_e32 v24, 4, v24
	v_or_b32_e32 v22, 4, v22
	v_xor_b32_e32 v25, v23, v22
	v_lshlrev_b32_e32 v25, 4, v25
	s_movk_i32 s98, 0x800
	s_movk_i32 s99, 0x800
	v_add_u32_e32 v26, 0, v21
	v_mad_u32_u24 v4, v26, s98, v24
	v_add_u32_e32 v26, 8, v21
	v_mad_u32_u24 v5, v26, s98, v25
	v_add_u32_e32 v26, 32, v21
	v_mad_u32_u24 v6, v26, s98, v24
	v_add_u32_e32 v26, 40, v21
	v_mad_u32_u24 v7, v26, s98, v25
	v_add_u32_e32 v26, 64, v21
	v_mad_u32_u24 v8, v26, s98, v24
	v_add_u32_e32 v26, 72, v21
	v_mad_u32_u24 v9, v26, s98, v25
	v_add_u32_e32 v26, 96, v21
	v_mad_u32_u24 v10, v26, s98, v24
	v_add_u32_e32 v26, 104, v21
	v_mad_u32_u24 v11, v26, s98, v25
	v_add_u32_e32 v26, 0, v21
	v_mad_u32_u24 v12, v26, s99, v24
	v_add_u32_e32 v26, 8, v21
	v_mad_u32_u24 v13, v26, s99, v25
	v_add_u32_e32 v26, 32, v21
	v_mad_u32_u24 v14, v26, s99, v24
	v_add_u32_e32 v26, 40, v21
	v_mad_u32_u24 v15, v26, s99, v25
	v_add_u32_e32 v26, 64, v21
	v_mad_u32_u24 v16, v26, s99, v24
	v_add_u32_e32 v26, 72, v21
	v_mad_u32_u24 v17, v26, s99, v25
	v_add_u32_e32 v26, 96, v21
	v_mad_u32_u24 v18, v26, s99, v24
	v_add_u32_e32 v26, 104, v21
	v_mad_u32_u24 v19, v26, s99, v25
	s_bfe_u32 vcc_hi, s101, 0x20002
	s_lshl_b32 vcc_hi, vcc_hi, 3
	s_mul_i32 s98, s98, vcc_hi
	s_mul_i32 s99, s99, vcc_hi
	s_lshl_b32 vcc_hi, vcc_hi, 3
	s_and_b32 vcc_hi, vcc_hi, 0x70
	s_add_u32 s98, s98, vcc_hi
	s_add_u32 s99, s99, vcc_hi
	s_lshl_b32 s100, vcc_lo, 11
	s_bitcmp1_b32 s101, 0
	s_cselect_b32 s100, -1, s100
	s_waitcnt vmcnt(0) lgkmcnt(0)
	s_barrier
	s_branch .LBB0_946
